# first K-iteration of every tile peeled with C=0 in the first MFMA of each accumulator: the 128-instruction accumulator zeroing at each tile head is gone
# speedup vs baseline: 1.0066x; 1.0016x over previous
.LBB0_310:
	s_ashr_i32 s55, s54, 31
	s_lshl_b64 s[58:59], s[54:55], 19
	s_add_u32 s58, s29, s58
	s_addc_u32 s59, s30, s59
	s_and_b64 s[60:61], s[38:39], exec
	s_cselect_b32 s33, s59, s35
	s_cselect_b32 s36, s58, s34
	s_ashr_i32 s53, s52, 31
	s_lshl_b64 s[60:61], s[52:53], 19
	s_add_u32 s60, s45, s60
	s_addc_u32 s61, s66, s61
	s_and_b64 s[62:63], s[38:39], exec
	s_cselect_b32 s53, s61, s65
	s_cselect_b32 s55, s60, s64
	s_add_u32 s62, s34, 0x40080
	s_addc_u32 s63, s35, 0
	s_add_u32 s75, s64, 0x100
	s_addc_u32 s79, s65, 0
	s_mov_b32 s82, -2
.Lpeel_311:
	s_add_u32 s4, s62, 0xfffc0080
	s_addc_u32 s5, s63, -1
	s_add_i32 s84, 0, 0x10000
	s_cmp_eq_u32 s82, 12
	s_cselect_b32 s65, s33, s5
	s_cselect_b32 s64, s36, s4
	s_cselect_b32 s35, s53, s79
	s_cselect_b32 s34, s55, s75
	s_add_i32 s4, 0, 0x14000
	v_add_u32_e32 v164, s84, v143
	v_add_u32_e32 v180, s4, v143
	ds_read_b128 v[138:141], v164
	ds_read_b128 v[156:159], v164 offset:1024
	ds_read_b128 v[160:163], v164 offset:2048
	ds_read_b128 v[164:167], v164 offset:3072
	ds_read_b128 v[168:171], v180
	ds_read_b128 v[172:175], v180 offset:1024
	ds_read_b128 v[176:179], v180 offset:2048
	ds_read_b128 v[204:207], v180 offset:3072
	v_lshl_add_u64 v[180:181], s[62:63], 0, v[134:135]
	s_add_i32 m0, s68, 0xc000
	ds_read_b128 v[208:211], v155
	ds_read_b128 v[212:215], v155 offset:1024
	ds_read_b128 v[216:219], v155 offset:2048
	ds_read_b128 v[220:223], v155 offset:3072
	ds_read_b128 v[224:227], v155 offset:4096
	ds_read_b128 v[228:231], v155 offset:5120
	ds_read_b128 v[232:235], v155 offset:6144
	ds_read_b128 v[236:239], v155 offset:7168
	global_load_lds_dwordx4 v[180:181], off
	v_lshl_add_u64 v[180:181], s[62:63], 0, v[136:137]
	s_add_i32 m0, s68, 0xe000
	s_nop 0
	global_load_lds_dwordx4 v[180:181], off
	s_waitcnt vmcnt(8)
	s_waitcnt lgkmcnt(0)
	s_barrier
	s_setprio 1
	s_waitcnt lgkmcnt(0)
	v_mfma_f32_16x16x32_bf16 v[124:127], v[138:141], v[208:211], 0
	v_mfma_f32_16x16x32_bf16 v[120:123], v[160:163], v[208:211], 0
	v_mfma_f32_16x16x32_bf16 v[108:111], v[138:141], v[216:219], 0
	v_mfma_f32_16x16x32_bf16 v[104:107], v[160:163], v[216:219], 0
	v_mfma_f32_16x16x32_bf16 v[92:95], v[138:141], v[224:227], 0
	v_mfma_f32_16x16x32_bf16 v[88:91], v[160:163], v[224:227], 0
	v_mfma_f32_16x16x32_bf16 v[76:79], v[138:141], v[232:235], 0
	v_mfma_f32_16x16x32_bf16 v[72:75], v[160:163], v[232:235], 0
	v_mfma_f32_16x16x32_bf16 v[124:127], v[156:159], v[212:215], v[124:127]
	v_mfma_f32_16x16x32_bf16 v[120:123], v[164:167], v[212:215], v[120:123]
	v_mfma_f32_16x16x32_bf16 v[108:111], v[156:159], v[220:223], v[108:111]
	v_mfma_f32_16x16x32_bf16 v[104:107], v[164:167], v[220:223], v[104:107]
	v_mfma_f32_16x16x32_bf16 v[92:95], v[156:159], v[228:231], v[92:95]
	v_mfma_f32_16x16x32_bf16 v[88:91], v[164:167], v[228:231], v[88:91]
	v_mfma_f32_16x16x32_bf16 v[76:79], v[156:159], v[236:239], v[76:79]
	v_mfma_f32_16x16x32_bf16 v[72:75], v[164:167], v[236:239], v[72:75]
	s_setprio 0
	s_setprio 1
	v_mfma_f32_16x16x32_bf16 v[116:119], v[168:171], v[208:211], 0
	v_mfma_f32_16x16x32_bf16 v[112:115], v[176:179], v[208:211], 0
	v_mfma_f32_16x16x32_bf16 v[100:103], v[168:171], v[216:219], 0
	v_mfma_f32_16x16x32_bf16 v[96:99], v[176:179], v[216:219], 0
	v_mfma_f32_16x16x32_bf16 v[84:87], v[168:171], v[224:227], 0
	v_mfma_f32_16x16x32_bf16 v[80:83], v[176:179], v[224:227], 0
	v_mfma_f32_16x16x32_bf16 v[68:71], v[168:171], v[232:235], 0
	v_mfma_f32_16x16x32_bf16 v[64:67], v[176:179], v[232:235], 0
	v_mfma_f32_16x16x32_bf16 v[116:119], v[172:175], v[212:215], v[116:119]
	v_mfma_f32_16x16x32_bf16 v[112:115], v[204:207], v[212:215], v[112:115]
	v_mfma_f32_16x16x32_bf16 v[100:103], v[172:175], v[220:223], v[100:103]
	v_mfma_f32_16x16x32_bf16 v[96:99], v[204:207], v[220:223], v[96:99]
	v_mfma_f32_16x16x32_bf16 v[84:87], v[172:175], v[228:231], v[84:87]
	v_mfma_f32_16x16x32_bf16 v[80:83], v[204:207], v[228:231], v[80:83]
	v_mfma_f32_16x16x32_bf16 v[68:71], v[172:175], v[236:239], v[68:71]
	v_mfma_f32_16x16x32_bf16 v[64:67], v[204:207], v[236:239], v[64:67]
	s_setprio 0
	s_barrier
	s_add_i32 s5, s84, s28
	v_lshl_add_u64 v[180:181], s[34:35], 0, v[144:145]
	s_mov_b32 m0, s5
	ds_read_b128 v[208:211], v155 offset:16384
	ds_read_b128 v[212:215], v155 offset:17408
	ds_read_b128 v[216:219], v155 offset:18432
	ds_read_b128 v[220:223], v155 offset:19456
	ds_read_b128 v[224:227], v155 offset:20480
	ds_read_b128 v[228:231], v155 offset:21504
	ds_read_b128 v[232:235], v155 offset:22528
	ds_read_b128 v[236:239], v155 offset:23552
	global_load_lds_dwordx4 v[180:181], off
	s_add_i32 m0, s5, 0x2000
	s_add_u32 s88, s34, 0x40000
	v_lshl_add_u64 v[240:241], s[34:35], 0, v[128:129]
	s_addc_u32 s89, s35, 0
	s_add_i32 s4, s4, s28
	global_load_lds_dwordx4 v[240:241], off
	v_lshl_add_u64 v[242:243], s[88:89], 0, v[144:145]
	s_mov_b32 m0, s4
	v_lshl_add_u64 v[244:245], s[64:65], 0, v[130:131]
	global_load_lds_dwordx4 v[242:243], off
	v_lshl_add_u64 v[242:243], s[88:89], 0, v[128:129]
	s_add_i32 m0, s4, 0x2000
	s_nop 0
	global_load_lds_dwordx4 v[242:243], off
	v_lshl_add_u64 v[242:243], s[64:65], 0, v[132:133]
	s_mov_b32 m0, s68
	s_nop 0
	global_load_lds_dwordx4 v[242:243], off
	s_mov_b32 m0, s69
	s_nop 0
	global_load_lds_dwordx4 v[244:245], off
	s_waitcnt vmcnt(8)
	s_waitcnt lgkmcnt(0)
	s_barrier
	s_setprio 1
	s_waitcnt lgkmcnt(0)
	v_mfma_f32_16x16x32_bf16 v[60:63], v[138:141], v[208:211], 0
	v_mfma_f32_16x16x32_bf16 v[56:59], v[160:163], v[208:211], 0
	v_mfma_f32_16x16x32_bf16 v[44:47], v[138:141], v[216:219], 0
	v_mfma_f32_16x16x32_bf16 v[40:43], v[160:163], v[216:219], 0
	v_mfma_f32_16x16x32_bf16 v[28:31], v[138:141], v[224:227], 0
	v_mfma_f32_16x16x32_bf16 v[24:27], v[160:163], v[224:227], 0
	v_mfma_f32_16x16x32_bf16 v[12:15], v[138:141], v[232:235], 0
	v_mfma_f32_16x16x32_bf16 v[8:11], v[160:163], v[232:235], 0
	v_mfma_f32_16x16x32_bf16 v[60:63], v[156:159], v[212:215], v[60:63]
	v_mfma_f32_16x16x32_bf16 v[56:59], v[164:167], v[212:215], v[56:59]
	v_mfma_f32_16x16x32_bf16 v[44:47], v[156:159], v[220:223], v[44:47]
	v_mfma_f32_16x16x32_bf16 v[40:43], v[164:167], v[220:223], v[40:43]
	v_mfma_f32_16x16x32_bf16 v[28:31], v[156:159], v[228:231], v[28:31]
	v_mfma_f32_16x16x32_bf16 v[24:27], v[164:167], v[228:231], v[24:27]
	v_mfma_f32_16x16x32_bf16 v[12:15], v[156:159], v[236:239], v[12:15]
	v_mfma_f32_16x16x32_bf16 v[8:11], v[164:167], v[236:239], v[8:11]
	s_setprio 0
	s_setprio 1
	v_mfma_f32_16x16x32_bf16 v[52:55], v[168:171], v[208:211], 0
	v_mfma_f32_16x16x32_bf16 v[48:51], v[176:179], v[208:211], 0
	v_mfma_f32_16x16x32_bf16 v[36:39], v[168:171], v[216:219], 0
	v_mfma_f32_16x16x32_bf16 v[32:35], v[176:179], v[216:219], 0
	v_mfma_f32_16x16x32_bf16 v[20:23], v[168:171], v[224:227], 0
	v_mfma_f32_16x16x32_bf16 v[16:19], v[176:179], v[224:227], 0
	v_mfma_f32_16x16x32_bf16 v[4:7], v[168:171], v[232:235], 0
	v_mfma_f32_16x16x32_bf16 v[0:3], v[176:179], v[232:235], 0
	v_mfma_f32_16x16x32_bf16 v[52:55], v[172:175], v[212:215], v[52:55]
	v_mfma_f32_16x16x32_bf16 v[48:51], v[204:207], v[212:215], v[48:51]
	v_mfma_f32_16x16x32_bf16 v[36:39], v[172:175], v[220:223], v[36:39]
	v_mfma_f32_16x16x32_bf16 v[32:35], v[204:207], v[220:223], v[32:35]
	v_mfma_f32_16x16x32_bf16 v[20:23], v[172:175], v[228:231], v[20:23]
	v_mfma_f32_16x16x32_bf16 v[16:19], v[204:207], v[228:231], v[16:19]
	v_mfma_f32_16x16x32_bf16 v[4:7], v[172:175], v[236:239], v[4:7]
	v_mfma_f32_16x16x32_bf16 v[0:3], v[204:207], v[236:239], v[0:3]
	s_setprio 0
	s_barrier
	s_add_i32 s4, 0, 0x18000
	s_add_i32 s5, 0, 0x1c000
	v_add_u32_e32 v164, s4, v143
	v_add_u32_e32 v202, s5, v143
	ds_read_b128 v[138:141], v164
	ds_read_b128 v[156:159], v164 offset:1024
	ds_read_b128 v[160:163], v164 offset:2048
	ds_read_b128 v[164:167], v164 offset:3072
	ds_read_b128 v[168:171], v202
	ds_read_b128 v[172:175], v202 offset:1024
	ds_read_b128 v[176:179], v202 offset:2048
	ds_read_b128 v[204:207], v202 offset:3072
	s_add_u32 s64, s64, 0x40000
	s_addc_u32 s65, s65, 0
	s_mov_b32 m0, s70
	v_lshl_add_u64 v[246:247], s[64:65], 0, v[132:133]
	ds_read_b128 v[208:211], v155 offset:32768
	ds_read_b128 v[212:215], v155 offset:33792
	ds_read_b128 v[216:219], v155 offset:34816
	ds_read_b128 v[220:223], v155 offset:35840
	ds_read_b128 v[224:227], v155 offset:36864
	ds_read_b128 v[228:231], v155 offset:37888
	ds_read_b128 v[232:235], v155 offset:38912
	ds_read_b128 v[236:239], v155 offset:39936
	global_load_lds_dwordx4 v[246:247], off
	v_lshl_add_u64 v[246:247], s[64:65], 0, v[130:131]
	s_mov_b32 m0, s71
	s_nop 0
	global_load_lds_dwordx4 v[246:247], off
	s_waitcnt vmcnt(8)
	s_waitcnt lgkmcnt(0)
	s_barrier
	s_setprio 1
	s_waitcnt lgkmcnt(0)
	v_mfma_f32_16x16x32_bf16 v[124:127], v[138:141], v[208:211], v[124:127]
	v_mfma_f32_16x16x32_bf16 v[120:123], v[160:163], v[208:211], v[120:123]
	v_mfma_f32_16x16x32_bf16 v[108:111], v[138:141], v[216:219], v[108:111]
	v_mfma_f32_16x16x32_bf16 v[104:107], v[160:163], v[216:219], v[104:107]
	v_mfma_f32_16x16x32_bf16 v[92:95], v[138:141], v[224:227], v[92:95]
	v_mfma_f32_16x16x32_bf16 v[88:91], v[160:163], v[224:227], v[88:91]
	v_mfma_f32_16x16x32_bf16 v[76:79], v[138:141], v[232:235], v[76:79]
	v_mfma_f32_16x16x32_bf16 v[72:75], v[160:163], v[232:235], v[72:75]
	v_mfma_f32_16x16x32_bf16 v[124:127], v[156:159], v[212:215], v[124:127]
	v_mfma_f32_16x16x32_bf16 v[120:123], v[164:167], v[212:215], v[120:123]
	v_mfma_f32_16x16x32_bf16 v[108:111], v[156:159], v[220:223], v[108:111]
	v_mfma_f32_16x16x32_bf16 v[104:107], v[164:167], v[220:223], v[104:107]
	v_mfma_f32_16x16x32_bf16 v[92:95], v[156:159], v[228:231], v[92:95]
	v_mfma_f32_16x16x32_bf16 v[88:91], v[164:167], v[228:231], v[88:91]
	v_mfma_f32_16x16x32_bf16 v[76:79], v[156:159], v[236:239], v[76:79]
	v_mfma_f32_16x16x32_bf16 v[72:75], v[164:167], v[236:239], v[72:75]
	s_setprio 0
	s_setprio 1
	v_mfma_f32_16x16x32_bf16 v[116:119], v[168:171], v[208:211], v[116:119]
	v_mfma_f32_16x16x32_bf16 v[112:115], v[176:179], v[208:211], v[112:115]
	v_mfma_f32_16x16x32_bf16 v[100:103], v[168:171], v[216:219], v[100:103]
	v_mfma_f32_16x16x32_bf16 v[96:99], v[176:179], v[216:219], v[96:99]
	v_mfma_f32_16x16x32_bf16 v[84:87], v[168:171], v[224:227], v[84:87]
	v_mfma_f32_16x16x32_bf16 v[80:83], v[176:179], v[224:227], v[80:83]
	v_mfma_f32_16x16x32_bf16 v[68:71], v[168:171], v[232:235], v[68:71]
	v_mfma_f32_16x16x32_bf16 v[64:67], v[176:179], v[232:235], v[64:67]
	v_mfma_f32_16x16x32_bf16 v[116:119], v[172:175], v[212:215], v[116:119]
	v_mfma_f32_16x16x32_bf16 v[112:115], v[204:207], v[212:215], v[112:115]
	v_mfma_f32_16x16x32_bf16 v[100:103], v[172:175], v[220:223], v[100:103]
	v_mfma_f32_16x16x32_bf16 v[96:99], v[204:207], v[220:223], v[96:99]
	v_mfma_f32_16x16x32_bf16 v[84:87], v[172:175], v[228:231], v[84:87]
	v_mfma_f32_16x16x32_bf16 v[80:83], v[204:207], v[228:231], v[80:83]
	v_mfma_f32_16x16x32_bf16 v[68:71], v[172:175], v[236:239], v[68:71]
	v_mfma_f32_16x16x32_bf16 v[64:67], v[204:207], v[236:239], v[64:67]
	s_setprio 0
	s_barrier
	s_add_i32 s4, s4, s28
	v_lshl_add_u64 v[180:181], v[180:181], 0, s[26:27]
	s_mov_b32 m0, s4
	ds_read_b128 v[208:211], v155 offset:49152
	ds_read_b128 v[212:215], v155 offset:50176
	ds_read_b128 v[216:219], v155 offset:51200
	ds_read_b128 v[220:223], v155 offset:52224
	ds_read_b128 v[224:227], v155 offset:53248
	ds_read_b128 v[228:231], v155 offset:54272
	ds_read_b128 v[232:235], v155 offset:55296
	ds_read_b128 v[236:239], v155 offset:56320
	global_load_lds_dwordx4 v[180:181], off
	s_add_i32 m0, s4, 0x2000
	s_add_u32 s34, s34, 0x40080
	v_lshl_add_u64 v[180:181], v[240:241], 0, s[26:27]
	s_addc_u32 s35, s35, 0
	s_add_i32 s4, s5, s28
	global_load_lds_dwordx4 v[180:181], off
	v_lshl_add_u64 v[180:181], s[34:35], 0, v[144:145]
	s_mov_b32 m0, s4
	s_nop 0
	global_load_lds_dwordx4 v[180:181], off
	v_lshl_add_u64 v[180:181], s[34:35], 0, v[128:129]
	s_add_i32 m0, s4, 0x2000
	s_nop 0
	global_load_lds_dwordx4 v[180:181], off
	v_lshl_add_u64 v[180:181], v[242:243], 0, s[26:27]
	s_mov_b32 m0, s72
	s_nop 0
	global_load_lds_dwordx4 v[180:181], off
	v_lshl_add_u64 v[180:181], v[244:245], 0, s[26:27]
	s_mov_b32 m0, s73
	s_nop 0
	global_load_lds_dwordx4 v[180:181], off
	s_waitcnt vmcnt(8)
	s_waitcnt lgkmcnt(0)
	s_barrier
	s_setprio 1
	s_waitcnt lgkmcnt(0)
	v_mfma_f32_16x16x32_bf16 v[60:63], v[138:141], v[208:211], v[60:63]
	v_mfma_f32_16x16x32_bf16 v[56:59], v[160:163], v[208:211], v[56:59]
	v_mfma_f32_16x16x32_bf16 v[44:47], v[138:141], v[216:219], v[44:47]
	v_mfma_f32_16x16x32_bf16 v[40:43], v[160:163], v[216:219], v[40:43]
	v_mfma_f32_16x16x32_bf16 v[28:31], v[138:141], v[224:227], v[28:31]
	v_mfma_f32_16x16x32_bf16 v[24:27], v[160:163], v[224:227], v[24:27]
	v_mfma_f32_16x16x32_bf16 v[12:15], v[138:141], v[232:235], v[12:15]
	v_mfma_f32_16x16x32_bf16 v[8:11], v[160:163], v[232:235], v[8:11]
	v_mfma_f32_16x16x32_bf16 v[60:63], v[156:159], v[212:215], v[60:63]
	v_mfma_f32_16x16x32_bf16 v[56:59], v[164:167], v[212:215], v[56:59]
	v_mfma_f32_16x16x32_bf16 v[44:47], v[156:159], v[220:223], v[44:47]
	v_mfma_f32_16x16x32_bf16 v[40:43], v[164:167], v[220:223], v[40:43]
	v_mfma_f32_16x16x32_bf16 v[28:31], v[156:159], v[228:231], v[28:31]
	v_mfma_f32_16x16x32_bf16 v[24:27], v[164:167], v[228:231], v[24:27]
	v_mfma_f32_16x16x32_bf16 v[12:15], v[156:159], v[236:239], v[12:15]
	v_mfma_f32_16x16x32_bf16 v[8:11], v[164:167], v[236:239], v[8:11]
	s_setprio 0
	s_setprio 1
	v_mfma_f32_16x16x32_bf16 v[52:55], v[168:171], v[208:211], v[52:55]
	v_mfma_f32_16x16x32_bf16 v[48:51], v[176:179], v[208:211], v[48:51]
	v_mfma_f32_16x16x32_bf16 v[36:39], v[168:171], v[216:219], v[36:39]
	v_mfma_f32_16x16x32_bf16 v[32:35], v[176:179], v[216:219], v[32:35]
	v_mfma_f32_16x16x32_bf16 v[20:23], v[168:171], v[224:227], v[20:23]
	v_mfma_f32_16x16x32_bf16 v[16:19], v[176:179], v[224:227], v[16:19]
	v_mfma_f32_16x16x32_bf16 v[4:7], v[168:171], v[232:235], v[4:7]
	v_mfma_f32_16x16x32_bf16 v[0:3], v[176:179], v[232:235], v[0:3]
	v_mfma_f32_16x16x32_bf16 v[52:55], v[172:175], v[212:215], v[52:55]
	v_mfma_f32_16x16x32_bf16 v[48:51], v[204:207], v[212:215], v[48:51]
	v_mfma_f32_16x16x32_bf16 v[36:39], v[172:175], v[220:223], v[36:39]
	v_mfma_f32_16x16x32_bf16 v[32:35], v[204:207], v[220:223], v[32:35]
	v_mfma_f32_16x16x32_bf16 v[20:23], v[172:175], v[228:231], v[20:23]
	v_mfma_f32_16x16x32_bf16 v[16:19], v[204:207], v[228:231], v[16:19]
	v_mfma_f32_16x16x32_bf16 v[4:7], v[172:175], v[236:239], v[4:7]
	v_mfma_f32_16x16x32_bf16 v[0:3], v[204:207], v[236:239], v[0:3]
	s_setprio 0
	s_barrier
	s_add_i32 s82, s82, 2
	s_add_u32 s62, s62, 0x100
	s_addc_u32 s63, s63, 0
	s_add_u32 s75, s75, 0x100
	s_addc_u32 s79, s79, 0
	s_cmp_gt_u32 s82, 13
	s_cbranch_scc0 .LBB0_311
	s_branch .Lkexit_311

.Lkexit_311:
	s_and_b64 vcc, exec, s[50:51]
	s_cbranch_vccz .LBB0_314
	s_barrier

.LBB0_405:
	s_add_u32 s3, s62, 0x100
	s_addc_u32 s28, s63, 0
	s_mov_b32 s29, -2
	s_waitcnt lgkmcnt(0)
.Lpeel_406:
	s_add_u32 s62, s60, 0x100
	s_addc_u32 s63, s61, 0
	s_add_i32 s4, 0, 0x10000
	s_cmp_eq_u32 s29, 40
	s_cselect_b32 s65, s45, s63
	s_cselect_b32 s64, s44, s62
	v_add_u32_e32 v142, s4, v160
	s_cselect_b32 s35, s59, s28
	s_cselect_b32 s34, s58, s3
	s_add_i32 s5, 0, 0x14000
	ds_read_b128 v[138:141], v142
	ds_read_b128 v[154:157], v142 offset:1024
	ds_read_b128 v[172:175], v142 offset:2048
	ds_read_b128 v[176:179], v142 offset:3072
	v_add_u32_e32 v142, s5, v160
	ds_read_b128 v[204:207], v142
	ds_read_b128 v[208:211], v142 offset:1024
	ds_read_b128 v[212:215], v142 offset:2048
	ds_read_b128 v[216:219], v142 offset:3072
	v_lshl_add_u64 v[142:143], s[60:61], 0, v[134:135]
	s_add_i32 m0, s36, 0xc000
	ds_read_b128 v[220:223], v170
	ds_read_b128 v[224:227], v170 offset:1024
	ds_read_b128 v[228:231], v170 offset:2048
	ds_read_b128 v[232:235], v170 offset:3072
	ds_read_b128 v[236:239], v170 offset:4096
	ds_read_b128 v[240:243], v170 offset:5120
	ds_read_b128 v[244:247], v170 offset:6144
	ds_read_b128 v[248:251], v170 offset:7168
	global_load_lds_dwordx4 v[142:143], off
	v_lshl_add_u64 v[142:143], s[60:61], 0, v[136:137]
	s_add_i32 m0, s36, 0xe000
	s_nop 0
	global_load_lds_dwordx4 v[142:143], off
	s_waitcnt vmcnt(8)
	s_waitcnt lgkmcnt(0)
	s_barrier
	s_setprio 1
	s_waitcnt lgkmcnt(0)
	v_mfma_f32_16x16x32_bf16 v[124:127], v[138:141], v[220:223], 0
	v_mfma_f32_16x16x32_bf16 v[120:123], v[172:175], v[220:223], 0
	v_mfma_f32_16x16x32_bf16 v[108:111], v[138:141], v[228:231], 0
	v_mfma_f32_16x16x32_bf16 v[104:107], v[172:175], v[228:231], 0
	v_mfma_f32_16x16x32_bf16 v[92:95], v[138:141], v[236:239], 0
	v_mfma_f32_16x16x32_bf16 v[88:91], v[172:175], v[236:239], 0
	v_mfma_f32_16x16x32_bf16 v[76:79], v[138:141], v[244:247], 0
	v_mfma_f32_16x16x32_bf16 v[72:75], v[172:175], v[244:247], 0
	v_mfma_f32_16x16x32_bf16 v[124:127], v[154:157], v[224:227], v[124:127]
	v_mfma_f32_16x16x32_bf16 v[120:123], v[176:179], v[224:227], v[120:123]
	v_mfma_f32_16x16x32_bf16 v[108:111], v[154:157], v[232:235], v[108:111]
	v_mfma_f32_16x16x32_bf16 v[104:107], v[176:179], v[232:235], v[104:107]
	v_mfma_f32_16x16x32_bf16 v[92:95], v[154:157], v[240:243], v[92:95]
	v_mfma_f32_16x16x32_bf16 v[88:91], v[176:179], v[240:243], v[88:91]
	v_mfma_f32_16x16x32_bf16 v[76:79], v[154:157], v[248:251], v[76:79]
	v_mfma_f32_16x16x32_bf16 v[72:75], v[176:179], v[248:251], v[72:75]
	s_setprio 0
	s_setprio 1
	v_mfma_f32_16x16x32_bf16 v[116:119], v[204:207], v[220:223], 0
	v_mfma_f32_16x16x32_bf16 v[112:115], v[212:215], v[220:223], 0
	v_mfma_f32_16x16x32_bf16 v[100:103], v[204:207], v[228:231], 0
	v_mfma_f32_16x16x32_bf16 v[96:99], v[212:215], v[228:231], 0
	v_mfma_f32_16x16x32_bf16 v[84:87], v[204:207], v[236:239], 0
	v_mfma_f32_16x16x32_bf16 v[80:83], v[212:215], v[236:239], 0
	v_mfma_f32_16x16x32_bf16 v[68:71], v[204:207], v[244:247], 0
	v_mfma_f32_16x16x32_bf16 v[64:67], v[212:215], v[244:247], 0
	v_mfma_f32_16x16x32_bf16 v[116:119], v[208:211], v[224:227], v[116:119]
	v_mfma_f32_16x16x32_bf16 v[112:115], v[216:219], v[224:227], v[112:115]
	v_mfma_f32_16x16x32_bf16 v[100:103], v[208:211], v[232:235], v[100:103]
	v_mfma_f32_16x16x32_bf16 v[96:99], v[216:219], v[232:235], v[96:99]
	v_mfma_f32_16x16x32_bf16 v[84:87], v[208:211], v[240:243], v[84:87]
	v_mfma_f32_16x16x32_bf16 v[80:83], v[216:219], v[240:243], v[80:83]
	v_mfma_f32_16x16x32_bf16 v[68:71], v[208:211], v[248:251], v[68:71]
	v_mfma_f32_16x16x32_bf16 v[64:67], v[216:219], v[248:251], v[64:67]
	s_setprio 0
	s_barrier
	s_add_i32 s4, s4, s33
	v_lshl_add_u64 v[142:143], s[34:35], 0, v[128:129]
	s_mov_b32 m0, s4
	ds_read_b128 v[220:223], v170 offset:16384
	ds_read_b128 v[224:227], v170 offset:17408
	ds_read_b128 v[228:231], v170 offset:18432
	ds_read_b128 v[232:235], v170 offset:19456
	ds_read_b128 v[236:239], v170 offset:20480
	ds_read_b128 v[240:243], v170 offset:21504
	ds_read_b128 v[244:247], v170 offset:22528
	ds_read_b128 v[248:251], v170 offset:23552
	global_load_lds_dwordx4 v[142:143], off
	s_add_i32 m0, s4, 0x2000
	s_add_u32 s60, s34, 0xb0000
	v_lshl_add_u64 v[158:159], s[34:35], 0, v[130:131]
	s_addc_u32 s61, s35, 0
	s_add_i32 s4, s5, s33
	global_load_lds_dwordx4 v[158:159], off
	v_lshl_add_u64 v[180:181], s[60:61], 0, v[128:129]
	s_mov_b32 m0, s4
	v_lshl_add_u64 v[202:203], s[64:65], 0, v[130:131]
	global_load_lds_dwordx4 v[180:181], off
	v_lshl_add_u64 v[180:181], s[60:61], 0, v[130:131]
	s_add_i32 m0, s4, 0x2000
	s_nop 0
	global_load_lds_dwordx4 v[180:181], off
	v_lshl_add_u64 v[180:181], s[64:65], 0, v[128:129]
	s_mov_b32 m0, s36
	s_nop 0
	global_load_lds_dwordx4 v[180:181], off
	s_mov_b32 m0, s70
	s_nop 0
	global_load_lds_dwordx4 v[202:203], off
	s_waitcnt vmcnt(8)
	s_waitcnt lgkmcnt(0)
	s_barrier
	s_setprio 1
	s_waitcnt lgkmcnt(0)
	v_mfma_f32_16x16x32_bf16 v[60:63], v[138:141], v[220:223], 0
	v_mfma_f32_16x16x32_bf16 v[56:59], v[172:175], v[220:223], 0
	v_mfma_f32_16x16x32_bf16 v[44:47], v[138:141], v[228:231], 0
	v_mfma_f32_16x16x32_bf16 v[40:43], v[172:175], v[228:231], 0
	v_mfma_f32_16x16x32_bf16 v[28:31], v[138:141], v[236:239], 0
	v_mfma_f32_16x16x32_bf16 v[24:27], v[172:175], v[236:239], 0
	v_mfma_f32_16x16x32_bf16 v[12:15], v[138:141], v[244:247], 0
	v_mfma_f32_16x16x32_bf16 v[8:11], v[172:175], v[244:247], 0
	v_mfma_f32_16x16x32_bf16 v[60:63], v[154:157], v[224:227], v[60:63]
	v_mfma_f32_16x16x32_bf16 v[56:59], v[176:179], v[224:227], v[56:59]
	v_mfma_f32_16x16x32_bf16 v[44:47], v[154:157], v[232:235], v[44:47]
	v_mfma_f32_16x16x32_bf16 v[40:43], v[176:179], v[232:235], v[40:43]
	v_mfma_f32_16x16x32_bf16 v[28:31], v[154:157], v[240:243], v[28:31]
	v_mfma_f32_16x16x32_bf16 v[24:27], v[176:179], v[240:243], v[24:27]
	v_mfma_f32_16x16x32_bf16 v[12:15], v[154:157], v[248:251], v[12:15]
	v_mfma_f32_16x16x32_bf16 v[8:11], v[176:179], v[248:251], v[8:11]
	s_setprio 0
	s_setprio 1
	v_mfma_f32_16x16x32_bf16 v[52:55], v[204:207], v[220:223], 0
	v_mfma_f32_16x16x32_bf16 v[48:51], v[212:215], v[220:223], 0
	v_mfma_f32_16x16x32_bf16 v[36:39], v[204:207], v[228:231], 0
	v_mfma_f32_16x16x32_bf16 v[32:35], v[212:215], v[228:231], 0
	v_mfma_f32_16x16x32_bf16 v[20:23], v[204:207], v[236:239], 0
	v_mfma_f32_16x16x32_bf16 v[16:19], v[212:215], v[236:239], 0
	v_mfma_f32_16x16x32_bf16 v[4:7], v[204:207], v[244:247], 0
	v_mfma_f32_16x16x32_bf16 v[0:3], v[212:215], v[244:247], 0
	v_mfma_f32_16x16x32_bf16 v[52:55], v[208:211], v[224:227], v[52:55]
	v_mfma_f32_16x16x32_bf16 v[48:51], v[216:219], v[224:227], v[48:51]
	v_mfma_f32_16x16x32_bf16 v[36:39], v[208:211], v[232:235], v[36:39]
	v_mfma_f32_16x16x32_bf16 v[32:35], v[216:219], v[232:235], v[32:35]
	v_mfma_f32_16x16x32_bf16 v[20:23], v[208:211], v[240:243], v[20:23]
	v_mfma_f32_16x16x32_bf16 v[16:19], v[216:219], v[240:243], v[16:19]
	v_mfma_f32_16x16x32_bf16 v[4:7], v[208:211], v[248:251], v[4:7]
	v_mfma_f32_16x16x32_bf16 v[0:3], v[216:219], v[248:251], v[0:3]
	s_setprio 0
	s_barrier
	s_add_i32 s4, 0, 0x18000
	v_add_u32_e32 v144, s4, v160
	s_add_i32 s5, 0, 0x1c000
	ds_read_b128 v[138:141], v144
	ds_read_b128 v[154:157], v144 offset:1024
	ds_read_b128 v[172:175], v144 offset:2048
	ds_read_b128 v[176:179], v144 offset:3072
	v_add_u32_e32 v144, s5, v160
	ds_read_b128 v[204:207], v144
	ds_read_b128 v[208:211], v144 offset:1024
	ds_read_b128 v[212:215], v144 offset:2048
	ds_read_b128 v[216:219], v144 offset:3072
	s_add_u32 s60, s64, 0xb0000
	s_addc_u32 s61, s65, 0
	s_mov_b32 m0, s71
	v_lshl_add_u64 v[252:253], s[60:61], 0, v[128:129]
	ds_read_b128 v[220:223], v170 offset:32768
	ds_read_b128 v[224:227], v170 offset:33792
	ds_read_b128 v[228:231], v170 offset:34816
	ds_read_b128 v[232:235], v170 offset:35840
	ds_read_b128 v[236:239], v170 offset:36864
	ds_read_b128 v[240:243], v170 offset:37888
	ds_read_b128 v[244:247], v170 offset:38912
	ds_read_b128 v[248:251], v170 offset:39936
	global_load_lds_dwordx4 v[252:253], off
	v_lshl_add_u64 v[252:253], s[60:61], 0, v[130:131]
	s_mov_b32 m0, s72
	s_nop 0
	global_load_lds_dwordx4 v[252:253], off
	s_waitcnt vmcnt(8)
	s_waitcnt lgkmcnt(0)
	s_barrier
	s_setprio 1
	s_waitcnt lgkmcnt(0)
	v_mfma_f32_16x16x32_bf16 v[124:127], v[138:141], v[220:223], v[124:127]
	v_mfma_f32_16x16x32_bf16 v[120:123], v[172:175], v[220:223], v[120:123]
	v_mfma_f32_16x16x32_bf16 v[108:111], v[138:141], v[228:231], v[108:111]
	v_mfma_f32_16x16x32_bf16 v[104:107], v[172:175], v[228:231], v[104:107]
	v_mfma_f32_16x16x32_bf16 v[92:95], v[138:141], v[236:239], v[92:95]
	v_mfma_f32_16x16x32_bf16 v[88:91], v[172:175], v[236:239], v[88:91]
	v_mfma_f32_16x16x32_bf16 v[76:79], v[138:141], v[244:247], v[76:79]
	v_mfma_f32_16x16x32_bf16 v[72:75], v[172:175], v[244:247], v[72:75]
	v_mfma_f32_16x16x32_bf16 v[124:127], v[154:157], v[224:227], v[124:127]
	v_mfma_f32_16x16x32_bf16 v[120:123], v[176:179], v[224:227], v[120:123]
	v_mfma_f32_16x16x32_bf16 v[108:111], v[154:157], v[232:235], v[108:111]
	v_mfma_f32_16x16x32_bf16 v[104:107], v[176:179], v[232:235], v[104:107]
	v_mfma_f32_16x16x32_bf16 v[92:95], v[154:157], v[240:243], v[92:95]
	v_mfma_f32_16x16x32_bf16 v[88:91], v[176:179], v[240:243], v[88:91]
	v_mfma_f32_16x16x32_bf16 v[76:79], v[154:157], v[248:251], v[76:79]
	v_mfma_f32_16x16x32_bf16 v[72:75], v[176:179], v[248:251], v[72:75]
	s_setprio 0
	s_setprio 1
	v_mfma_f32_16x16x32_bf16 v[116:119], v[204:207], v[220:223], v[116:119]
	v_mfma_f32_16x16x32_bf16 v[112:115], v[212:215], v[220:223], v[112:115]
	v_mfma_f32_16x16x32_bf16 v[100:103], v[204:207], v[228:231], v[100:103]
	v_mfma_f32_16x16x32_bf16 v[96:99], v[212:215], v[228:231], v[96:99]
	v_mfma_f32_16x16x32_bf16 v[84:87], v[204:207], v[236:239], v[84:87]
	v_mfma_f32_16x16x32_bf16 v[80:83], v[212:215], v[236:239], v[80:83]
	v_mfma_f32_16x16x32_bf16 v[68:71], v[204:207], v[244:247], v[68:71]
	v_mfma_f32_16x16x32_bf16 v[64:67], v[212:215], v[244:247], v[64:67]
	v_mfma_f32_16x16x32_bf16 v[116:119], v[208:211], v[224:227], v[116:119]
	v_mfma_f32_16x16x32_bf16 v[112:115], v[216:219], v[224:227], v[112:115]
	v_mfma_f32_16x16x32_bf16 v[100:103], v[208:211], v[232:235], v[100:103]
	v_mfma_f32_16x16x32_bf16 v[96:99], v[216:219], v[232:235], v[96:99]
	v_mfma_f32_16x16x32_bf16 v[84:87], v[208:211], v[240:243], v[84:87]
	v_mfma_f32_16x16x32_bf16 v[80:83], v[216:219], v[240:243], v[80:83]
	v_mfma_f32_16x16x32_bf16 v[68:71], v[208:211], v[248:251], v[68:71]
	v_mfma_f32_16x16x32_bf16 v[64:67], v[216:219], v[248:251], v[64:67]
	s_setprio 0
	s_barrier
	s_add_i32 s4, s4, s33
	v_lshl_add_u64 v[142:143], v[142:143], 0, s[26:27]
	s_mov_b32 m0, s4
	ds_read_b128 v[220:223], v170 offset:49152
	ds_read_b128 v[224:227], v170 offset:50176
	ds_read_b128 v[228:231], v170 offset:51200
	ds_read_b128 v[232:235], v170 offset:52224
	ds_read_b128 v[236:239], v170 offset:53248
	ds_read_b128 v[240:243], v170 offset:54272
	ds_read_b128 v[244:247], v170 offset:55296
	ds_read_b128 v[248:251], v170 offset:56320
	global_load_lds_dwordx4 v[142:143], off
	s_add_i32 m0, s4, 0x2000
	s_add_u32 s34, s34, 0xb0080
	v_lshl_add_u64 v[142:143], v[158:159], 0, s[26:27]
	s_addc_u32 s35, s35, 0
	s_add_i32 s4, s5, s33
	global_load_lds_dwordx4 v[142:143], off
	v_lshl_add_u64 v[142:143], s[34:35], 0, v[128:129]
	s_mov_b32 m0, s4
	s_nop 0
	global_load_lds_dwordx4 v[142:143], off
	v_lshl_add_u64 v[142:143], s[34:35], 0, v[130:131]
	s_add_i32 m0, s4, 0x2000
	s_nop 0
	global_load_lds_dwordx4 v[142:143], off
	v_lshl_add_u64 v[142:143], v[180:181], 0, s[26:27]
	s_mov_b32 m0, s73
	s_nop 0
	global_load_lds_dwordx4 v[142:143], off
	v_lshl_add_u64 v[142:143], v[202:203], 0, s[26:27]
	s_mov_b32 m0, s74
	s_nop 0
	global_load_lds_dwordx4 v[142:143], off
	s_waitcnt vmcnt(8)
	s_waitcnt lgkmcnt(0)
	s_barrier
	s_setprio 1
	s_waitcnt lgkmcnt(0)
	v_mfma_f32_16x16x32_bf16 v[60:63], v[138:141], v[220:223], v[60:63]
	v_mfma_f32_16x16x32_bf16 v[56:59], v[172:175], v[220:223], v[56:59]
	v_mfma_f32_16x16x32_bf16 v[44:47], v[138:141], v[228:231], v[44:47]
	v_mfma_f32_16x16x32_bf16 v[40:43], v[172:175], v[228:231], v[40:43]
	v_mfma_f32_16x16x32_bf16 v[28:31], v[138:141], v[236:239], v[28:31]
	v_mfma_f32_16x16x32_bf16 v[24:27], v[172:175], v[236:239], v[24:27]
	v_mfma_f32_16x16x32_bf16 v[12:15], v[138:141], v[244:247], v[12:15]
	v_mfma_f32_16x16x32_bf16 v[8:11], v[172:175], v[244:247], v[8:11]
	v_mfma_f32_16x16x32_bf16 v[60:63], v[154:157], v[224:227], v[60:63]
	v_mfma_f32_16x16x32_bf16 v[56:59], v[176:179], v[224:227], v[56:59]
	v_mfma_f32_16x16x32_bf16 v[44:47], v[154:157], v[232:235], v[44:47]
	v_mfma_f32_16x16x32_bf16 v[40:43], v[176:179], v[232:235], v[40:43]
	v_mfma_f32_16x16x32_bf16 v[28:31], v[154:157], v[240:243], v[28:31]
	v_mfma_f32_16x16x32_bf16 v[24:27], v[176:179], v[240:243], v[24:27]
	v_mfma_f32_16x16x32_bf16 v[12:15], v[154:157], v[248:251], v[12:15]
	v_mfma_f32_16x16x32_bf16 v[8:11], v[176:179], v[248:251], v[8:11]
	s_setprio 0
	s_setprio 1
	v_mfma_f32_16x16x32_bf16 v[52:55], v[204:207], v[220:223], v[52:55]
	v_mfma_f32_16x16x32_bf16 v[48:51], v[212:215], v[220:223], v[48:51]
	v_mfma_f32_16x16x32_bf16 v[36:39], v[204:207], v[228:231], v[36:39]
	v_mfma_f32_16x16x32_bf16 v[32:35], v[212:215], v[228:231], v[32:35]
	v_mfma_f32_16x16x32_bf16 v[20:23], v[204:207], v[236:239], v[20:23]
	v_mfma_f32_16x16x32_bf16 v[16:19], v[212:215], v[236:239], v[16:19]
	v_mfma_f32_16x16x32_bf16 v[4:7], v[204:207], v[244:247], v[4:7]
	v_mfma_f32_16x16x32_bf16 v[0:3], v[212:215], v[244:247], v[0:3]
	v_mfma_f32_16x16x32_bf16 v[52:55], v[208:211], v[224:227], v[52:55]
	v_mfma_f32_16x16x32_bf16 v[48:51], v[216:219], v[224:227], v[48:51]
	v_mfma_f32_16x16x32_bf16 v[36:39], v[208:211], v[232:235], v[36:39]
	v_mfma_f32_16x16x32_bf16 v[32:35], v[216:219], v[232:235], v[32:35]
	v_mfma_f32_16x16x32_bf16 v[20:23], v[208:211], v[240:243], v[20:23]
	v_mfma_f32_16x16x32_bf16 v[16:19], v[216:219], v[240:243], v[16:19]
	v_mfma_f32_16x16x32_bf16 v[4:7], v[208:211], v[248:251], v[4:7]
	v_mfma_f32_16x16x32_bf16 v[0:3], v[216:219], v[248:251], v[0:3]
	s_setprio 0
	s_barrier
	s_add_i32 s29, s29, 2
	s_add_u32 s3, s3, 0x100
	s_addc_u32 s28, s28, 0
	s_cmp_gt_u32 s29, 41
	s_mov_b64 s[60:61], s[62:63]
	s_cbranch_scc0 .LBB0_406
	s_branch .Lkexit_406

.Lkexit_406:
	s_and_b64 vcc, exec, s[54:55]
	s_cbranch_vccz .LBB0_409
	s_barrier

.LBB0_455:
	s_add_u32 s28, s60, 0x100
	s_addc_u32 s29, s61, 0
	s_mov_b32 s51, -2
	s_waitcnt lgkmcnt(0)
.Lpeel_456:
	s_add_u32 s60, s58, 0x100
	s_addc_u32 s61, s59, 0
	s_add_i32 s4, 0, 0x10000
	s_cmp_eq_u32 s51, 40
	s_cselect_b32 s63, s45, s61
	s_cselect_b32 s62, s44, s60
	s_cselect_b32 s35, s47, s29
	s_cselect_b32 s34, s46, s28
	s_add_i32 s5, 0, 0x14000
	v_add_u32_e32 v140, s4, v166
	v_add_u32_e32 v144, s5, v166
	ds_read_b128 v[128:131], v140
	ds_read_b128 v[132:135], v140 offset:1024
	ds_read_b128 v[136:139], v140 offset:2048
	ds_read_b128 v[140:143], v140 offset:3072
	ds_read_b128 v[178:181], v144
	ds_read_b128 v[204:207], v144 offset:1024
	ds_read_b128 v[208:211], v144 offset:2048
	ds_read_b128 v[212:215], v144 offset:3072
	v_lshl_add_u64 v[164:165], s[58:59], 0, v[160:161]
	s_add_i32 m0, s36, 0xc000
	ds_read_b128 v[216:219], v176
	ds_read_b128 v[220:223], v176 offset:1024
	ds_read_b128 v[224:227], v176 offset:2048
	ds_read_b128 v[228:231], v176 offset:3072
	ds_read_b128 v[232:235], v176 offset:4096
	ds_read_b128 v[236:239], v176 offset:5120
	ds_read_b128 v[240:243], v176 offset:6144
	ds_read_b128 v[244:247], v176 offset:7168
	global_load_lds_dwordx4 v[164:165], off
	v_lshl_add_u64 v[164:165], s[58:59], 0, v[162:163]
	s_add_i32 m0, s36, 0xe000
	s_nop 0
	global_load_lds_dwordx4 v[164:165], off
	s_waitcnt vmcnt(8)
	s_waitcnt lgkmcnt(0)
	s_barrier
	s_setprio 1
	s_waitcnt lgkmcnt(0)
	v_mfma_f32_16x16x32_bf16 v[124:127], v[128:131], v[216:219], 0
	v_mfma_f32_16x16x32_bf16 v[120:123], v[136:139], v[216:219], 0
	v_mfma_f32_16x16x32_bf16 v[108:111], v[128:131], v[224:227], 0
	v_mfma_f32_16x16x32_bf16 v[104:107], v[136:139], v[224:227], 0
	v_mfma_f32_16x16x32_bf16 v[92:95], v[128:131], v[232:235], 0
	v_mfma_f32_16x16x32_bf16 v[88:91], v[136:139], v[232:235], 0
	v_mfma_f32_16x16x32_bf16 v[76:79], v[128:131], v[240:243], 0
	v_mfma_f32_16x16x32_bf16 v[72:75], v[136:139], v[240:243], 0
	v_mfma_f32_16x16x32_bf16 v[124:127], v[132:135], v[220:223], v[124:127]
	v_mfma_f32_16x16x32_bf16 v[120:123], v[140:143], v[220:223], v[120:123]
	v_mfma_f32_16x16x32_bf16 v[108:111], v[132:135], v[228:231], v[108:111]
	v_mfma_f32_16x16x32_bf16 v[104:107], v[140:143], v[228:231], v[104:107]
	v_mfma_f32_16x16x32_bf16 v[92:95], v[132:135], v[236:239], v[92:95]
	v_mfma_f32_16x16x32_bf16 v[88:91], v[140:143], v[236:239], v[88:91]
	v_mfma_f32_16x16x32_bf16 v[76:79], v[132:135], v[244:247], v[76:79]
	v_mfma_f32_16x16x32_bf16 v[72:75], v[140:143], v[244:247], v[72:75]
	s_setprio 0
	s_setprio 1
	v_mfma_f32_16x16x32_bf16 v[116:119], v[178:181], v[216:219], 0
	v_mfma_f32_16x16x32_bf16 v[112:115], v[208:211], v[216:219], 0
	v_mfma_f32_16x16x32_bf16 v[100:103], v[178:181], v[224:227], 0
	v_mfma_f32_16x16x32_bf16 v[96:99], v[208:211], v[224:227], 0
	v_mfma_f32_16x16x32_bf16 v[84:87], v[178:181], v[232:235], 0
	v_mfma_f32_16x16x32_bf16 v[80:83], v[208:211], v[232:235], 0
	v_mfma_f32_16x16x32_bf16 v[68:71], v[178:181], v[240:243], 0
	v_mfma_f32_16x16x32_bf16 v[64:67], v[208:211], v[240:243], 0
	v_mfma_f32_16x16x32_bf16 v[116:119], v[204:207], v[220:223], v[116:119]
	v_mfma_f32_16x16x32_bf16 v[112:115], v[212:215], v[220:223], v[112:115]
	v_mfma_f32_16x16x32_bf16 v[100:103], v[204:207], v[228:231], v[100:103]
	v_mfma_f32_16x16x32_bf16 v[96:99], v[212:215], v[228:231], v[96:99]
	v_mfma_f32_16x16x32_bf16 v[84:87], v[204:207], v[236:239], v[84:87]
	v_mfma_f32_16x16x32_bf16 v[80:83], v[212:215], v[236:239], v[80:83]
	v_mfma_f32_16x16x32_bf16 v[68:71], v[204:207], v[244:247], v[68:71]
	v_mfma_f32_16x16x32_bf16 v[64:67], v[212:215], v[244:247], v[64:67]
	s_setprio 0
	s_barrier
	s_add_i32 s4, s4, s33
	v_lshl_add_u64 v[164:165], s[34:35], 0, v[154:155]
	s_mov_b32 m0, s4
	ds_read_b128 v[216:219], v176 offset:16384
	ds_read_b128 v[220:223], v176 offset:17408
	ds_read_b128 v[224:227], v176 offset:18432
	ds_read_b128 v[228:231], v176 offset:19456
	ds_read_b128 v[232:235], v176 offset:20480
	ds_read_b128 v[236:239], v176 offset:21504
	ds_read_b128 v[240:243], v176 offset:22528
	ds_read_b128 v[244:247], v176 offset:23552
	global_load_lds_dwordx4 v[164:165], off
	s_add_i32 m0, s4, 0x2000
	s_add_u32 s58, s34, 0xb0000
	v_lshl_add_u64 v[248:249], s[34:35], 0, v[156:157]
	s_addc_u32 s59, s35, 0
	s_add_i32 s4, s5, s33
	global_load_lds_dwordx4 v[248:249], off
	v_lshl_add_u64 v[250:251], s[58:59], 0, v[154:155]
	s_mov_b32 m0, s4
	v_lshl_add_u64 v[252:253], s[62:63], 0, v[156:157]
	global_load_lds_dwordx4 v[250:251], off
	v_lshl_add_u64 v[250:251], s[58:59], 0, v[156:157]
	s_add_i32 m0, s4, 0x2000
	s_nop 0
	global_load_lds_dwordx4 v[250:251], off
	v_lshl_add_u64 v[250:251], s[62:63], 0, v[154:155]
	s_mov_b32 m0, s36
	s_nop 0
	global_load_lds_dwordx4 v[250:251], off
	s_mov_b32 m0, s64
	s_nop 0
	global_load_lds_dwordx4 v[252:253], off
	s_waitcnt vmcnt(8)
	s_waitcnt lgkmcnt(0)
	s_barrier
	s_setprio 1
	s_waitcnt lgkmcnt(0)
	v_mfma_f32_16x16x32_bf16 v[60:63], v[128:131], v[216:219], 0
	v_mfma_f32_16x16x32_bf16 v[56:59], v[136:139], v[216:219], 0
	v_mfma_f32_16x16x32_bf16 v[44:47], v[128:131], v[224:227], 0
	v_mfma_f32_16x16x32_bf16 v[40:43], v[136:139], v[224:227], 0
	v_mfma_f32_16x16x32_bf16 v[28:31], v[128:131], v[232:235], 0
	v_mfma_f32_16x16x32_bf16 v[24:27], v[136:139], v[232:235], 0
	v_mfma_f32_16x16x32_bf16 v[12:15], v[128:131], v[240:243], 0
	v_mfma_f32_16x16x32_bf16 v[8:11], v[136:139], v[240:243], 0
	v_mfma_f32_16x16x32_bf16 v[60:63], v[132:135], v[220:223], v[60:63]
	v_mfma_f32_16x16x32_bf16 v[56:59], v[140:143], v[220:223], v[56:59]
	v_mfma_f32_16x16x32_bf16 v[44:47], v[132:135], v[228:231], v[44:47]
	v_mfma_f32_16x16x32_bf16 v[40:43], v[140:143], v[228:231], v[40:43]
	v_mfma_f32_16x16x32_bf16 v[28:31], v[132:135], v[236:239], v[28:31]
	v_mfma_f32_16x16x32_bf16 v[24:27], v[140:143], v[236:239], v[24:27]
	v_mfma_f32_16x16x32_bf16 v[12:15], v[132:135], v[244:247], v[12:15]
	v_mfma_f32_16x16x32_bf16 v[8:11], v[140:143], v[244:247], v[8:11]
	s_setprio 0
	s_setprio 1
	v_mfma_f32_16x16x32_bf16 v[52:55], v[178:181], v[216:219], 0
	v_mfma_f32_16x16x32_bf16 v[48:51], v[208:211], v[216:219], 0
	v_mfma_f32_16x16x32_bf16 v[36:39], v[178:181], v[224:227], 0
	v_mfma_f32_16x16x32_bf16 v[32:35], v[208:211], v[224:227], 0
	v_mfma_f32_16x16x32_bf16 v[20:23], v[178:181], v[232:235], 0
	v_mfma_f32_16x16x32_bf16 v[16:19], v[208:211], v[232:235], 0
	v_mfma_f32_16x16x32_bf16 v[4:7], v[178:181], v[240:243], 0
	v_mfma_f32_16x16x32_bf16 v[0:3], v[208:211], v[240:243], 0
	v_mfma_f32_16x16x32_bf16 v[52:55], v[204:207], v[220:223], v[52:55]
	v_mfma_f32_16x16x32_bf16 v[48:51], v[212:215], v[220:223], v[48:51]
	v_mfma_f32_16x16x32_bf16 v[36:39], v[204:207], v[228:231], v[36:39]
	v_mfma_f32_16x16x32_bf16 v[32:35], v[212:215], v[228:231], v[32:35]
	v_mfma_f32_16x16x32_bf16 v[20:23], v[204:207], v[236:239], v[20:23]
	v_mfma_f32_16x16x32_bf16 v[16:19], v[212:215], v[236:239], v[16:19]
	v_mfma_f32_16x16x32_bf16 v[4:7], v[204:207], v[244:247], v[4:7]
	v_mfma_f32_16x16x32_bf16 v[0:3], v[212:215], v[244:247], v[0:3]
	s_setprio 0
	s_barrier
	s_add_i32 s4, 0, 0x18000
	s_add_i32 s5, 0, 0x1c000
	v_add_u32_e32 v140, s4, v166
	v_add_u32_e32 v144, s5, v166
	ds_read_b128 v[128:131], v140
	ds_read_b128 v[132:135], v140 offset:1024
	ds_read_b128 v[136:139], v140 offset:2048
	ds_read_b128 v[140:143], v140 offset:3072
	ds_read_b128 v[178:181], v144
	ds_read_b128 v[204:207], v144 offset:1024
	ds_read_b128 v[208:211], v144 offset:2048
	ds_read_b128 v[212:215], v144 offset:3072
	s_add_u32 s58, s62, 0xb0000
	s_addc_u32 s59, s63, 0
	s_mov_b32 m0, s65
	v_lshl_add_u64 v[202:203], s[58:59], 0, v[154:155]
	ds_read_b128 v[216:219], v176 offset:32768
	ds_read_b128 v[220:223], v176 offset:33792
	ds_read_b128 v[224:227], v176 offset:34816
	ds_read_b128 v[228:231], v176 offset:35840
	ds_read_b128 v[232:235], v176 offset:36864
	ds_read_b128 v[236:239], v176 offset:37888
	ds_read_b128 v[240:243], v176 offset:38912
	ds_read_b128 v[244:247], v176 offset:39936
	global_load_lds_dwordx4 v[202:203], off
	v_lshl_add_u64 v[202:203], s[58:59], 0, v[156:157]
	s_mov_b32 m0, s70
	s_nop 0
	global_load_lds_dwordx4 v[202:203], off
	s_waitcnt vmcnt(8)
	s_waitcnt lgkmcnt(0)
	s_barrier
	s_setprio 1
	s_waitcnt lgkmcnt(0)
	v_mfma_f32_16x16x32_bf16 v[124:127], v[128:131], v[216:219], v[124:127]
	v_mfma_f32_16x16x32_bf16 v[120:123], v[136:139], v[216:219], v[120:123]
	v_mfma_f32_16x16x32_bf16 v[108:111], v[128:131], v[224:227], v[108:111]
	v_mfma_f32_16x16x32_bf16 v[104:107], v[136:139], v[224:227], v[104:107]
	v_mfma_f32_16x16x32_bf16 v[92:95], v[128:131], v[232:235], v[92:95]
	v_mfma_f32_16x16x32_bf16 v[88:91], v[136:139], v[232:235], v[88:91]
	v_mfma_f32_16x16x32_bf16 v[76:79], v[128:131], v[240:243], v[76:79]
	v_mfma_f32_16x16x32_bf16 v[72:75], v[136:139], v[240:243], v[72:75]
	v_mfma_f32_16x16x32_bf16 v[124:127], v[132:135], v[220:223], v[124:127]
	v_mfma_f32_16x16x32_bf16 v[120:123], v[140:143], v[220:223], v[120:123]
	v_mfma_f32_16x16x32_bf16 v[108:111], v[132:135], v[228:231], v[108:111]
	v_mfma_f32_16x16x32_bf16 v[104:107], v[140:143], v[228:231], v[104:107]
	v_mfma_f32_16x16x32_bf16 v[92:95], v[132:135], v[236:239], v[92:95]
	v_mfma_f32_16x16x32_bf16 v[88:91], v[140:143], v[236:239], v[88:91]
	v_mfma_f32_16x16x32_bf16 v[76:79], v[132:135], v[244:247], v[76:79]
	v_mfma_f32_16x16x32_bf16 v[72:75], v[140:143], v[244:247], v[72:75]
	s_setprio 0
	s_setprio 1
	v_mfma_f32_16x16x32_bf16 v[116:119], v[178:181], v[216:219], v[116:119]
	v_mfma_f32_16x16x32_bf16 v[112:115], v[208:211], v[216:219], v[112:115]
	v_mfma_f32_16x16x32_bf16 v[100:103], v[178:181], v[224:227], v[100:103]
	v_mfma_f32_16x16x32_bf16 v[96:99], v[208:211], v[224:227], v[96:99]
	v_mfma_f32_16x16x32_bf16 v[84:87], v[178:181], v[232:235], v[84:87]
	v_mfma_f32_16x16x32_bf16 v[80:83], v[208:211], v[232:235], v[80:83]
	v_mfma_f32_16x16x32_bf16 v[68:71], v[178:181], v[240:243], v[68:71]
	v_mfma_f32_16x16x32_bf16 v[64:67], v[208:211], v[240:243], v[64:67]
	v_mfma_f32_16x16x32_bf16 v[116:119], v[204:207], v[220:223], v[116:119]
	v_mfma_f32_16x16x32_bf16 v[112:115], v[212:215], v[220:223], v[112:115]
	v_mfma_f32_16x16x32_bf16 v[100:103], v[204:207], v[228:231], v[100:103]
	v_mfma_f32_16x16x32_bf16 v[96:99], v[212:215], v[228:231], v[96:99]
	v_mfma_f32_16x16x32_bf16 v[84:87], v[204:207], v[236:239], v[84:87]
	v_mfma_f32_16x16x32_bf16 v[80:83], v[212:215], v[236:239], v[80:83]
	v_mfma_f32_16x16x32_bf16 v[68:71], v[204:207], v[244:247], v[68:71]
	v_mfma_f32_16x16x32_bf16 v[64:67], v[212:215], v[244:247], v[64:67]
	s_setprio 0
	s_barrier
	s_add_i32 s4, s4, s33
	v_lshl_add_u64 v[164:165], v[164:165], 0, s[26:27]
	s_mov_b32 m0, s4
	ds_read_b128 v[216:219], v176 offset:49152
	ds_read_b128 v[220:223], v176 offset:50176
	ds_read_b128 v[224:227], v176 offset:51200
	ds_read_b128 v[228:231], v176 offset:52224
	ds_read_b128 v[232:235], v176 offset:53248
	ds_read_b128 v[236:239], v176 offset:54272
	ds_read_b128 v[240:243], v176 offset:55296
	ds_read_b128 v[244:247], v176 offset:56320
	global_load_lds_dwordx4 v[164:165], off
	s_add_i32 m0, s4, 0x2000
	s_add_u32 s34, s34, 0xb0080
	v_lshl_add_u64 v[164:165], v[248:249], 0, s[26:27]
	s_addc_u32 s35, s35, 0
	s_add_i32 s4, s5, s33
	global_load_lds_dwordx4 v[164:165], off
	v_lshl_add_u64 v[164:165], s[34:35], 0, v[154:155]
	s_mov_b32 m0, s4
	s_nop 0
	global_load_lds_dwordx4 v[164:165], off
	v_lshl_add_u64 v[164:165], s[34:35], 0, v[156:157]
	s_add_i32 m0, s4, 0x2000
	s_nop 0
	global_load_lds_dwordx4 v[164:165], off
	v_lshl_add_u64 v[164:165], v[250:251], 0, s[26:27]
	s_mov_b32 m0, s71
	s_nop 0
	global_load_lds_dwordx4 v[164:165], off
	v_lshl_add_u64 v[164:165], v[252:253], 0, s[26:27]
	s_mov_b32 m0, s72
	s_nop 0
	global_load_lds_dwordx4 v[164:165], off
	s_waitcnt vmcnt(8)
	s_waitcnt lgkmcnt(0)
	s_barrier
	s_setprio 1
	s_waitcnt lgkmcnt(0)
	v_mfma_f32_16x16x32_bf16 v[60:63], v[128:131], v[216:219], v[60:63]
	v_mfma_f32_16x16x32_bf16 v[56:59], v[136:139], v[216:219], v[56:59]
	v_mfma_f32_16x16x32_bf16 v[44:47], v[128:131], v[224:227], v[44:47]
	v_mfma_f32_16x16x32_bf16 v[40:43], v[136:139], v[224:227], v[40:43]
	v_mfma_f32_16x16x32_bf16 v[28:31], v[128:131], v[232:235], v[28:31]
	v_mfma_f32_16x16x32_bf16 v[24:27], v[136:139], v[232:235], v[24:27]
	v_mfma_f32_16x16x32_bf16 v[12:15], v[128:131], v[240:243], v[12:15]
	v_mfma_f32_16x16x32_bf16 v[8:11], v[136:139], v[240:243], v[8:11]
	v_mfma_f32_16x16x32_bf16 v[60:63], v[132:135], v[220:223], v[60:63]
	v_mfma_f32_16x16x32_bf16 v[56:59], v[140:143], v[220:223], v[56:59]
	v_mfma_f32_16x16x32_bf16 v[44:47], v[132:135], v[228:231], v[44:47]
	v_mfma_f32_16x16x32_bf16 v[40:43], v[140:143], v[228:231], v[40:43]
	v_mfma_f32_16x16x32_bf16 v[28:31], v[132:135], v[236:239], v[28:31]
	v_mfma_f32_16x16x32_bf16 v[24:27], v[140:143], v[236:239], v[24:27]
	v_mfma_f32_16x16x32_bf16 v[12:15], v[132:135], v[244:247], v[12:15]
	v_mfma_f32_16x16x32_bf16 v[8:11], v[140:143], v[244:247], v[8:11]
	s_setprio 0
	s_setprio 1
	v_mfma_f32_16x16x32_bf16 v[52:55], v[178:181], v[216:219], v[52:55]
	v_mfma_f32_16x16x32_bf16 v[48:51], v[208:211], v[216:219], v[48:51]
	v_mfma_f32_16x16x32_bf16 v[36:39], v[178:181], v[224:227], v[36:39]
	v_mfma_f32_16x16x32_bf16 v[32:35], v[208:211], v[224:227], v[32:35]
	v_mfma_f32_16x16x32_bf16 v[20:23], v[178:181], v[232:235], v[20:23]
	v_mfma_f32_16x16x32_bf16 v[16:19], v[208:211], v[232:235], v[16:19]
	v_mfma_f32_16x16x32_bf16 v[4:7], v[178:181], v[240:243], v[4:7]
	v_mfma_f32_16x16x32_bf16 v[0:3], v[208:211], v[240:243], v[0:3]
	v_mfma_f32_16x16x32_bf16 v[52:55], v[204:207], v[220:223], v[52:55]
	v_mfma_f32_16x16x32_bf16 v[48:51], v[212:215], v[220:223], v[48:51]
	v_mfma_f32_16x16x32_bf16 v[36:39], v[204:207], v[228:231], v[36:39]
	v_mfma_f32_16x16x32_bf16 v[32:35], v[212:215], v[228:231], v[32:35]
	v_mfma_f32_16x16x32_bf16 v[20:23], v[204:207], v[236:239], v[20:23]
	v_mfma_f32_16x16x32_bf16 v[16:19], v[212:215], v[236:239], v[16:19]
	v_mfma_f32_16x16x32_bf16 v[4:7], v[204:207], v[244:247], v[4:7]
	v_mfma_f32_16x16x32_bf16 v[0:3], v[212:215], v[244:247], v[0:3]
	s_setprio 0
	s_barrier
	s_add_i32 s51, s51, 2
	s_add_u32 s28, s28, 0x100
	s_addc_u32 s29, s29, 0
	s_cmp_gt_u32 s51, 41
	s_mov_b64 s[58:59], s[60:61]
	s_cbranch_scc0 .LBB0_456
	s_branch .Lkexit_456

.LBB0_604:
	s_ashr_i32 s71, s70, 31
	s_lshl_b64 s[34:35], s[70:71], 19
	s_cmp_eq_u32 s30, 0
	s_cselect_b32 s4, s29, s55
	s_cselect_b32 s3, s47, s46
	s_cselect_b32 s5, s53, s29
	s_cselect_b32 s71, s54, s47
	s_add_u32 s72, s4, s34
	s_addc_u32 s73, s3, s35
	s_and_b64 s[34:35], s[40:41], exec
	s_cselect_b32 s3, s73, s1
	s_cselect_b32 s36, s72, s0
	s_ashr_i32 s39, s38, 31
	s_lshl_b64 s[34:35], s[38:39], 19
	s_add_u32 s74, s5, s34
	s_addc_u32 s75, s71, s35
	s_and_b64 s[34:35], s[40:41], exec
	s_cselect_b32 s39, s75, s43
	s_cselect_b32 s71, s74, s42
	s_add_u32 s0, s0, 0x40080
	s_addc_u32 s1, s1, 0
	s_add_u32 s79, s42, 0x100
	s_addc_u32 s84, s43, 0
	s_mov_b32 s88, -2
.Lpeel_605:
	s_add_u32 s4, s0, 0xfffc0080
	s_addc_u32 s5, s1, -1
	s_add_i32 s89, 0, 0x10000
	s_cmp_eq_u32 s88, 12
	s_cselect_b32 s43, s3, s5
	s_cselect_b32 s42, s36, s4
	s_cselect_b32 s35, s39, s84
	s_cselect_b32 s34, s71, s79
	s_add_i32 s4, 0, 0x14000
	v_add_u32_e32 v140, s89, v203
	v_add_u32_e32 v144, s4, v203
	ds_read_b128 v[128:131], v140
	ds_read_b128 v[132:135], v140 offset:1024
	ds_read_b128 v[136:139], v140 offset:2048
	ds_read_b128 v[140:143], v140 offset:3072
	ds_read_b128 v[168:171], v144
	ds_read_b128 v[172:175], v144 offset:1024
	ds_read_b128 v[176:179], v144 offset:2048
	ds_read_b128 v[206:209], v144 offset:3072
	v_lshl_add_u64 v[180:181], s[0:1], 0, v[164:165]
	s_add_i32 m0, s69, 0xc000
	ds_read_b128 v[210:213], v205
	ds_read_b128 v[214:217], v205 offset:1024
	ds_read_b128 v[218:221], v205 offset:2048
	ds_read_b128 v[222:225], v205 offset:3072
	ds_read_b128 v[226:229], v205 offset:4096
	ds_read_b128 v[230:233], v205 offset:5120
	ds_read_b128 v[234:237], v205 offset:6144
	ds_read_b128 v[238:241], v205 offset:7168
	global_load_lds_dwordx4 v[180:181], off
	v_lshl_add_u64 v[180:181], s[0:1], 0, v[166:167]
	s_add_i32 m0, s69, 0xe000
	s_nop 0
	global_load_lds_dwordx4 v[180:181], off
	s_waitcnt vmcnt(8)
	s_waitcnt lgkmcnt(0)
	s_barrier
	s_setprio 1
	s_waitcnt lgkmcnt(0)
	v_mfma_f32_16x16x32_bf16 v[124:127], v[128:131], v[210:213], 0
	v_mfma_f32_16x16x32_bf16 v[120:123], v[136:139], v[210:213], 0
	v_mfma_f32_16x16x32_bf16 v[112:115], v[128:131], v[218:221], 0
	v_mfma_f32_16x16x32_bf16 v[108:111], v[136:139], v[218:221], 0
	v_mfma_f32_16x16x32_bf16 v[100:103], v[128:131], v[226:229], 0
	v_mfma_f32_16x16x32_bf16 v[92:95], v[136:139], v[226:229], 0
	v_mfma_f32_16x16x32_bf16 v[84:87], v[128:131], v[234:237], 0
	v_mfma_f32_16x16x32_bf16 v[76:79], v[136:139], v[234:237], 0
	v_mfma_f32_16x16x32_bf16 v[124:127], v[132:135], v[214:217], v[124:127]
	v_mfma_f32_16x16x32_bf16 v[120:123], v[140:143], v[214:217], v[120:123]
	v_mfma_f32_16x16x32_bf16 v[112:115], v[132:135], v[222:225], v[112:115]
	v_mfma_f32_16x16x32_bf16 v[108:111], v[140:143], v[222:225], v[108:111]
	v_mfma_f32_16x16x32_bf16 v[100:103], v[132:135], v[230:233], v[100:103]
	v_mfma_f32_16x16x32_bf16 v[92:95], v[140:143], v[230:233], v[92:95]
	v_mfma_f32_16x16x32_bf16 v[84:87], v[132:135], v[238:241], v[84:87]
	v_mfma_f32_16x16x32_bf16 v[76:79], v[140:143], v[238:241], v[76:79]
	s_setprio 0
	s_setprio 1
	v_mfma_f32_16x16x32_bf16 v[116:119], v[168:171], v[210:213], 0
	v_mfma_f32_16x16x32_bf16 v[104:107], v[176:179], v[210:213], 0
	v_mfma_f32_16x16x32_bf16 v[96:99], v[168:171], v[218:221], 0
	v_mfma_f32_16x16x32_bf16 v[88:91], v[176:179], v[218:221], 0
	v_mfma_f32_16x16x32_bf16 v[80:83], v[168:171], v[226:229], 0
	v_mfma_f32_16x16x32_bf16 v[72:75], v[176:179], v[226:229], 0
	v_mfma_f32_16x16x32_bf16 v[68:71], v[168:171], v[234:237], 0
	v_mfma_f32_16x16x32_bf16 v[64:67], v[176:179], v[234:237], 0
	v_mfma_f32_16x16x32_bf16 v[116:119], v[172:175], v[214:217], v[116:119]
	v_mfma_f32_16x16x32_bf16 v[104:107], v[206:209], v[214:217], v[104:107]
	v_mfma_f32_16x16x32_bf16 v[96:99], v[172:175], v[222:225], v[96:99]
	v_mfma_f32_16x16x32_bf16 v[88:91], v[206:209], v[222:225], v[88:91]
	v_mfma_f32_16x16x32_bf16 v[80:83], v[172:175], v[230:233], v[80:83]
	v_mfma_f32_16x16x32_bf16 v[72:75], v[206:209], v[230:233], v[72:75]
	v_mfma_f32_16x16x32_bf16 v[68:71], v[172:175], v[238:241], v[68:71]
	v_mfma_f32_16x16x32_bf16 v[64:67], v[206:209], v[238:241], v[64:67]
	s_setprio 0
	s_barrier
	s_add_i32 s5, s89, s28
	v_lshl_add_u64 v[180:181], s[34:35], 0, v[156:157]
	s_mov_b32 m0, s5
	ds_read_b128 v[210:213], v205 offset:16384
	ds_read_b128 v[214:217], v205 offset:17408
	ds_read_b128 v[218:221], v205 offset:18432
	ds_read_b128 v[222:225], v205 offset:19456
	ds_read_b128 v[226:229], v205 offset:20480
	ds_read_b128 v[230:233], v205 offset:21504
	ds_read_b128 v[234:237], v205 offset:22528
	ds_read_b128 v[238:241], v205 offset:23552
	global_load_lds_dwordx4 v[180:181], off
	s_add_i32 m0, s5, 0x2000
	s_add_u32 s90, s34, 0x40000
	v_lshl_add_u64 v[242:243], s[34:35], 0, v[160:161]
	s_addc_u32 s91, s35, 0
	s_add_i32 s4, s4, s28
	global_load_lds_dwordx4 v[242:243], off
	v_lshl_add_u64 v[244:245], s[90:91], 0, v[156:157]
	s_mov_b32 m0, s4
	v_lshl_add_u64 v[246:247], s[42:43], 0, v[158:159]
	global_load_lds_dwordx4 v[244:245], off
	v_lshl_add_u64 v[244:245], s[90:91], 0, v[160:161]
	s_add_i32 m0, s4, 0x2000
	s_nop 0
	global_load_lds_dwordx4 v[244:245], off
	v_lshl_add_u64 v[244:245], s[42:43], 0, v[154:155]
	s_mov_b32 m0, s69
	s_nop 0
	global_load_lds_dwordx4 v[244:245], off
	s_mov_b32 m0, s62
	s_nop 0
	global_load_lds_dwordx4 v[246:247], off
	s_waitcnt vmcnt(8)
	s_waitcnt lgkmcnt(0)
	s_barrier
	s_setprio 1
	s_waitcnt lgkmcnt(0)
	v_mfma_f32_16x16x32_bf16 v[60:63], v[128:131], v[210:213], 0
	v_mfma_f32_16x16x32_bf16 v[56:59], v[136:139], v[210:213], 0
	v_mfma_f32_16x16x32_bf16 v[52:55], v[128:131], v[218:221], 0
	v_mfma_f32_16x16x32_bf16 v[44:47], v[136:139], v[218:221], 0
	v_mfma_f32_16x16x32_bf16 v[36:39], v[128:131], v[226:229], 0
	v_mfma_f32_16x16x32_bf16 v[28:31], v[136:139], v[226:229], 0
	v_mfma_f32_16x16x32_bf16 v[20:23], v[128:131], v[234:237], 0
	v_mfma_f32_16x16x32_bf16 v[12:15], v[136:139], v[234:237], 0
	v_mfma_f32_16x16x32_bf16 v[60:63], v[132:135], v[214:217], v[60:63]
	v_mfma_f32_16x16x32_bf16 v[56:59], v[140:143], v[214:217], v[56:59]
	v_mfma_f32_16x16x32_bf16 v[52:55], v[132:135], v[222:225], v[52:55]
	v_mfma_f32_16x16x32_bf16 v[44:47], v[140:143], v[222:225], v[44:47]
	v_mfma_f32_16x16x32_bf16 v[36:39], v[132:135], v[230:233], v[36:39]
	v_mfma_f32_16x16x32_bf16 v[28:31], v[140:143], v[230:233], v[28:31]
	v_mfma_f32_16x16x32_bf16 v[20:23], v[132:135], v[238:241], v[20:23]
	v_mfma_f32_16x16x32_bf16 v[12:15], v[140:143], v[238:241], v[12:15]
	s_setprio 0
	s_setprio 1
	v_mfma_f32_16x16x32_bf16 v[48:51], v[168:171], v[210:213], 0
	v_mfma_f32_16x16x32_bf16 v[40:43], v[176:179], v[210:213], 0
	v_mfma_f32_16x16x32_bf16 v[32:35], v[168:171], v[218:221], 0
	v_mfma_f32_16x16x32_bf16 v[24:27], v[176:179], v[218:221], 0
	v_mfma_f32_16x16x32_bf16 v[16:19], v[168:171], v[226:229], 0
	v_mfma_f32_16x16x32_bf16 v[8:11], v[176:179], v[226:229], 0
	v_mfma_f32_16x16x32_bf16 v[4:7], v[168:171], v[234:237], 0
	v_mfma_f32_16x16x32_bf16 v[0:3], v[176:179], v[234:237], 0
	v_mfma_f32_16x16x32_bf16 v[48:51], v[172:175], v[214:217], v[48:51]
	v_mfma_f32_16x16x32_bf16 v[40:43], v[206:209], v[214:217], v[40:43]
	v_mfma_f32_16x16x32_bf16 v[32:35], v[172:175], v[222:225], v[32:35]
	v_mfma_f32_16x16x32_bf16 v[24:27], v[206:209], v[222:225], v[24:27]
	v_mfma_f32_16x16x32_bf16 v[16:19], v[172:175], v[230:233], v[16:19]
	v_mfma_f32_16x16x32_bf16 v[8:11], v[206:209], v[230:233], v[8:11]
	v_mfma_f32_16x16x32_bf16 v[4:7], v[172:175], v[238:241], v[4:7]
	v_mfma_f32_16x16x32_bf16 v[0:3], v[206:209], v[238:241], v[0:3]
	s_setprio 0
	s_barrier
	s_add_i32 s4, 0, 0x18000
	s_add_i32 s5, 0, 0x1c000
	v_add_u32_e32 v140, s4, v203
	v_add_u32_e32 v144, s5, v203
	ds_read_b128 v[128:131], v140
	ds_read_b128 v[132:135], v140 offset:1024
	ds_read_b128 v[136:139], v140 offset:2048
	ds_read_b128 v[140:143], v140 offset:3072
	ds_read_b128 v[168:171], v144
	ds_read_b128 v[172:175], v144 offset:1024
	ds_read_b128 v[176:179], v144 offset:2048
	ds_read_b128 v[206:209], v144 offset:3072
	s_add_u32 s42, s42, 0x40000
	s_addc_u32 s43, s43, 0
	s_mov_b32 m0, s63
	v_lshl_add_u64 v[248:249], s[42:43], 0, v[154:155]
	ds_read_b128 v[210:213], v205 offset:32768
	ds_read_b128 v[214:217], v205 offset:33792
	ds_read_b128 v[218:221], v205 offset:34816
	ds_read_b128 v[222:225], v205 offset:35840
	ds_read_b128 v[226:229], v205 offset:36864
	ds_read_b128 v[230:233], v205 offset:37888
	ds_read_b128 v[234:237], v205 offset:38912
	ds_read_b128 v[238:241], v205 offset:39936
	global_load_lds_dwordx4 v[248:249], off
	v_lshl_add_u64 v[248:249], s[42:43], 0, v[158:159]
	s_mov_b32 m0, s50
	s_nop 0
	global_load_lds_dwordx4 v[248:249], off
	s_waitcnt vmcnt(8)
	s_waitcnt lgkmcnt(0)
	s_barrier
	s_setprio 1
	s_waitcnt lgkmcnt(0)
	v_mfma_f32_16x16x32_bf16 v[124:127], v[128:131], v[210:213], v[124:127]
	v_mfma_f32_16x16x32_bf16 v[120:123], v[136:139], v[210:213], v[120:123]
	v_mfma_f32_16x16x32_bf16 v[112:115], v[128:131], v[218:221], v[112:115]
	v_mfma_f32_16x16x32_bf16 v[108:111], v[136:139], v[218:221], v[108:111]
	v_mfma_f32_16x16x32_bf16 v[100:103], v[128:131], v[226:229], v[100:103]
	v_mfma_f32_16x16x32_bf16 v[92:95], v[136:139], v[226:229], v[92:95]
	v_mfma_f32_16x16x32_bf16 v[84:87], v[128:131], v[234:237], v[84:87]
	v_mfma_f32_16x16x32_bf16 v[76:79], v[136:139], v[234:237], v[76:79]
	v_mfma_f32_16x16x32_bf16 v[124:127], v[132:135], v[214:217], v[124:127]
	v_mfma_f32_16x16x32_bf16 v[120:123], v[140:143], v[214:217], v[120:123]
	v_mfma_f32_16x16x32_bf16 v[112:115], v[132:135], v[222:225], v[112:115]
	v_mfma_f32_16x16x32_bf16 v[108:111], v[140:143], v[222:225], v[108:111]
	v_mfma_f32_16x16x32_bf16 v[100:103], v[132:135], v[230:233], v[100:103]
	v_mfma_f32_16x16x32_bf16 v[92:95], v[140:143], v[230:233], v[92:95]
	v_mfma_f32_16x16x32_bf16 v[84:87], v[132:135], v[238:241], v[84:87]
	v_mfma_f32_16x16x32_bf16 v[76:79], v[140:143], v[238:241], v[76:79]
	s_setprio 0
	s_setprio 1
	v_mfma_f32_16x16x32_bf16 v[116:119], v[168:171], v[210:213], v[116:119]
	v_mfma_f32_16x16x32_bf16 v[104:107], v[176:179], v[210:213], v[104:107]
	v_mfma_f32_16x16x32_bf16 v[96:99], v[168:171], v[218:221], v[96:99]
	v_mfma_f32_16x16x32_bf16 v[88:91], v[176:179], v[218:221], v[88:91]
	v_mfma_f32_16x16x32_bf16 v[80:83], v[168:171], v[226:229], v[80:83]
	v_mfma_f32_16x16x32_bf16 v[72:75], v[176:179], v[226:229], v[72:75]
	v_mfma_f32_16x16x32_bf16 v[68:71], v[168:171], v[234:237], v[68:71]
	v_mfma_f32_16x16x32_bf16 v[64:67], v[176:179], v[234:237], v[64:67]
	v_mfma_f32_16x16x32_bf16 v[116:119], v[172:175], v[214:217], v[116:119]
	v_mfma_f32_16x16x32_bf16 v[104:107], v[206:209], v[214:217], v[104:107]
	v_mfma_f32_16x16x32_bf16 v[96:99], v[172:175], v[222:225], v[96:99]
	v_mfma_f32_16x16x32_bf16 v[88:91], v[206:209], v[222:225], v[88:91]
	v_mfma_f32_16x16x32_bf16 v[80:83], v[172:175], v[230:233], v[80:83]
	v_mfma_f32_16x16x32_bf16 v[72:75], v[206:209], v[230:233], v[72:75]
	v_mfma_f32_16x16x32_bf16 v[68:71], v[172:175], v[238:241], v[68:71]
	v_mfma_f32_16x16x32_bf16 v[64:67], v[206:209], v[238:241], v[64:67]
	s_setprio 0
	s_barrier
	s_add_i32 s4, s4, s28
	v_lshl_add_u64 v[180:181], v[180:181], 0, s[26:27]
	s_mov_b32 m0, s4
	ds_read_b128 v[210:213], v205 offset:49152
	ds_read_b128 v[214:217], v205 offset:50176
	ds_read_b128 v[218:221], v205 offset:51200
	ds_read_b128 v[222:225], v205 offset:52224
	ds_read_b128 v[226:229], v205 offset:53248
	ds_read_b128 v[230:233], v205 offset:54272
	ds_read_b128 v[234:237], v205 offset:55296
	ds_read_b128 v[238:241], v205 offset:56320
	global_load_lds_dwordx4 v[180:181], off
	s_add_i32 m0, s4, 0x2000
	s_add_u32 s34, s34, 0x40080
	v_lshl_add_u64 v[180:181], v[242:243], 0, s[26:27]
	s_addc_u32 s35, s35, 0
	s_add_i32 s4, s5, s28
	global_load_lds_dwordx4 v[180:181], off
	v_lshl_add_u64 v[180:181], s[34:35], 0, v[156:157]
	s_mov_b32 m0, s4
	s_nop 0
	global_load_lds_dwordx4 v[180:181], off
	v_lshl_add_u64 v[180:181], s[34:35], 0, v[160:161]
	s_add_i32 m0, s4, 0x2000
	s_nop 0
	global_load_lds_dwordx4 v[180:181], off
	v_lshl_add_u64 v[180:181], v[244:245], 0, s[26:27]
	s_mov_b32 m0, s51
	s_nop 0
	global_load_lds_dwordx4 v[180:181], off
	v_lshl_add_u64 v[180:181], v[246:247], 0, s[26:27]
	s_mov_b32 m0, s64
	s_nop 0
	global_load_lds_dwordx4 v[180:181], off
	s_waitcnt vmcnt(8)
	s_waitcnt lgkmcnt(0)
	s_barrier
	s_setprio 1
	s_waitcnt lgkmcnt(0)
	v_mfma_f32_16x16x32_bf16 v[60:63], v[128:131], v[210:213], v[60:63]
	v_mfma_f32_16x16x32_bf16 v[56:59], v[136:139], v[210:213], v[56:59]
	v_mfma_f32_16x16x32_bf16 v[52:55], v[128:131], v[218:221], v[52:55]
	v_mfma_f32_16x16x32_bf16 v[44:47], v[136:139], v[218:221], v[44:47]
	v_mfma_f32_16x16x32_bf16 v[36:39], v[128:131], v[226:229], v[36:39]
	v_mfma_f32_16x16x32_bf16 v[28:31], v[136:139], v[226:229], v[28:31]
	v_mfma_f32_16x16x32_bf16 v[20:23], v[128:131], v[234:237], v[20:23]
	v_mfma_f32_16x16x32_bf16 v[12:15], v[136:139], v[234:237], v[12:15]
	v_mfma_f32_16x16x32_bf16 v[60:63], v[132:135], v[214:217], v[60:63]
	v_mfma_f32_16x16x32_bf16 v[56:59], v[140:143], v[214:217], v[56:59]
	v_mfma_f32_16x16x32_bf16 v[52:55], v[132:135], v[222:225], v[52:55]
	v_mfma_f32_16x16x32_bf16 v[44:47], v[140:143], v[222:225], v[44:47]
	v_mfma_f32_16x16x32_bf16 v[36:39], v[132:135], v[230:233], v[36:39]
	v_mfma_f32_16x16x32_bf16 v[28:31], v[140:143], v[230:233], v[28:31]
	v_mfma_f32_16x16x32_bf16 v[20:23], v[132:135], v[238:241], v[20:23]
	v_mfma_f32_16x16x32_bf16 v[12:15], v[140:143], v[238:241], v[12:15]
	s_setprio 0
	s_setprio 1
	v_mfma_f32_16x16x32_bf16 v[48:51], v[168:171], v[210:213], v[48:51]
	v_mfma_f32_16x16x32_bf16 v[40:43], v[176:179], v[210:213], v[40:43]
	v_mfma_f32_16x16x32_bf16 v[32:35], v[168:171], v[218:221], v[32:35]
	v_mfma_f32_16x16x32_bf16 v[24:27], v[176:179], v[218:221], v[24:27]
	v_mfma_f32_16x16x32_bf16 v[16:19], v[168:171], v[226:229], v[16:19]
	v_mfma_f32_16x16x32_bf16 v[8:11], v[176:179], v[226:229], v[8:11]
	v_mfma_f32_16x16x32_bf16 v[4:7], v[168:171], v[234:237], v[4:7]
	v_mfma_f32_16x16x32_bf16 v[0:3], v[176:179], v[234:237], v[0:3]
	v_mfma_f32_16x16x32_bf16 v[48:51], v[172:175], v[214:217], v[48:51]
	v_mfma_f32_16x16x32_bf16 v[40:43], v[206:209], v[214:217], v[40:43]
	v_mfma_f32_16x16x32_bf16 v[32:35], v[172:175], v[222:225], v[32:35]
	v_mfma_f32_16x16x32_bf16 v[24:27], v[206:209], v[222:225], v[24:27]
	v_mfma_f32_16x16x32_bf16 v[16:19], v[172:175], v[230:233], v[16:19]
	v_mfma_f32_16x16x32_bf16 v[8:11], v[206:209], v[230:233], v[8:11]
	v_mfma_f32_16x16x32_bf16 v[4:7], v[172:175], v[238:241], v[4:7]
	v_mfma_f32_16x16x32_bf16 v[0:3], v[206:209], v[238:241], v[0:3]
	s_setprio 0
	s_barrier
	s_add_i32 s88, s88, 2
	s_add_u32 s0, s0, 0x100
	s_addc_u32 s1, s1, 0
	s_add_u32 s79, s79, 0x100
	s_addc_u32 s84, s84, 0
	s_cmp_gt_u32 s88, 13
	s_cbranch_scc0 .LBB0_605
	s_branch .Lkexit_605

.Lkexit_605:
	s_and_b64 vcc, exec, s[66:67]
	s_cbranch_vccz .LBB0_608
	s_barrier

.LBB0_1004:
	s_ashr_i32 s47, s46, 31
	s_lshl_b64 s[4:5], s[46:47], 18
	s_add_u32 s48, s33, s4
	s_addc_u32 s49, s36, s5
	s_and_b64 s[4:5], s[38:39], exec
	s_cselect_b32 s29, s49, s55
	s_cselect_b32 s47, s48, s54
	s_ashr_i32 s45, s44, 31
	s_lshl_b64 s[4:5], s[44:45], 18
	s_add_u32 s50, s60, s4
	s_addc_u32 s51, s61, s5
	s_and_b64 s[4:5], s[38:39], exec
	s_cselect_b32 s45, s51, s59
	s_cselect_b32 s68, s50, s58
	s_add_u32 s54, s54, 0x20080
	s_addc_u32 s55, s55, 0
	s_add_u32 s69, s58, 0x100
	s_addc_u32 s70, s59, 0
	s_mov_b32 s71, -2
.Lpeel_1005:
	s_add_u32 s4, s54, 0xfffe0080
	s_addc_u32 s5, s55, -1
	s_add_i32 s72, 0, 0x10000
	s_cmp_eq_u32 s71, 4
	s_cselect_b32 s59, s29, s5
	s_cselect_b32 s58, s47, s4
	v_add_u32_e32 v138, s72, v141
	s_cselect_b32 s35, s45, s70
	s_cselect_b32 s34, s68, s69
	s_add_i32 s73, 0, 0x14000
	ds_read_b128 v[154:157], v138
	ds_read_b128 v[158:161], v138 offset:1024
	ds_read_b128 v[162:165], v138 offset:2048
	ds_read_b128 v[166:169], v138 offset:3072
	v_add_u32_e32 v138, s73, v141
	ds_read_b128 v[170:173], v138
	ds_read_b128 v[174:177], v138 offset:1024
	ds_read_b128 v[178:181], v138 offset:2048
	ds_read_b128 v[204:207], v138 offset:3072
	v_lshl_add_u64 v[138:139], s[54:55], 0, v[134:135]
	s_add_i32 m0, s53, 0xc000
	ds_read_b128 v[208:211], v143
	ds_read_b128 v[212:215], v143 offset:1024
	ds_read_b128 v[216:219], v143 offset:2048
	ds_read_b128 v[220:223], v143 offset:3072
	ds_read_b128 v[224:227], v143 offset:4096
	ds_read_b128 v[228:231], v143 offset:5120
	ds_read_b128 v[232:235], v143 offset:6144
	ds_read_b128 v[236:239], v143 offset:7168
	global_load_lds_dwordx4 v[138:139], off
	v_lshl_add_u64 v[138:139], s[54:55], 0, v[136:137]
	s_add_i32 m0, s53, 0xe000
	s_nop 0
	global_load_lds_dwordx4 v[138:139], off
	s_waitcnt vmcnt(8)
	s_waitcnt lgkmcnt(0)
	s_barrier
	s_setprio 1
	s_waitcnt lgkmcnt(0)
	v_mfma_f32_16x16x32_bf16 v[120:123], v[154:157], v[208:211], 0
	v_mfma_f32_16x16x32_bf16 v[124:127], v[162:165], v[208:211], 0
	v_mfma_f32_16x16x32_bf16 v[104:107], v[154:157], v[216:219], 0
	v_mfma_f32_16x16x32_bf16 v[108:111], v[162:165], v[216:219], 0
	v_mfma_f32_16x16x32_bf16 v[88:91], v[154:157], v[224:227], 0
	v_mfma_f32_16x16x32_bf16 v[92:95], v[162:165], v[224:227], 0
	v_mfma_f32_16x16x32_bf16 v[72:75], v[154:157], v[232:235], 0
	v_mfma_f32_16x16x32_bf16 v[76:79], v[162:165], v[232:235], 0
	v_mfma_f32_16x16x32_bf16 v[120:123], v[158:161], v[212:215], v[120:123]
	v_mfma_f32_16x16x32_bf16 v[124:127], v[166:169], v[212:215], v[124:127]
	v_mfma_f32_16x16x32_bf16 v[104:107], v[158:161], v[220:223], v[104:107]
	v_mfma_f32_16x16x32_bf16 v[108:111], v[166:169], v[220:223], v[108:111]
	v_mfma_f32_16x16x32_bf16 v[88:91], v[158:161], v[228:231], v[88:91]
	v_mfma_f32_16x16x32_bf16 v[92:95], v[166:169], v[228:231], v[92:95]
	v_mfma_f32_16x16x32_bf16 v[72:75], v[158:161], v[236:239], v[72:75]
	v_mfma_f32_16x16x32_bf16 v[76:79], v[166:169], v[236:239], v[76:79]
	s_setprio 0
	s_setprio 1
	v_mfma_f32_16x16x32_bf16 v[112:115], v[170:173], v[208:211], 0
	v_mfma_f32_16x16x32_bf16 v[116:119], v[178:181], v[208:211], 0
	v_mfma_f32_16x16x32_bf16 v[96:99], v[170:173], v[216:219], 0
	v_mfma_f32_16x16x32_bf16 v[100:103], v[178:181], v[216:219], 0
	v_mfma_f32_16x16x32_bf16 v[80:83], v[170:173], v[224:227], 0
	v_mfma_f32_16x16x32_bf16 v[84:87], v[178:181], v[224:227], 0
	v_mfma_f32_16x16x32_bf16 v[64:67], v[170:173], v[232:235], 0
	v_mfma_f32_16x16x32_bf16 v[68:71], v[178:181], v[232:235], 0
	v_mfma_f32_16x16x32_bf16 v[112:115], v[174:177], v[212:215], v[112:115]
	v_mfma_f32_16x16x32_bf16 v[116:119], v[204:207], v[212:215], v[116:119]
	v_mfma_f32_16x16x32_bf16 v[96:99], v[174:177], v[220:223], v[96:99]
	v_mfma_f32_16x16x32_bf16 v[100:103], v[204:207], v[220:223], v[100:103]
	v_mfma_f32_16x16x32_bf16 v[80:83], v[174:177], v[228:231], v[80:83]
	v_mfma_f32_16x16x32_bf16 v[84:87], v[204:207], v[228:231], v[84:87]
	v_mfma_f32_16x16x32_bf16 v[64:67], v[174:177], v[236:239], v[64:67]
	v_mfma_f32_16x16x32_bf16 v[68:71], v[204:207], v[236:239], v[68:71]
	s_setprio 0
	s_barrier
	s_add_i32 s4, s72, s30
	v_lshl_add_u64 v[138:139], s[34:35], 0, v[144:145]
	s_mov_b32 m0, s4
	ds_read_b128 v[208:211], v143 offset:16384
	ds_read_b128 v[212:215], v143 offset:17408
	ds_read_b128 v[216:219], v143 offset:18432
	ds_read_b128 v[220:223], v143 offset:19456
	ds_read_b128 v[224:227], v143 offset:20480
	ds_read_b128 v[228:231], v143 offset:21504
	ds_read_b128 v[232:235], v143 offset:22528
	ds_read_b128 v[236:239], v143 offset:23552
	global_load_lds_dwordx4 v[138:139], off
	s_add_i32 m0, s4, 0x2000
	s_add_u32 s4, s34, 0x20000
	v_lshl_add_u64 v[202:203], s[34:35], 0, v[132:133]
	s_addc_u32 s5, s35, 0
	s_add_i32 s72, s73, s30
	global_load_lds_dwordx4 v[202:203], off
	v_lshl_add_u64 v[240:241], s[4:5], 0, v[144:145]
	s_mov_b32 m0, s72
	v_lshl_add_u64 v[242:243], s[58:59], 0, v[130:131]
	global_load_lds_dwordx4 v[240:241], off
	v_lshl_add_u64 v[240:241], s[4:5], 0, v[132:133]
	s_add_i32 m0, s72, 0x2000
	s_nop 0
	global_load_lds_dwordx4 v[240:241], off
	v_lshl_add_u64 v[240:241], s[58:59], 0, v[128:129]
	s_mov_b32 m0, s53
	s_nop 0
	global_load_lds_dwordx4 v[240:241], off
	s_mov_b32 m0, s62
	s_nop 0
	global_load_lds_dwordx4 v[242:243], off
	s_waitcnt vmcnt(8)
	s_waitcnt lgkmcnt(0)
	s_barrier
	s_setprio 1
	s_waitcnt lgkmcnt(0)
	v_mfma_f32_16x16x32_bf16 v[56:59], v[154:157], v[208:211], 0
	v_mfma_f32_16x16x32_bf16 v[60:63], v[162:165], v[208:211], 0
	v_mfma_f32_16x16x32_bf16 v[40:43], v[154:157], v[216:219], 0
	v_mfma_f32_16x16x32_bf16 v[44:47], v[162:165], v[216:219], 0
	v_mfma_f32_16x16x32_bf16 v[24:27], v[154:157], v[224:227], 0
	v_mfma_f32_16x16x32_bf16 v[28:31], v[162:165], v[224:227], 0
	v_mfma_f32_16x16x32_bf16 v[8:11], v[154:157], v[232:235], 0
	v_mfma_f32_16x16x32_bf16 v[12:15], v[162:165], v[232:235], 0
	v_mfma_f32_16x16x32_bf16 v[56:59], v[158:161], v[212:215], v[56:59]
	v_mfma_f32_16x16x32_bf16 v[60:63], v[166:169], v[212:215], v[60:63]
	v_mfma_f32_16x16x32_bf16 v[40:43], v[158:161], v[220:223], v[40:43]
	v_mfma_f32_16x16x32_bf16 v[44:47], v[166:169], v[220:223], v[44:47]
	v_mfma_f32_16x16x32_bf16 v[24:27], v[158:161], v[228:231], v[24:27]
	v_mfma_f32_16x16x32_bf16 v[28:31], v[166:169], v[228:231], v[28:31]
	v_mfma_f32_16x16x32_bf16 v[8:11], v[158:161], v[236:239], v[8:11]
	v_mfma_f32_16x16x32_bf16 v[12:15], v[166:169], v[236:239], v[12:15]
	s_setprio 0
	s_setprio 1
	v_mfma_f32_16x16x32_bf16 v[48:51], v[170:173], v[208:211], 0
	v_mfma_f32_16x16x32_bf16 v[52:55], v[178:181], v[208:211], 0
	v_mfma_f32_16x16x32_bf16 v[32:35], v[170:173], v[216:219], 0
	v_mfma_f32_16x16x32_bf16 v[36:39], v[178:181], v[216:219], 0
	v_mfma_f32_16x16x32_bf16 v[16:19], v[170:173], v[224:227], 0
	v_mfma_f32_16x16x32_bf16 v[20:23], v[178:181], v[224:227], 0
	v_mfma_f32_16x16x32_bf16 v[0:3], v[170:173], v[232:235], 0
	v_mfma_f32_16x16x32_bf16 v[4:7], v[178:181], v[232:235], 0
	v_mfma_f32_16x16x32_bf16 v[48:51], v[174:177], v[212:215], v[48:51]
	v_mfma_f32_16x16x32_bf16 v[52:55], v[204:207], v[212:215], v[52:55]
	v_mfma_f32_16x16x32_bf16 v[32:35], v[174:177], v[220:223], v[32:35]
	v_mfma_f32_16x16x32_bf16 v[36:39], v[204:207], v[220:223], v[36:39]
	v_mfma_f32_16x16x32_bf16 v[16:19], v[174:177], v[228:231], v[16:19]
	v_mfma_f32_16x16x32_bf16 v[20:23], v[204:207], v[228:231], v[20:23]
	v_mfma_f32_16x16x32_bf16 v[0:3], v[174:177], v[236:239], v[0:3]
	v_mfma_f32_16x16x32_bf16 v[4:7], v[204:207], v[236:239], v[4:7]
	s_setprio 0
	s_barrier
	s_add_i32 s72, 0, 0x18000
	s_add_i32 s73, 0, 0x1c000
	v_add_u32_e32 v166, s72, v141
	v_add_u32_e32 v204, s73, v141
	ds_read_b128 v[154:157], v166
	ds_read_b128 v[158:161], v166 offset:1024
	ds_read_b128 v[162:165], v166 offset:2048
	ds_read_b128 v[166:169], v166 offset:3072
	ds_read_b128 v[170:173], v204
	ds_read_b128 v[174:177], v204 offset:1024
	ds_read_b128 v[178:181], v204 offset:2048
	ds_read_b128 v[204:207], v204 offset:3072
	s_add_u32 s4, s58, 0x20000
	s_addc_u32 s5, s59, 0
	s_mov_b32 m0, s63
	v_lshl_add_u64 v[244:245], s[4:5], 0, v[128:129]
	ds_read_b128 v[208:211], v143 offset:32768
	ds_read_b128 v[212:215], v143 offset:33792
	ds_read_b128 v[216:219], v143 offset:34816
	ds_read_b128 v[220:223], v143 offset:35840
	ds_read_b128 v[224:227], v143 offset:36864
	ds_read_b128 v[228:231], v143 offset:37888
	ds_read_b128 v[232:235], v143 offset:38912
	ds_read_b128 v[236:239], v143 offset:39936
	global_load_lds_dwordx4 v[244:245], off
	v_lshl_add_u64 v[244:245], s[4:5], 0, v[130:131]
	s_mov_b32 m0, s64
	s_nop 0
	global_load_lds_dwordx4 v[244:245], off
	s_waitcnt vmcnt(8)
	s_waitcnt lgkmcnt(0)
	s_barrier
	s_setprio 1
	s_waitcnt lgkmcnt(0)
	v_mfma_f32_16x16x32_bf16 v[120:123], v[154:157], v[208:211], v[120:123]
	v_mfma_f32_16x16x32_bf16 v[124:127], v[162:165], v[208:211], v[124:127]
	v_mfma_f32_16x16x32_bf16 v[104:107], v[154:157], v[216:219], v[104:107]
	v_mfma_f32_16x16x32_bf16 v[108:111], v[162:165], v[216:219], v[108:111]
	v_mfma_f32_16x16x32_bf16 v[88:91], v[154:157], v[224:227], v[88:91]
	v_mfma_f32_16x16x32_bf16 v[92:95], v[162:165], v[224:227], v[92:95]
	v_mfma_f32_16x16x32_bf16 v[72:75], v[154:157], v[232:235], v[72:75]
	v_mfma_f32_16x16x32_bf16 v[76:79], v[162:165], v[232:235], v[76:79]
	v_mfma_f32_16x16x32_bf16 v[120:123], v[158:161], v[212:215], v[120:123]
	v_mfma_f32_16x16x32_bf16 v[124:127], v[166:169], v[212:215], v[124:127]
	v_mfma_f32_16x16x32_bf16 v[104:107], v[158:161], v[220:223], v[104:107]
	v_mfma_f32_16x16x32_bf16 v[108:111], v[166:169], v[220:223], v[108:111]
	v_mfma_f32_16x16x32_bf16 v[88:91], v[158:161], v[228:231], v[88:91]
	v_mfma_f32_16x16x32_bf16 v[92:95], v[166:169], v[228:231], v[92:95]
	v_mfma_f32_16x16x32_bf16 v[72:75], v[158:161], v[236:239], v[72:75]
	v_mfma_f32_16x16x32_bf16 v[76:79], v[166:169], v[236:239], v[76:79]
	s_setprio 0
	s_setprio 1
	v_mfma_f32_16x16x32_bf16 v[112:115], v[170:173], v[208:211], v[112:115]
	v_mfma_f32_16x16x32_bf16 v[116:119], v[178:181], v[208:211], v[116:119]
	v_mfma_f32_16x16x32_bf16 v[96:99], v[170:173], v[216:219], v[96:99]
	v_mfma_f32_16x16x32_bf16 v[100:103], v[178:181], v[216:219], v[100:103]
	v_mfma_f32_16x16x32_bf16 v[80:83], v[170:173], v[224:227], v[80:83]
	v_mfma_f32_16x16x32_bf16 v[84:87], v[178:181], v[224:227], v[84:87]
	v_mfma_f32_16x16x32_bf16 v[64:67], v[170:173], v[232:235], v[64:67]
	v_mfma_f32_16x16x32_bf16 v[68:71], v[178:181], v[232:235], v[68:71]
	v_mfma_f32_16x16x32_bf16 v[112:115], v[174:177], v[212:215], v[112:115]
	v_mfma_f32_16x16x32_bf16 v[116:119], v[204:207], v[212:215], v[116:119]
	v_mfma_f32_16x16x32_bf16 v[96:99], v[174:177], v[220:223], v[96:99]
	v_mfma_f32_16x16x32_bf16 v[100:103], v[204:207], v[220:223], v[100:103]
	v_mfma_f32_16x16x32_bf16 v[80:83], v[174:177], v[228:231], v[80:83]
	v_mfma_f32_16x16x32_bf16 v[84:87], v[204:207], v[228:231], v[84:87]
	v_mfma_f32_16x16x32_bf16 v[64:67], v[174:177], v[236:239], v[64:67]
	v_mfma_f32_16x16x32_bf16 v[68:71], v[204:207], v[236:239], v[68:71]
	s_setprio 0
	s_barrier
	s_add_i32 s4, s72, s30
	v_lshl_add_u64 v[138:139], v[138:139], 0, s[26:27]
	s_mov_b32 m0, s4
	ds_read_b128 v[208:211], v143 offset:49152
	ds_read_b128 v[212:215], v143 offset:50176
	ds_read_b128 v[216:219], v143 offset:51200
	ds_read_b128 v[220:223], v143 offset:52224
	ds_read_b128 v[224:227], v143 offset:53248
	ds_read_b128 v[228:231], v143 offset:54272
	ds_read_b128 v[232:235], v143 offset:55296
	ds_read_b128 v[236:239], v143 offset:56320
	global_load_lds_dwordx4 v[138:139], off
	s_add_i32 m0, s4, 0x2000
	s_add_u32 s4, s34, 0x20080
	v_lshl_add_u64 v[138:139], v[202:203], 0, s[26:27]
	s_addc_u32 s5, s35, 0
	s_add_i32 s34, s73, s30
	global_load_lds_dwordx4 v[138:139], off
	v_lshl_add_u64 v[138:139], s[4:5], 0, v[144:145]
	s_mov_b32 m0, s34
	s_nop 0
	global_load_lds_dwordx4 v[138:139], off
	v_lshl_add_u64 v[138:139], s[4:5], 0, v[132:133]
	s_add_i32 m0, s34, 0x2000
	s_nop 0
	global_load_lds_dwordx4 v[138:139], off
	v_lshl_add_u64 v[138:139], v[240:241], 0, s[26:27]
	s_mov_b32 m0, s65
	s_nop 0
	global_load_lds_dwordx4 v[138:139], off
	v_lshl_add_u64 v[138:139], v[242:243], 0, s[26:27]
	s_mov_b32 m0, s66
	s_nop 0
	global_load_lds_dwordx4 v[138:139], off
	s_waitcnt vmcnt(8)
	s_waitcnt lgkmcnt(0)
	s_barrier
	s_setprio 1
	s_waitcnt lgkmcnt(0)
	v_mfma_f32_16x16x32_bf16 v[56:59], v[154:157], v[208:211], v[56:59]
	v_mfma_f32_16x16x32_bf16 v[60:63], v[162:165], v[208:211], v[60:63]
	v_mfma_f32_16x16x32_bf16 v[40:43], v[154:157], v[216:219], v[40:43]
	v_mfma_f32_16x16x32_bf16 v[44:47], v[162:165], v[216:219], v[44:47]
	v_mfma_f32_16x16x32_bf16 v[24:27], v[154:157], v[224:227], v[24:27]
	v_mfma_f32_16x16x32_bf16 v[28:31], v[162:165], v[224:227], v[28:31]
	v_mfma_f32_16x16x32_bf16 v[8:11], v[154:157], v[232:235], v[8:11]
	v_mfma_f32_16x16x32_bf16 v[12:15], v[162:165], v[232:235], v[12:15]
	v_mfma_f32_16x16x32_bf16 v[56:59], v[158:161], v[212:215], v[56:59]
	v_mfma_f32_16x16x32_bf16 v[60:63], v[166:169], v[212:215], v[60:63]
	v_mfma_f32_16x16x32_bf16 v[40:43], v[158:161], v[220:223], v[40:43]
	v_mfma_f32_16x16x32_bf16 v[44:47], v[166:169], v[220:223], v[44:47]
	v_mfma_f32_16x16x32_bf16 v[24:27], v[158:161], v[228:231], v[24:27]
	v_mfma_f32_16x16x32_bf16 v[28:31], v[166:169], v[228:231], v[28:31]
	v_mfma_f32_16x16x32_bf16 v[8:11], v[158:161], v[236:239], v[8:11]
	v_mfma_f32_16x16x32_bf16 v[12:15], v[166:169], v[236:239], v[12:15]
	s_setprio 0
	s_setprio 1
	v_mfma_f32_16x16x32_bf16 v[48:51], v[170:173], v[208:211], v[48:51]
	v_mfma_f32_16x16x32_bf16 v[52:55], v[178:181], v[208:211], v[52:55]
	v_mfma_f32_16x16x32_bf16 v[32:35], v[170:173], v[216:219], v[32:35]
	v_mfma_f32_16x16x32_bf16 v[36:39], v[178:181], v[216:219], v[36:39]
	v_mfma_f32_16x16x32_bf16 v[16:19], v[170:173], v[224:227], v[16:19]
	v_mfma_f32_16x16x32_bf16 v[20:23], v[178:181], v[224:227], v[20:23]
	v_mfma_f32_16x16x32_bf16 v[0:3], v[170:173], v[232:235], v[0:3]
	v_mfma_f32_16x16x32_bf16 v[4:7], v[178:181], v[232:235], v[4:7]
	v_mfma_f32_16x16x32_bf16 v[48:51], v[174:177], v[212:215], v[48:51]
	v_mfma_f32_16x16x32_bf16 v[52:55], v[204:207], v[212:215], v[52:55]
	v_mfma_f32_16x16x32_bf16 v[32:35], v[174:177], v[220:223], v[32:35]
	v_mfma_f32_16x16x32_bf16 v[36:39], v[204:207], v[220:223], v[36:39]
	v_mfma_f32_16x16x32_bf16 v[16:19], v[174:177], v[228:231], v[16:19]
	v_mfma_f32_16x16x32_bf16 v[20:23], v[204:207], v[228:231], v[20:23]
	v_mfma_f32_16x16x32_bf16 v[0:3], v[174:177], v[236:239], v[0:3]
	v_mfma_f32_16x16x32_bf16 v[4:7], v[204:207], v[236:239], v[4:7]
	s_setprio 0
	s_barrier
	s_add_i32 s71, s71, 2
	s_add_u32 s54, s54, 0x100
	s_addc_u32 s55, s55, 0
	s_add_u32 s69, s69, 0x100
	s_addc_u32 s70, s70, 0
	s_cmp_gt_u32 s71, 5
	s_cbranch_scc0 .LBB0_1005
	s_branch .Lkexit_1005

.Lkexit_1005:
	v_readlane_b32 s68, v255, 7
	s_and_b64 vcc, exec, s[42:43]
	v_readlane_b32 s69, v255, 8
	s_cbranch_vccz .LBB0_1008
	s_barrier

.LBB0_1092:
	s_ashr_i32 s51, s50, 31
	s_lshl_b64 s[4:5], s[50:51], 18
	s_add_u32 s52, s29, s4
	s_addc_u32 s53, s30, s5
	s_and_b64 s[4:5], s[38:39], exec
	s_cselect_b32 s33, s53, s59
	s_cselect_b32 s36, s52, s58
	s_ashr_i32 s49, s48, 31
	s_lshl_b64 s[4:5], s[48:49], 18
	s_add_u32 s54, s62, s4
	s_addc_u32 s55, s63, s5
	s_and_b64 s[4:5], s[38:39], exec
	s_cselect_b32 s49, s55, s61
	s_cselect_b32 s51, s54, s60
	s_add_u32 s58, s58, 0x20080
	s_addc_u32 s59, s59, 0
	s_add_u32 s71, s60, 0x100
	s_addc_u32 s72, s61, 0
	s_mov_b32 s73, -2
.Lpeel_1093:
	s_add_u32 s4, s58, 0xfffe0080
	s_addc_u32 s5, s59, -1
	s_add_i32 s74, 0, 0x10000
	s_cmp_eq_u32 s73, 4
	s_cselect_b32 s61, s33, s5
	s_cselect_b32 s60, s36, s4
	s_cselect_b32 s35, s49, s72
	s_cselect_b32 s34, s51, s71
	s_add_i32 s75, 0, 0x14000
	v_add_u32_e32 v164, s74, v143
	v_add_u32_e32 v180, s75, v143
	ds_read_b128 v[138:141], v164
	ds_read_b128 v[156:159], v164 offset:1024
	ds_read_b128 v[160:163], v164 offset:2048
	ds_read_b128 v[164:167], v164 offset:3072
	ds_read_b128 v[168:171], v180
	ds_read_b128 v[172:175], v180 offset:1024
	ds_read_b128 v[176:179], v180 offset:2048
	ds_read_b128 v[204:207], v180 offset:3072
	v_lshl_add_u64 v[180:181], s[58:59], 0, v[134:135]
	s_add_i32 m0, s64, 0xc000
	ds_read_b128 v[208:211], v155
	ds_read_b128 v[212:215], v155 offset:1024
	ds_read_b128 v[216:219], v155 offset:2048
	ds_read_b128 v[220:223], v155 offset:3072
	ds_read_b128 v[224:227], v155 offset:4096
	ds_read_b128 v[228:231], v155 offset:5120
	ds_read_b128 v[232:235], v155 offset:6144
	ds_read_b128 v[236:239], v155 offset:7168
	global_load_lds_dwordx4 v[180:181], off
	v_lshl_add_u64 v[180:181], s[58:59], 0, v[136:137]
	s_add_i32 m0, s64, 0xe000
	s_nop 0
	global_load_lds_dwordx4 v[180:181], off
	s_waitcnt vmcnt(8)
	s_waitcnt lgkmcnt(0)
	s_barrier
	s_setprio 1
	s_waitcnt lgkmcnt(0)
	v_mfma_f32_16x16x32_bf16 v[124:127], v[138:141], v[208:211], 0
	v_mfma_f32_16x16x32_bf16 v[120:123], v[160:163], v[208:211], 0
	v_mfma_f32_16x16x32_bf16 v[108:111], v[138:141], v[216:219], 0
	v_mfma_f32_16x16x32_bf16 v[104:107], v[160:163], v[216:219], 0
	v_mfma_f32_16x16x32_bf16 v[92:95], v[138:141], v[224:227], 0
	v_mfma_f32_16x16x32_bf16 v[88:91], v[160:163], v[224:227], 0
	v_mfma_f32_16x16x32_bf16 v[76:79], v[138:141], v[232:235], 0
	v_mfma_f32_16x16x32_bf16 v[72:75], v[160:163], v[232:235], 0
	v_mfma_f32_16x16x32_bf16 v[124:127], v[156:159], v[212:215], v[124:127]
	v_mfma_f32_16x16x32_bf16 v[120:123], v[164:167], v[212:215], v[120:123]
	v_mfma_f32_16x16x32_bf16 v[108:111], v[156:159], v[220:223], v[108:111]
	v_mfma_f32_16x16x32_bf16 v[104:107], v[164:167], v[220:223], v[104:107]
	v_mfma_f32_16x16x32_bf16 v[92:95], v[156:159], v[228:231], v[92:95]
	v_mfma_f32_16x16x32_bf16 v[88:91], v[164:167], v[228:231], v[88:91]
	v_mfma_f32_16x16x32_bf16 v[76:79], v[156:159], v[236:239], v[76:79]
	v_mfma_f32_16x16x32_bf16 v[72:75], v[164:167], v[236:239], v[72:75]
	s_setprio 0
	s_setprio 1
	v_mfma_f32_16x16x32_bf16 v[116:119], v[168:171], v[208:211], 0
	v_mfma_f32_16x16x32_bf16 v[112:115], v[176:179], v[208:211], 0
	v_mfma_f32_16x16x32_bf16 v[100:103], v[168:171], v[216:219], 0
	v_mfma_f32_16x16x32_bf16 v[96:99], v[176:179], v[216:219], 0
	v_mfma_f32_16x16x32_bf16 v[84:87], v[168:171], v[224:227], 0
	v_mfma_f32_16x16x32_bf16 v[80:83], v[176:179], v[224:227], 0
	v_mfma_f32_16x16x32_bf16 v[68:71], v[168:171], v[232:235], 0
	v_mfma_f32_16x16x32_bf16 v[64:67], v[176:179], v[232:235], 0
	v_mfma_f32_16x16x32_bf16 v[116:119], v[172:175], v[212:215], v[116:119]
	v_mfma_f32_16x16x32_bf16 v[112:115], v[204:207], v[212:215], v[112:115]
	v_mfma_f32_16x16x32_bf16 v[100:103], v[172:175], v[220:223], v[100:103]
	v_mfma_f32_16x16x32_bf16 v[96:99], v[204:207], v[220:223], v[96:99]
	v_mfma_f32_16x16x32_bf16 v[84:87], v[172:175], v[228:231], v[84:87]
	v_mfma_f32_16x16x32_bf16 v[80:83], v[204:207], v[228:231], v[80:83]
	v_mfma_f32_16x16x32_bf16 v[68:71], v[172:175], v[236:239], v[68:71]
	v_mfma_f32_16x16x32_bf16 v[64:67], v[204:207], v[236:239], v[64:67]
	s_setprio 0
	s_barrier
	s_add_i32 s4, s74, s28
	v_lshl_add_u64 v[180:181], s[34:35], 0, v[144:145]
	s_mov_b32 m0, s4
	ds_read_b128 v[208:211], v155 offset:16384
	ds_read_b128 v[212:215], v155 offset:17408
	ds_read_b128 v[216:219], v155 offset:18432
	ds_read_b128 v[220:223], v155 offset:19456
	ds_read_b128 v[224:227], v155 offset:20480
	ds_read_b128 v[228:231], v155 offset:21504
	ds_read_b128 v[232:235], v155 offset:22528
	ds_read_b128 v[236:239], v155 offset:23552
	global_load_lds_dwordx4 v[180:181], off
	s_add_i32 m0, s4, 0x2000
	s_add_u32 s4, s34, 0x20000
	v_lshl_add_u64 v[202:203], s[34:35], 0, v[132:133]
	s_addc_u32 s5, s35, 0
	s_add_i32 s74, s75, s28
	global_load_lds_dwordx4 v[202:203], off
	v_lshl_add_u64 v[240:241], s[4:5], 0, v[144:145]
	s_mov_b32 m0, s74
	v_lshl_add_u64 v[242:243], s[60:61], 0, v[130:131]
	global_load_lds_dwordx4 v[240:241], off
	v_lshl_add_u64 v[240:241], s[4:5], 0, v[132:133]
	s_add_i32 m0, s74, 0x2000
	s_nop 0
	global_load_lds_dwordx4 v[240:241], off
	v_lshl_add_u64 v[240:241], s[60:61], 0, v[128:129]
	s_mov_b32 m0, s64
	s_nop 0
	global_load_lds_dwordx4 v[240:241], off
	s_mov_b32 m0, s65
	s_nop 0
	global_load_lds_dwordx4 v[242:243], off
	s_waitcnt vmcnt(8)
	s_waitcnt lgkmcnt(0)
	s_barrier
	s_setprio 1
	s_waitcnt lgkmcnt(0)
	v_mfma_f32_16x16x32_bf16 v[60:63], v[138:141], v[208:211], 0
	v_mfma_f32_16x16x32_bf16 v[56:59], v[160:163], v[208:211], 0
	v_mfma_f32_16x16x32_bf16 v[44:47], v[138:141], v[216:219], 0
	v_mfma_f32_16x16x32_bf16 v[40:43], v[160:163], v[216:219], 0
	v_mfma_f32_16x16x32_bf16 v[28:31], v[138:141], v[224:227], 0
	v_mfma_f32_16x16x32_bf16 v[24:27], v[160:163], v[224:227], 0
	v_mfma_f32_16x16x32_bf16 v[12:15], v[138:141], v[232:235], 0
	v_mfma_f32_16x16x32_bf16 v[8:11], v[160:163], v[232:235], 0
	v_mfma_f32_16x16x32_bf16 v[60:63], v[156:159], v[212:215], v[60:63]
	v_mfma_f32_16x16x32_bf16 v[56:59], v[164:167], v[212:215], v[56:59]
	v_mfma_f32_16x16x32_bf16 v[44:47], v[156:159], v[220:223], v[44:47]
	v_mfma_f32_16x16x32_bf16 v[40:43], v[164:167], v[220:223], v[40:43]
	v_mfma_f32_16x16x32_bf16 v[28:31], v[156:159], v[228:231], v[28:31]
	v_mfma_f32_16x16x32_bf16 v[24:27], v[164:167], v[228:231], v[24:27]
	v_mfma_f32_16x16x32_bf16 v[12:15], v[156:159], v[236:239], v[12:15]
	v_mfma_f32_16x16x32_bf16 v[8:11], v[164:167], v[236:239], v[8:11]
	s_setprio 0
	s_setprio 1
	v_mfma_f32_16x16x32_bf16 v[52:55], v[168:171], v[208:211], 0
	v_mfma_f32_16x16x32_bf16 v[48:51], v[176:179], v[208:211], 0
	v_mfma_f32_16x16x32_bf16 v[36:39], v[168:171], v[216:219], 0
	v_mfma_f32_16x16x32_bf16 v[32:35], v[176:179], v[216:219], 0
	v_mfma_f32_16x16x32_bf16 v[20:23], v[168:171], v[224:227], 0
	v_mfma_f32_16x16x32_bf16 v[16:19], v[176:179], v[224:227], 0
	v_mfma_f32_16x16x32_bf16 v[4:7], v[168:171], v[232:235], 0
	v_mfma_f32_16x16x32_bf16 v[0:3], v[176:179], v[232:235], 0
	v_mfma_f32_16x16x32_bf16 v[52:55], v[172:175], v[212:215], v[52:55]
	v_mfma_f32_16x16x32_bf16 v[48:51], v[204:207], v[212:215], v[48:51]
	v_mfma_f32_16x16x32_bf16 v[36:39], v[172:175], v[220:223], v[36:39]
	v_mfma_f32_16x16x32_bf16 v[32:35], v[204:207], v[220:223], v[32:35]
	v_mfma_f32_16x16x32_bf16 v[20:23], v[172:175], v[228:231], v[20:23]
	v_mfma_f32_16x16x32_bf16 v[16:19], v[204:207], v[228:231], v[16:19]
	v_mfma_f32_16x16x32_bf16 v[4:7], v[172:175], v[236:239], v[4:7]
	v_mfma_f32_16x16x32_bf16 v[0:3], v[204:207], v[236:239], v[0:3]
	s_setprio 0
	s_barrier
	s_add_i32 s74, 0, 0x18000
	s_add_i32 s75, 0, 0x1c000
	v_add_u32_e32 v164, s74, v143
	v_add_u32_e32 v204, s75, v143
	ds_read_b128 v[138:141], v164
	ds_read_b128 v[156:159], v164 offset:1024
	ds_read_b128 v[160:163], v164 offset:2048
	ds_read_b128 v[164:167], v164 offset:3072
	ds_read_b128 v[168:171], v204
	ds_read_b128 v[172:175], v204 offset:1024
	ds_read_b128 v[176:179], v204 offset:2048
	ds_read_b128 v[204:207], v204 offset:3072
	s_add_u32 s4, s60, 0x20000
	s_addc_u32 s5, s61, 0
	s_mov_b32 m0, s66
	v_lshl_add_u64 v[244:245], s[4:5], 0, v[128:129]
	ds_read_b128 v[208:211], v155 offset:32768
	ds_read_b128 v[212:215], v155 offset:33792
	ds_read_b128 v[216:219], v155 offset:34816
	ds_read_b128 v[220:223], v155 offset:35840
	ds_read_b128 v[224:227], v155 offset:36864
	ds_read_b128 v[228:231], v155 offset:37888
	ds_read_b128 v[232:235], v155 offset:38912
	ds_read_b128 v[236:239], v155 offset:39936
	global_load_lds_dwordx4 v[244:245], off
	v_lshl_add_u64 v[244:245], s[4:5], 0, v[130:131]
	s_mov_b32 m0, s67
	s_nop 0
	global_load_lds_dwordx4 v[244:245], off
	s_waitcnt vmcnt(8)
	s_waitcnt lgkmcnt(0)
	s_barrier
	s_setprio 1
	s_waitcnt lgkmcnt(0)
	v_mfma_f32_16x16x32_bf16 v[124:127], v[138:141], v[208:211], v[124:127]
	v_mfma_f32_16x16x32_bf16 v[120:123], v[160:163], v[208:211], v[120:123]
	v_mfma_f32_16x16x32_bf16 v[108:111], v[138:141], v[216:219], v[108:111]
	v_mfma_f32_16x16x32_bf16 v[104:107], v[160:163], v[216:219], v[104:107]
	v_mfma_f32_16x16x32_bf16 v[92:95], v[138:141], v[224:227], v[92:95]
	v_mfma_f32_16x16x32_bf16 v[88:91], v[160:163], v[224:227], v[88:91]
	v_mfma_f32_16x16x32_bf16 v[76:79], v[138:141], v[232:235], v[76:79]
	v_mfma_f32_16x16x32_bf16 v[72:75], v[160:163], v[232:235], v[72:75]
	v_mfma_f32_16x16x32_bf16 v[124:127], v[156:159], v[212:215], v[124:127]
	v_mfma_f32_16x16x32_bf16 v[120:123], v[164:167], v[212:215], v[120:123]
	v_mfma_f32_16x16x32_bf16 v[108:111], v[156:159], v[220:223], v[108:111]
	v_mfma_f32_16x16x32_bf16 v[104:107], v[164:167], v[220:223], v[104:107]
	v_mfma_f32_16x16x32_bf16 v[92:95], v[156:159], v[228:231], v[92:95]
	v_mfma_f32_16x16x32_bf16 v[88:91], v[164:167], v[228:231], v[88:91]
	v_mfma_f32_16x16x32_bf16 v[76:79], v[156:159], v[236:239], v[76:79]
	v_mfma_f32_16x16x32_bf16 v[72:75], v[164:167], v[236:239], v[72:75]
	s_setprio 0
	s_setprio 1
	v_mfma_f32_16x16x32_bf16 v[116:119], v[168:171], v[208:211], v[116:119]
	v_mfma_f32_16x16x32_bf16 v[112:115], v[176:179], v[208:211], v[112:115]
	v_mfma_f32_16x16x32_bf16 v[100:103], v[168:171], v[216:219], v[100:103]
	v_mfma_f32_16x16x32_bf16 v[96:99], v[176:179], v[216:219], v[96:99]
	v_mfma_f32_16x16x32_bf16 v[84:87], v[168:171], v[224:227], v[84:87]
	v_mfma_f32_16x16x32_bf16 v[80:83], v[176:179], v[224:227], v[80:83]
	v_mfma_f32_16x16x32_bf16 v[68:71], v[168:171], v[232:235], v[68:71]
	v_mfma_f32_16x16x32_bf16 v[64:67], v[176:179], v[232:235], v[64:67]
	v_mfma_f32_16x16x32_bf16 v[116:119], v[172:175], v[212:215], v[116:119]
	v_mfma_f32_16x16x32_bf16 v[112:115], v[204:207], v[212:215], v[112:115]
	v_mfma_f32_16x16x32_bf16 v[100:103], v[172:175], v[220:223], v[100:103]
	v_mfma_f32_16x16x32_bf16 v[96:99], v[204:207], v[220:223], v[96:99]
	v_mfma_f32_16x16x32_bf16 v[84:87], v[172:175], v[228:231], v[84:87]
	v_mfma_f32_16x16x32_bf16 v[80:83], v[204:207], v[228:231], v[80:83]
	v_mfma_f32_16x16x32_bf16 v[68:71], v[172:175], v[236:239], v[68:71]
	v_mfma_f32_16x16x32_bf16 v[64:67], v[204:207], v[236:239], v[64:67]
	s_setprio 0
	s_barrier
	s_add_i32 s4, s74, s28
	v_lshl_add_u64 v[180:181], v[180:181], 0, s[26:27]
	s_mov_b32 m0, s4
	ds_read_b128 v[208:211], v155 offset:49152
	ds_read_b128 v[212:215], v155 offset:50176
	ds_read_b128 v[216:219], v155 offset:51200
	ds_read_b128 v[220:223], v155 offset:52224
	ds_read_b128 v[224:227], v155 offset:53248
	ds_read_b128 v[228:231], v155 offset:54272
	ds_read_b128 v[232:235], v155 offset:55296
	ds_read_b128 v[236:239], v155 offset:56320
	global_load_lds_dwordx4 v[180:181], off
	s_add_i32 m0, s4, 0x2000
	s_add_u32 s4, s34, 0x20080
	v_lshl_add_u64 v[180:181], v[202:203], 0, s[26:27]
	s_addc_u32 s5, s35, 0
	s_add_i32 s34, s75, s28
	global_load_lds_dwordx4 v[180:181], off
	v_lshl_add_u64 v[180:181], s[4:5], 0, v[144:145]
	s_mov_b32 m0, s34
	s_nop 0
	global_load_lds_dwordx4 v[180:181], off
	v_lshl_add_u64 v[180:181], s[4:5], 0, v[132:133]
	s_add_i32 m0, s34, 0x2000
	s_nop 0
	global_load_lds_dwordx4 v[180:181], off
	v_lshl_add_u64 v[180:181], v[240:241], 0, s[26:27]
	s_mov_b32 m0, s68
	s_nop 0
	global_load_lds_dwordx4 v[180:181], off
	v_lshl_add_u64 v[180:181], v[242:243], 0, s[26:27]
	s_mov_b32 m0, s69
	s_nop 0
	global_load_lds_dwordx4 v[180:181], off
	s_waitcnt vmcnt(8)
	s_waitcnt lgkmcnt(0)
	s_barrier
	s_setprio 1
	s_waitcnt lgkmcnt(0)
	v_mfma_f32_16x16x32_bf16 v[60:63], v[138:141], v[208:211], v[60:63]
	v_mfma_f32_16x16x32_bf16 v[56:59], v[160:163], v[208:211], v[56:59]
	v_mfma_f32_16x16x32_bf16 v[44:47], v[138:141], v[216:219], v[44:47]
	v_mfma_f32_16x16x32_bf16 v[40:43], v[160:163], v[216:219], v[40:43]
	v_mfma_f32_16x16x32_bf16 v[28:31], v[138:141], v[224:227], v[28:31]
	v_mfma_f32_16x16x32_bf16 v[24:27], v[160:163], v[224:227], v[24:27]
	v_mfma_f32_16x16x32_bf16 v[12:15], v[138:141], v[232:235], v[12:15]
	v_mfma_f32_16x16x32_bf16 v[8:11], v[160:163], v[232:235], v[8:11]
	v_mfma_f32_16x16x32_bf16 v[60:63], v[156:159], v[212:215], v[60:63]
	v_mfma_f32_16x16x32_bf16 v[56:59], v[164:167], v[212:215], v[56:59]
	v_mfma_f32_16x16x32_bf16 v[44:47], v[156:159], v[220:223], v[44:47]
	v_mfma_f32_16x16x32_bf16 v[40:43], v[164:167], v[220:223], v[40:43]
	v_mfma_f32_16x16x32_bf16 v[28:31], v[156:159], v[228:231], v[28:31]
	v_mfma_f32_16x16x32_bf16 v[24:27], v[164:167], v[228:231], v[24:27]
	v_mfma_f32_16x16x32_bf16 v[12:15], v[156:159], v[236:239], v[12:15]
	v_mfma_f32_16x16x32_bf16 v[8:11], v[164:167], v[236:239], v[8:11]
	s_setprio 0
	s_setprio 1
	v_mfma_f32_16x16x32_bf16 v[52:55], v[168:171], v[208:211], v[52:55]
	v_mfma_f32_16x16x32_bf16 v[48:51], v[176:179], v[208:211], v[48:51]
	v_mfma_f32_16x16x32_bf16 v[36:39], v[168:171], v[216:219], v[36:39]
	v_mfma_f32_16x16x32_bf16 v[32:35], v[176:179], v[216:219], v[32:35]
	v_mfma_f32_16x16x32_bf16 v[20:23], v[168:171], v[224:227], v[20:23]
	v_mfma_f32_16x16x32_bf16 v[16:19], v[176:179], v[224:227], v[16:19]
	v_mfma_f32_16x16x32_bf16 v[4:7], v[168:171], v[232:235], v[4:7]
	v_mfma_f32_16x16x32_bf16 v[0:3], v[176:179], v[232:235], v[0:3]
	v_mfma_f32_16x16x32_bf16 v[52:55], v[172:175], v[212:215], v[52:55]
	v_mfma_f32_16x16x32_bf16 v[48:51], v[204:207], v[212:215], v[48:51]
	v_mfma_f32_16x16x32_bf16 v[36:39], v[172:175], v[220:223], v[36:39]
	v_mfma_f32_16x16x32_bf16 v[32:35], v[204:207], v[220:223], v[32:35]
	v_mfma_f32_16x16x32_bf16 v[20:23], v[172:175], v[228:231], v[20:23]
	v_mfma_f32_16x16x32_bf16 v[16:19], v[204:207], v[228:231], v[16:19]
	v_mfma_f32_16x16x32_bf16 v[4:7], v[172:175], v[236:239], v[4:7]
	v_mfma_f32_16x16x32_bf16 v[0:3], v[204:207], v[236:239], v[0:3]
	s_setprio 0
	s_barrier
	s_add_i32 s73, s73, 2
	s_add_u32 s58, s58, 0x100
	s_addc_u32 s59, s59, 0
	s_add_u32 s71, s71, 0x100
	s_addc_u32 s72, s72, 0
	s_cmp_gt_u32 s73, 5
	s_cbranch_scc0 .LBB0_1093
	s_branch .Lkexit_1093

.Lkexit_1093:
	s_and_b64 vcc, exec, s[46:47]
	s_cbranch_vccz .LBB0_1096
	s_barrier

.LBB0_1116:
	s_ashr_i32 s49, s48, 31
	s_lshl_b64 s[4:5], s[48:49], 18
	s_add_u32 s50, s30, s4
	s_addc_u32 s51, s60, s5
	s_and_b64 s[4:5], s[38:39], exec
	s_cselect_b32 s33, s51, s55
	s_cselect_b32 s36, s50, s54
	s_ashr_i32 s47, s46, 31
	s_lshl_b64 s[4:5], s[46:47], 18
	s_add_u32 s52, s61, s4
	s_addc_u32 s53, s62, s5
	s_and_b64 s[4:5], s[38:39], exec
	s_cselect_b32 s47, s53, s59
	s_cselect_b32 s49, s52, s58
	s_add_u32 s54, s54, 0x20080
	s_addc_u32 s55, s55, 0
	s_add_u32 s71, s58, 0x100
	s_addc_u32 s72, s59, 0
	s_mov_b32 s73, -2
.Lpeel_1117:
	s_add_u32 s4, s54, 0xfffe0080
	s_addc_u32 s5, s55, -1
	s_add_i32 s74, 0, 0x10000
	s_cmp_eq_u32 s73, 4
	s_cselect_b32 s59, s33, s5
	s_cselect_b32 s58, s36, s4
	s_cselect_b32 s35, s47, s72
	s_cselect_b32 s34, s49, s71
	s_add_i32 s75, 0, 0x14000
	v_add_u32_e32 v164, s74, v143
	v_add_u32_e32 v180, s75, v143
	ds_read_b128 v[138:141], v164
	ds_read_b128 v[156:159], v164 offset:1024
	ds_read_b128 v[160:163], v164 offset:2048
	ds_read_b128 v[164:167], v164 offset:3072
	ds_read_b128 v[168:171], v180
	ds_read_b128 v[172:175], v180 offset:1024
	ds_read_b128 v[176:179], v180 offset:2048
	ds_read_b128 v[204:207], v180 offset:3072
	v_lshl_add_u64 v[180:181], s[54:55], 0, v[134:135]
	s_add_i32 m0, s64, 0xc000
	ds_read_b128 v[208:211], v155
	ds_read_b128 v[212:215], v155 offset:1024
	ds_read_b128 v[216:219], v155 offset:2048
	ds_read_b128 v[220:223], v155 offset:3072
	ds_read_b128 v[224:227], v155 offset:4096
	ds_read_b128 v[228:231], v155 offset:5120
	ds_read_b128 v[232:235], v155 offset:6144
	ds_read_b128 v[236:239], v155 offset:7168
	global_load_lds_dwordx4 v[180:181], off
	v_lshl_add_u64 v[180:181], s[54:55], 0, v[136:137]
	s_add_i32 m0, s64, 0xe000
	s_nop 0
	global_load_lds_dwordx4 v[180:181], off
	s_waitcnt vmcnt(8)
	s_waitcnt lgkmcnt(0)
	s_barrier
	s_setprio 1
	s_waitcnt lgkmcnt(0)
	v_mfma_f32_16x16x32_bf16 v[124:127], v[138:141], v[208:211], 0
	v_mfma_f32_16x16x32_bf16 v[120:123], v[160:163], v[208:211], 0
	v_mfma_f32_16x16x32_bf16 v[108:111], v[138:141], v[216:219], 0
	v_mfma_f32_16x16x32_bf16 v[104:107], v[160:163], v[216:219], 0
	v_mfma_f32_16x16x32_bf16 v[92:95], v[138:141], v[224:227], 0
	v_mfma_f32_16x16x32_bf16 v[88:91], v[160:163], v[224:227], 0
	v_mfma_f32_16x16x32_bf16 v[76:79], v[138:141], v[232:235], 0
	v_mfma_f32_16x16x32_bf16 v[72:75], v[160:163], v[232:235], 0
	v_mfma_f32_16x16x32_bf16 v[124:127], v[156:159], v[212:215], v[124:127]
	v_mfma_f32_16x16x32_bf16 v[120:123], v[164:167], v[212:215], v[120:123]
	v_mfma_f32_16x16x32_bf16 v[108:111], v[156:159], v[220:223], v[108:111]
	v_mfma_f32_16x16x32_bf16 v[104:107], v[164:167], v[220:223], v[104:107]
	v_mfma_f32_16x16x32_bf16 v[92:95], v[156:159], v[228:231], v[92:95]
	v_mfma_f32_16x16x32_bf16 v[88:91], v[164:167], v[228:231], v[88:91]
	v_mfma_f32_16x16x32_bf16 v[76:79], v[156:159], v[236:239], v[76:79]
	v_mfma_f32_16x16x32_bf16 v[72:75], v[164:167], v[236:239], v[72:75]
	s_setprio 0
	s_setprio 1
	v_mfma_f32_16x16x32_bf16 v[116:119], v[168:171], v[208:211], 0
	v_mfma_f32_16x16x32_bf16 v[112:115], v[176:179], v[208:211], 0
	v_mfma_f32_16x16x32_bf16 v[100:103], v[168:171], v[216:219], 0
	v_mfma_f32_16x16x32_bf16 v[96:99], v[176:179], v[216:219], 0
	v_mfma_f32_16x16x32_bf16 v[84:87], v[168:171], v[224:227], 0
	v_mfma_f32_16x16x32_bf16 v[80:83], v[176:179], v[224:227], 0
	v_mfma_f32_16x16x32_bf16 v[68:71], v[168:171], v[232:235], 0
	v_mfma_f32_16x16x32_bf16 v[64:67], v[176:179], v[232:235], 0
	v_mfma_f32_16x16x32_bf16 v[116:119], v[172:175], v[212:215], v[116:119]
	v_mfma_f32_16x16x32_bf16 v[112:115], v[204:207], v[212:215], v[112:115]
	v_mfma_f32_16x16x32_bf16 v[100:103], v[172:175], v[220:223], v[100:103]
	v_mfma_f32_16x16x32_bf16 v[96:99], v[204:207], v[220:223], v[96:99]
	v_mfma_f32_16x16x32_bf16 v[84:87], v[172:175], v[228:231], v[84:87]
	v_mfma_f32_16x16x32_bf16 v[80:83], v[204:207], v[228:231], v[80:83]
	v_mfma_f32_16x16x32_bf16 v[68:71], v[172:175], v[236:239], v[68:71]
	v_mfma_f32_16x16x32_bf16 v[64:67], v[204:207], v[236:239], v[64:67]
	s_setprio 0
	s_barrier
	s_add_i32 s4, s74, s63
	v_lshl_add_u64 v[180:181], s[34:35], 0, v[144:145]
	s_mov_b32 m0, s4
	ds_read_b128 v[208:211], v155 offset:16384
	ds_read_b128 v[212:215], v155 offset:17408
	ds_read_b128 v[216:219], v155 offset:18432
	ds_read_b128 v[220:223], v155 offset:19456
	ds_read_b128 v[224:227], v155 offset:20480
	ds_read_b128 v[228:231], v155 offset:21504
	ds_read_b128 v[232:235], v155 offset:22528
	ds_read_b128 v[236:239], v155 offset:23552
	global_load_lds_dwordx4 v[180:181], off
	s_add_i32 m0, s4, 0x2000
	s_add_u32 s4, s34, 0x20000
	v_lshl_add_u64 v[202:203], s[34:35], 0, v[132:133]
	s_addc_u32 s5, s35, 0
	s_add_i32 s74, s75, s63
	global_load_lds_dwordx4 v[202:203], off
	v_lshl_add_u64 v[240:241], s[4:5], 0, v[144:145]
	s_mov_b32 m0, s74
	v_lshl_add_u64 v[242:243], s[58:59], 0, v[130:131]
	global_load_lds_dwordx4 v[240:241], off
	v_lshl_add_u64 v[240:241], s[4:5], 0, v[132:133]
	s_add_i32 m0, s74, 0x2000
	s_nop 0
	global_load_lds_dwordx4 v[240:241], off
	v_lshl_add_u64 v[240:241], s[58:59], 0, v[128:129]
	s_mov_b32 m0, s64
	s_nop 0
	global_load_lds_dwordx4 v[240:241], off
	s_mov_b32 m0, s65
	s_nop 0
	global_load_lds_dwordx4 v[242:243], off
	s_waitcnt vmcnt(8)
	s_waitcnt lgkmcnt(0)
	s_barrier
	s_setprio 1
	s_waitcnt lgkmcnt(0)
	v_mfma_f32_16x16x32_bf16 v[60:63], v[138:141], v[208:211], 0
	v_mfma_f32_16x16x32_bf16 v[56:59], v[160:163], v[208:211], 0
	v_mfma_f32_16x16x32_bf16 v[44:47], v[138:141], v[216:219], 0
	v_mfma_f32_16x16x32_bf16 v[40:43], v[160:163], v[216:219], 0
	v_mfma_f32_16x16x32_bf16 v[28:31], v[138:141], v[224:227], 0
	v_mfma_f32_16x16x32_bf16 v[24:27], v[160:163], v[224:227], 0
	v_mfma_f32_16x16x32_bf16 v[12:15], v[138:141], v[232:235], 0
	v_mfma_f32_16x16x32_bf16 v[8:11], v[160:163], v[232:235], 0
	v_mfma_f32_16x16x32_bf16 v[60:63], v[156:159], v[212:215], v[60:63]
	v_mfma_f32_16x16x32_bf16 v[56:59], v[164:167], v[212:215], v[56:59]
	v_mfma_f32_16x16x32_bf16 v[44:47], v[156:159], v[220:223], v[44:47]
	v_mfma_f32_16x16x32_bf16 v[40:43], v[164:167], v[220:223], v[40:43]
	v_mfma_f32_16x16x32_bf16 v[28:31], v[156:159], v[228:231], v[28:31]
	v_mfma_f32_16x16x32_bf16 v[24:27], v[164:167], v[228:231], v[24:27]
	v_mfma_f32_16x16x32_bf16 v[12:15], v[156:159], v[236:239], v[12:15]
	v_mfma_f32_16x16x32_bf16 v[8:11], v[164:167], v[236:239], v[8:11]
	s_setprio 0
	s_setprio 1
	v_mfma_f32_16x16x32_bf16 v[52:55], v[168:171], v[208:211], 0
	v_mfma_f32_16x16x32_bf16 v[48:51], v[176:179], v[208:211], 0
	v_mfma_f32_16x16x32_bf16 v[36:39], v[168:171], v[216:219], 0
	v_mfma_f32_16x16x32_bf16 v[32:35], v[176:179], v[216:219], 0
	v_mfma_f32_16x16x32_bf16 v[20:23], v[168:171], v[224:227], 0
	v_mfma_f32_16x16x32_bf16 v[16:19], v[176:179], v[224:227], 0
	v_mfma_f32_16x16x32_bf16 v[4:7], v[168:171], v[232:235], 0
	v_mfma_f32_16x16x32_bf16 v[0:3], v[176:179], v[232:235], 0
	v_mfma_f32_16x16x32_bf16 v[52:55], v[172:175], v[212:215], v[52:55]
	v_mfma_f32_16x16x32_bf16 v[48:51], v[204:207], v[212:215], v[48:51]
	v_mfma_f32_16x16x32_bf16 v[36:39], v[172:175], v[220:223], v[36:39]
	v_mfma_f32_16x16x32_bf16 v[32:35], v[204:207], v[220:223], v[32:35]
	v_mfma_f32_16x16x32_bf16 v[20:23], v[172:175], v[228:231], v[20:23]
	v_mfma_f32_16x16x32_bf16 v[16:19], v[204:207], v[228:231], v[16:19]
	v_mfma_f32_16x16x32_bf16 v[4:7], v[172:175], v[236:239], v[4:7]
	v_mfma_f32_16x16x32_bf16 v[0:3], v[204:207], v[236:239], v[0:3]
	s_setprio 0
	s_barrier
	s_add_i32 s74, 0, 0x18000
	s_add_i32 s75, 0, 0x1c000
	v_add_u32_e32 v164, s74, v143
	v_add_u32_e32 v204, s75, v143
	ds_read_b128 v[138:141], v164
	ds_read_b128 v[156:159], v164 offset:1024
	ds_read_b128 v[160:163], v164 offset:2048
	ds_read_b128 v[164:167], v164 offset:3072
	ds_read_b128 v[168:171], v204
	ds_read_b128 v[172:175], v204 offset:1024
	ds_read_b128 v[176:179], v204 offset:2048
	ds_read_b128 v[204:207], v204 offset:3072
	s_add_u32 s4, s58, 0x20000
	s_addc_u32 s5, s59, 0
	s_mov_b32 m0, s66
	v_lshl_add_u64 v[244:245], s[4:5], 0, v[128:129]
	ds_read_b128 v[208:211], v155 offset:32768
	ds_read_b128 v[212:215], v155 offset:33792
	ds_read_b128 v[216:219], v155 offset:34816
	ds_read_b128 v[220:223], v155 offset:35840
	ds_read_b128 v[224:227], v155 offset:36864
	ds_read_b128 v[228:231], v155 offset:37888
	ds_read_b128 v[232:235], v155 offset:38912
	ds_read_b128 v[236:239], v155 offset:39936
	global_load_lds_dwordx4 v[244:245], off
	v_lshl_add_u64 v[244:245], s[4:5], 0, v[130:131]
	s_mov_b32 m0, s67
	s_nop 0
	global_load_lds_dwordx4 v[244:245], off
	s_waitcnt vmcnt(8)
	s_waitcnt lgkmcnt(0)
	s_barrier
	s_setprio 1
	s_waitcnt lgkmcnt(0)
	v_mfma_f32_16x16x32_bf16 v[124:127], v[138:141], v[208:211], v[124:127]
	v_mfma_f32_16x16x32_bf16 v[120:123], v[160:163], v[208:211], v[120:123]
	v_mfma_f32_16x16x32_bf16 v[108:111], v[138:141], v[216:219], v[108:111]
	v_mfma_f32_16x16x32_bf16 v[104:107], v[160:163], v[216:219], v[104:107]
	v_mfma_f32_16x16x32_bf16 v[92:95], v[138:141], v[224:227], v[92:95]
	v_mfma_f32_16x16x32_bf16 v[88:91], v[160:163], v[224:227], v[88:91]
	v_mfma_f32_16x16x32_bf16 v[76:79], v[138:141], v[232:235], v[76:79]
	v_mfma_f32_16x16x32_bf16 v[72:75], v[160:163], v[232:235], v[72:75]
	v_mfma_f32_16x16x32_bf16 v[124:127], v[156:159], v[212:215], v[124:127]
	v_mfma_f32_16x16x32_bf16 v[120:123], v[164:167], v[212:215], v[120:123]
	v_mfma_f32_16x16x32_bf16 v[108:111], v[156:159], v[220:223], v[108:111]
	v_mfma_f32_16x16x32_bf16 v[104:107], v[164:167], v[220:223], v[104:107]
	v_mfma_f32_16x16x32_bf16 v[92:95], v[156:159], v[228:231], v[92:95]
	v_mfma_f32_16x16x32_bf16 v[88:91], v[164:167], v[228:231], v[88:91]
	v_mfma_f32_16x16x32_bf16 v[76:79], v[156:159], v[236:239], v[76:79]
	v_mfma_f32_16x16x32_bf16 v[72:75], v[164:167], v[236:239], v[72:75]
	s_setprio 0
	s_setprio 1
	v_mfma_f32_16x16x32_bf16 v[116:119], v[168:171], v[208:211], v[116:119]
	v_mfma_f32_16x16x32_bf16 v[112:115], v[176:179], v[208:211], v[112:115]
	v_mfma_f32_16x16x32_bf16 v[100:103], v[168:171], v[216:219], v[100:103]
	v_mfma_f32_16x16x32_bf16 v[96:99], v[176:179], v[216:219], v[96:99]
	v_mfma_f32_16x16x32_bf16 v[84:87], v[168:171], v[224:227], v[84:87]
	v_mfma_f32_16x16x32_bf16 v[80:83], v[176:179], v[224:227], v[80:83]
	v_mfma_f32_16x16x32_bf16 v[68:71], v[168:171], v[232:235], v[68:71]
	v_mfma_f32_16x16x32_bf16 v[64:67], v[176:179], v[232:235], v[64:67]
	v_mfma_f32_16x16x32_bf16 v[116:119], v[172:175], v[212:215], v[116:119]
	v_mfma_f32_16x16x32_bf16 v[112:115], v[204:207], v[212:215], v[112:115]
	v_mfma_f32_16x16x32_bf16 v[100:103], v[172:175], v[220:223], v[100:103]
	v_mfma_f32_16x16x32_bf16 v[96:99], v[204:207], v[220:223], v[96:99]
	v_mfma_f32_16x16x32_bf16 v[84:87], v[172:175], v[228:231], v[84:87]
	v_mfma_f32_16x16x32_bf16 v[80:83], v[204:207], v[228:231], v[80:83]
	v_mfma_f32_16x16x32_bf16 v[68:71], v[172:175], v[236:239], v[68:71]
	v_mfma_f32_16x16x32_bf16 v[64:67], v[204:207], v[236:239], v[64:67]
	s_setprio 0
	s_barrier
	s_add_i32 s4, s74, s63
	v_lshl_add_u64 v[180:181], v[180:181], 0, s[26:27]
	s_mov_b32 m0, s4
	ds_read_b128 v[208:211], v155 offset:49152
	ds_read_b128 v[212:215], v155 offset:50176
	ds_read_b128 v[216:219], v155 offset:51200
	ds_read_b128 v[220:223], v155 offset:52224
	ds_read_b128 v[224:227], v155 offset:53248
	ds_read_b128 v[228:231], v155 offset:54272
	ds_read_b128 v[232:235], v155 offset:55296
	ds_read_b128 v[236:239], v155 offset:56320
	global_load_lds_dwordx4 v[180:181], off
	s_add_i32 m0, s4, 0x2000
	s_add_u32 s4, s34, 0x20080
	v_lshl_add_u64 v[180:181], v[202:203], 0, s[26:27]
	s_addc_u32 s5, s35, 0
	s_add_i32 s34, s75, s63
	global_load_lds_dwordx4 v[180:181], off
	v_lshl_add_u64 v[180:181], s[4:5], 0, v[144:145]
	s_mov_b32 m0, s34
	s_nop 0
	global_load_lds_dwordx4 v[180:181], off
	v_lshl_add_u64 v[180:181], s[4:5], 0, v[132:133]
	s_add_i32 m0, s34, 0x2000
	s_nop 0
	global_load_lds_dwordx4 v[180:181], off
	v_lshl_add_u64 v[180:181], v[240:241], 0, s[26:27]
	s_mov_b32 m0, s68
	s_nop 0
	global_load_lds_dwordx4 v[180:181], off
	v_lshl_add_u64 v[180:181], v[242:243], 0, s[26:27]
	s_mov_b32 m0, s69
	s_nop 0
	global_load_lds_dwordx4 v[180:181], off
	s_waitcnt vmcnt(8)
	s_waitcnt lgkmcnt(0)
	s_barrier
	s_setprio 1
	s_waitcnt lgkmcnt(0)
	v_mfma_f32_16x16x32_bf16 v[60:63], v[138:141], v[208:211], v[60:63]
	v_mfma_f32_16x16x32_bf16 v[56:59], v[160:163], v[208:211], v[56:59]
	v_mfma_f32_16x16x32_bf16 v[44:47], v[138:141], v[216:219], v[44:47]
	v_mfma_f32_16x16x32_bf16 v[40:43], v[160:163], v[216:219], v[40:43]
	v_mfma_f32_16x16x32_bf16 v[28:31], v[138:141], v[224:227], v[28:31]
	v_mfma_f32_16x16x32_bf16 v[24:27], v[160:163], v[224:227], v[24:27]
	v_mfma_f32_16x16x32_bf16 v[12:15], v[138:141], v[232:235], v[12:15]
	v_mfma_f32_16x16x32_bf16 v[8:11], v[160:163], v[232:235], v[8:11]
	v_mfma_f32_16x16x32_bf16 v[60:63], v[156:159], v[212:215], v[60:63]
	v_mfma_f32_16x16x32_bf16 v[56:59], v[164:167], v[212:215], v[56:59]
	v_mfma_f32_16x16x32_bf16 v[44:47], v[156:159], v[220:223], v[44:47]
	v_mfma_f32_16x16x32_bf16 v[40:43], v[164:167], v[220:223], v[40:43]
	v_mfma_f32_16x16x32_bf16 v[28:31], v[156:159], v[228:231], v[28:31]
	v_mfma_f32_16x16x32_bf16 v[24:27], v[164:167], v[228:231], v[24:27]
	v_mfma_f32_16x16x32_bf16 v[12:15], v[156:159], v[236:239], v[12:15]
	v_mfma_f32_16x16x32_bf16 v[8:11], v[164:167], v[236:239], v[8:11]
	s_setprio 0
	s_setprio 1
	v_mfma_f32_16x16x32_bf16 v[52:55], v[168:171], v[208:211], v[52:55]
	v_mfma_f32_16x16x32_bf16 v[48:51], v[176:179], v[208:211], v[48:51]
	v_mfma_f32_16x16x32_bf16 v[36:39], v[168:171], v[216:219], v[36:39]
	v_mfma_f32_16x16x32_bf16 v[32:35], v[176:179], v[216:219], v[32:35]
	v_mfma_f32_16x16x32_bf16 v[20:23], v[168:171], v[224:227], v[20:23]
	v_mfma_f32_16x16x32_bf16 v[16:19], v[176:179], v[224:227], v[16:19]
	v_mfma_f32_16x16x32_bf16 v[4:7], v[168:171], v[232:235], v[4:7]
	v_mfma_f32_16x16x32_bf16 v[0:3], v[176:179], v[232:235], v[0:3]
	v_mfma_f32_16x16x32_bf16 v[52:55], v[172:175], v[212:215], v[52:55]
	v_mfma_f32_16x16x32_bf16 v[48:51], v[204:207], v[212:215], v[48:51]
	v_mfma_f32_16x16x32_bf16 v[36:39], v[172:175], v[220:223], v[36:39]
	v_mfma_f32_16x16x32_bf16 v[32:35], v[204:207], v[220:223], v[32:35]
	v_mfma_f32_16x16x32_bf16 v[20:23], v[172:175], v[228:231], v[20:23]
	v_mfma_f32_16x16x32_bf16 v[16:19], v[204:207], v[228:231], v[16:19]
	v_mfma_f32_16x16x32_bf16 v[4:7], v[172:175], v[236:239], v[4:7]
	v_mfma_f32_16x16x32_bf16 v[0:3], v[204:207], v[236:239], v[0:3]
	s_setprio 0
	s_barrier
	s_add_i32 s73, s73, 2
	s_add_u32 s54, s54, 0x100
	s_addc_u32 s55, s55, 0
	s_add_u32 s71, s71, 0x100
	s_addc_u32 s72, s72, 0
	s_cmp_gt_u32 s73, 5
	s_cbranch_scc0 .LBB0_1117
	s_branch .Lkexit_1117

.Lkexit_1117:
	s_and_b64 vcc, exec, s[44:45]
	s_cbranch_vccz .LBB0_1120
	s_barrier

.LBB0_1206:
	s_ashr_i32 s53, s52, 31
	s_lshl_b64 s[4:5], s[52:53], 19
	s_add_u32 s3, s36, s4
	s_addc_u32 s28, s68, s5
	s_and_b64 s[4:5], s[42:43], exec
	s_cselect_b32 s55, s28, s61
	s_cselect_b32 s54, s3, s60
	s_ashr_i32 s51, s50, 31
	s_lshl_b64 s[4:5], s[50:51], 19
	s_add_u32 s3, s66, s4
	s_addc_u32 s28, s67, s5
	s_and_b64 s[4:5], s[42:43], exec
	s_cselect_b32 s59, s28, s63
	s_cselect_b32 s58, s3, s62
	s_add_u32 s3, s62, 0x100
	s_addc_u32 s28, s63, 0
	s_mov_b32 s29, -2
	s_waitcnt lgkmcnt(0)
.Lpeel_1207:
	s_add_u32 s62, s60, 0x100
	s_addc_u32 s63, s61, 0
	s_add_i32 s4, 0, 0x10000
	s_cmp_eq_u32 s29, 12
	s_cselect_b32 s65, s55, s63
	s_cselect_b32 s64, s54, s62
	v_add_u32_e32 v142, s4, v160
	s_cselect_b32 s35, s59, s28
	s_cselect_b32 s34, s58, s3
	s_add_i32 s45, 0, 0x14000
	ds_read_b128 v[138:141], v142
	ds_read_b128 v[154:157], v142 offset:1024
	ds_read_b128 v[172:175], v142 offset:2048
	ds_read_b128 v[176:179], v142 offset:3072
	v_add_u32_e32 v142, s45, v160
	ds_read_b128 v[204:207], v142
	ds_read_b128 v[208:211], v142 offset:1024
	ds_read_b128 v[212:215], v142 offset:2048
	ds_read_b128 v[216:219], v142 offset:3072
	v_lshl_add_u64 v[142:143], s[60:61], 0, v[134:135]
	s_add_i32 m0, s69, 0xc000
	ds_read_b128 v[220:223], v170
	ds_read_b128 v[224:227], v170 offset:1024
	ds_read_b128 v[228:231], v170 offset:2048
	ds_read_b128 v[232:235], v170 offset:3072
	ds_read_b128 v[236:239], v170 offset:4096
	ds_read_b128 v[240:243], v170 offset:5120
	ds_read_b128 v[244:247], v170 offset:6144
	ds_read_b128 v[248:251], v170 offset:7168
	global_load_lds_dwordx4 v[142:143], off
	v_lshl_add_u64 v[142:143], s[60:61], 0, v[136:137]
	s_add_i32 m0, s69, 0xe000
	s_nop 0
	global_load_lds_dwordx4 v[142:143], off
	s_waitcnt vmcnt(8)
	s_waitcnt lgkmcnt(0)
	s_barrier
	s_setprio 1
	s_waitcnt lgkmcnt(0)
	v_mfma_f32_16x16x32_bf16 v[124:127], v[138:141], v[220:223], 0
	v_mfma_f32_16x16x32_bf16 v[120:123], v[172:175], v[220:223], 0
	v_mfma_f32_16x16x32_bf16 v[108:111], v[138:141], v[228:231], 0
	v_mfma_f32_16x16x32_bf16 v[104:107], v[172:175], v[228:231], 0
	v_mfma_f32_16x16x32_bf16 v[92:95], v[138:141], v[236:239], 0
	v_mfma_f32_16x16x32_bf16 v[88:91], v[172:175], v[236:239], 0
	v_mfma_f32_16x16x32_bf16 v[76:79], v[138:141], v[244:247], 0
	v_mfma_f32_16x16x32_bf16 v[72:75], v[172:175], v[244:247], 0
	v_mfma_f32_16x16x32_bf16 v[124:127], v[154:157], v[224:227], v[124:127]
	v_mfma_f32_16x16x32_bf16 v[120:123], v[176:179], v[224:227], v[120:123]
	v_mfma_f32_16x16x32_bf16 v[108:111], v[154:157], v[232:235], v[108:111]
	v_mfma_f32_16x16x32_bf16 v[104:107], v[176:179], v[232:235], v[104:107]
	v_mfma_f32_16x16x32_bf16 v[92:95], v[154:157], v[240:243], v[92:95]
	v_mfma_f32_16x16x32_bf16 v[88:91], v[176:179], v[240:243], v[88:91]
	v_mfma_f32_16x16x32_bf16 v[76:79], v[154:157], v[248:251], v[76:79]
	v_mfma_f32_16x16x32_bf16 v[72:75], v[176:179], v[248:251], v[72:75]
	s_setprio 0
	s_setprio 1
	v_mfma_f32_16x16x32_bf16 v[116:119], v[204:207], v[220:223], 0
	v_mfma_f32_16x16x32_bf16 v[112:115], v[212:215], v[220:223], 0
	v_mfma_f32_16x16x32_bf16 v[100:103], v[204:207], v[228:231], 0
	v_mfma_f32_16x16x32_bf16 v[96:99], v[212:215], v[228:231], 0
	v_mfma_f32_16x16x32_bf16 v[84:87], v[204:207], v[236:239], 0
	v_mfma_f32_16x16x32_bf16 v[80:83], v[212:215], v[236:239], 0
	v_mfma_f32_16x16x32_bf16 v[68:71], v[204:207], v[244:247], 0
	v_mfma_f32_16x16x32_bf16 v[64:67], v[212:215], v[244:247], 0
	v_mfma_f32_16x16x32_bf16 v[116:119], v[208:211], v[224:227], v[116:119]
	v_mfma_f32_16x16x32_bf16 v[112:115], v[216:219], v[224:227], v[112:115]
	v_mfma_f32_16x16x32_bf16 v[100:103], v[208:211], v[232:235], v[100:103]
	v_mfma_f32_16x16x32_bf16 v[96:99], v[216:219], v[232:235], v[96:99]
	v_mfma_f32_16x16x32_bf16 v[84:87], v[208:211], v[240:243], v[84:87]
	v_mfma_f32_16x16x32_bf16 v[80:83], v[216:219], v[240:243], v[80:83]
	v_mfma_f32_16x16x32_bf16 v[68:71], v[208:211], v[248:251], v[68:71]
	v_mfma_f32_16x16x32_bf16 v[64:67], v[216:219], v[248:251], v[64:67]
	s_setprio 0
	s_barrier
	s_add_i32 s4, s4, s33
	v_lshl_add_u64 v[142:143], s[34:35], 0, v[128:129]
	s_mov_b32 m0, s4
	ds_read_b128 v[220:223], v170 offset:16384
	ds_read_b128 v[224:227], v170 offset:17408
	ds_read_b128 v[228:231], v170 offset:18432
	ds_read_b128 v[232:235], v170 offset:19456
	ds_read_b128 v[236:239], v170 offset:20480
	ds_read_b128 v[240:243], v170 offset:21504
	ds_read_b128 v[244:247], v170 offset:22528
	ds_read_b128 v[248:251], v170 offset:23552
	global_load_lds_dwordx4 v[142:143], off
	s_add_i32 m0, s4, 0x2000
	s_add_u32 s4, s34, 0x40000
	v_lshl_add_u64 v[158:159], s[34:35], 0, v[130:131]
	s_addc_u32 s5, s35, 0
	s_add_i32 s45, s45, s33
	global_load_lds_dwordx4 v[158:159], off
	v_lshl_add_u64 v[180:181], s[4:5], 0, v[128:129]
	s_mov_b32 m0, s45
	v_lshl_add_u64 v[202:203], s[64:65], 0, v[130:131]
	global_load_lds_dwordx4 v[180:181], off
	v_lshl_add_u64 v[180:181], s[4:5], 0, v[130:131]
	s_add_i32 m0, s45, 0x2000
	s_nop 0
	global_load_lds_dwordx4 v[180:181], off
	v_lshl_add_u64 v[180:181], s[64:65], 0, v[128:129]
	s_mov_b32 m0, s69
	s_nop 0
	global_load_lds_dwordx4 v[180:181], off
	s_mov_b32 m0, s70
	s_nop 0
	global_load_lds_dwordx4 v[202:203], off
	s_waitcnt vmcnt(8)
	s_waitcnt lgkmcnt(0)
	s_barrier
	s_setprio 1
	s_waitcnt lgkmcnt(0)
	v_mfma_f32_16x16x32_bf16 v[60:63], v[138:141], v[220:223], 0
	v_mfma_f32_16x16x32_bf16 v[56:59], v[172:175], v[220:223], 0
	v_mfma_f32_16x16x32_bf16 v[44:47], v[138:141], v[228:231], 0
	v_mfma_f32_16x16x32_bf16 v[40:43], v[172:175], v[228:231], 0
	v_mfma_f32_16x16x32_bf16 v[28:31], v[138:141], v[236:239], 0
	v_mfma_f32_16x16x32_bf16 v[24:27], v[172:175], v[236:239], 0
	v_mfma_f32_16x16x32_bf16 v[12:15], v[138:141], v[244:247], 0
	v_mfma_f32_16x16x32_bf16 v[8:11], v[172:175], v[244:247], 0
	v_mfma_f32_16x16x32_bf16 v[60:63], v[154:157], v[224:227], v[60:63]
	v_mfma_f32_16x16x32_bf16 v[56:59], v[176:179], v[224:227], v[56:59]
	v_mfma_f32_16x16x32_bf16 v[44:47], v[154:157], v[232:235], v[44:47]
	v_mfma_f32_16x16x32_bf16 v[40:43], v[176:179], v[232:235], v[40:43]
	v_mfma_f32_16x16x32_bf16 v[28:31], v[154:157], v[240:243], v[28:31]
	v_mfma_f32_16x16x32_bf16 v[24:27], v[176:179], v[240:243], v[24:27]
	v_mfma_f32_16x16x32_bf16 v[12:15], v[154:157], v[248:251], v[12:15]
	v_mfma_f32_16x16x32_bf16 v[8:11], v[176:179], v[248:251], v[8:11]
	s_setprio 0
	s_setprio 1
	v_mfma_f32_16x16x32_bf16 v[52:55], v[204:207], v[220:223], 0
	v_mfma_f32_16x16x32_bf16 v[48:51], v[212:215], v[220:223], 0
	v_mfma_f32_16x16x32_bf16 v[36:39], v[204:207], v[228:231], 0
	v_mfma_f32_16x16x32_bf16 v[32:35], v[212:215], v[228:231], 0
	v_mfma_f32_16x16x32_bf16 v[20:23], v[204:207], v[236:239], 0
	v_mfma_f32_16x16x32_bf16 v[16:19], v[212:215], v[236:239], 0
	v_mfma_f32_16x16x32_bf16 v[4:7], v[204:207], v[244:247], 0
	v_mfma_f32_16x16x32_bf16 v[0:3], v[212:215], v[244:247], 0
	v_mfma_f32_16x16x32_bf16 v[52:55], v[208:211], v[224:227], v[52:55]
	v_mfma_f32_16x16x32_bf16 v[48:51], v[216:219], v[224:227], v[48:51]
	v_mfma_f32_16x16x32_bf16 v[36:39], v[208:211], v[232:235], v[36:39]
	v_mfma_f32_16x16x32_bf16 v[32:35], v[216:219], v[232:235], v[32:35]
	v_mfma_f32_16x16x32_bf16 v[20:23], v[208:211], v[240:243], v[20:23]
	v_mfma_f32_16x16x32_bf16 v[16:19], v[216:219], v[240:243], v[16:19]
	v_mfma_f32_16x16x32_bf16 v[4:7], v[208:211], v[248:251], v[4:7]
	v_mfma_f32_16x16x32_bf16 v[0:3], v[216:219], v[248:251], v[0:3]
	s_setprio 0
	s_barrier
	s_add_i32 s45, 0, 0x18000
	v_add_u32_e32 v144, s45, v160
	s_add_i32 s51, 0, 0x1c000
	ds_read_b128 v[138:141], v144
	ds_read_b128 v[154:157], v144 offset:1024
	ds_read_b128 v[172:175], v144 offset:2048
	ds_read_b128 v[176:179], v144 offset:3072
	v_add_u32_e32 v144, s51, v160
	ds_read_b128 v[204:207], v144
	ds_read_b128 v[208:211], v144 offset:1024
	ds_read_b128 v[212:215], v144 offset:2048
	ds_read_b128 v[216:219], v144 offset:3072
	s_add_u32 s4, s64, 0x40000
	s_addc_u32 s5, s65, 0
	s_mov_b32 m0, s71
	v_lshl_add_u64 v[252:253], s[4:5], 0, v[128:129]
	ds_read_b128 v[220:223], v170 offset:32768
	ds_read_b128 v[224:227], v170 offset:33792
	ds_read_b128 v[228:231], v170 offset:34816
	ds_read_b128 v[232:235], v170 offset:35840
	ds_read_b128 v[236:239], v170 offset:36864
	ds_read_b128 v[240:243], v170 offset:37888
	ds_read_b128 v[244:247], v170 offset:38912
	ds_read_b128 v[248:251], v170 offset:39936
	global_load_lds_dwordx4 v[252:253], off
	v_lshl_add_u64 v[252:253], s[4:5], 0, v[130:131]
	s_mov_b32 m0, s72
	s_nop 0
	global_load_lds_dwordx4 v[252:253], off
	s_waitcnt vmcnt(8)
	s_waitcnt lgkmcnt(0)
	s_barrier
	s_setprio 1
	s_waitcnt lgkmcnt(0)
	v_mfma_f32_16x16x32_bf16 v[124:127], v[138:141], v[220:223], v[124:127]
	v_mfma_f32_16x16x32_bf16 v[120:123], v[172:175], v[220:223], v[120:123]
	v_mfma_f32_16x16x32_bf16 v[108:111], v[138:141], v[228:231], v[108:111]
	v_mfma_f32_16x16x32_bf16 v[104:107], v[172:175], v[228:231], v[104:107]
	v_mfma_f32_16x16x32_bf16 v[92:95], v[138:141], v[236:239], v[92:95]
	v_mfma_f32_16x16x32_bf16 v[88:91], v[172:175], v[236:239], v[88:91]
	v_mfma_f32_16x16x32_bf16 v[76:79], v[138:141], v[244:247], v[76:79]
	v_mfma_f32_16x16x32_bf16 v[72:75], v[172:175], v[244:247], v[72:75]
	v_mfma_f32_16x16x32_bf16 v[124:127], v[154:157], v[224:227], v[124:127]
	v_mfma_f32_16x16x32_bf16 v[120:123], v[176:179], v[224:227], v[120:123]
	v_mfma_f32_16x16x32_bf16 v[108:111], v[154:157], v[232:235], v[108:111]
	v_mfma_f32_16x16x32_bf16 v[104:107], v[176:179], v[232:235], v[104:107]
	v_mfma_f32_16x16x32_bf16 v[92:95], v[154:157], v[240:243], v[92:95]
	v_mfma_f32_16x16x32_bf16 v[88:91], v[176:179], v[240:243], v[88:91]
	v_mfma_f32_16x16x32_bf16 v[76:79], v[154:157], v[248:251], v[76:79]
	v_mfma_f32_16x16x32_bf16 v[72:75], v[176:179], v[248:251], v[72:75]
	s_setprio 0
	s_setprio 1
	v_mfma_f32_16x16x32_bf16 v[116:119], v[204:207], v[220:223], v[116:119]
	v_mfma_f32_16x16x32_bf16 v[112:115], v[212:215], v[220:223], v[112:115]
	v_mfma_f32_16x16x32_bf16 v[100:103], v[204:207], v[228:231], v[100:103]
	v_mfma_f32_16x16x32_bf16 v[96:99], v[212:215], v[228:231], v[96:99]
	v_mfma_f32_16x16x32_bf16 v[84:87], v[204:207], v[236:239], v[84:87]
	v_mfma_f32_16x16x32_bf16 v[80:83], v[212:215], v[236:239], v[80:83]
	v_mfma_f32_16x16x32_bf16 v[68:71], v[204:207], v[244:247], v[68:71]
	v_mfma_f32_16x16x32_bf16 v[64:67], v[212:215], v[244:247], v[64:67]
	v_mfma_f32_16x16x32_bf16 v[116:119], v[208:211], v[224:227], v[116:119]
	v_mfma_f32_16x16x32_bf16 v[112:115], v[216:219], v[224:227], v[112:115]
	v_mfma_f32_16x16x32_bf16 v[100:103], v[208:211], v[232:235], v[100:103]
	v_mfma_f32_16x16x32_bf16 v[96:99], v[216:219], v[232:235], v[96:99]
	v_mfma_f32_16x16x32_bf16 v[84:87], v[208:211], v[240:243], v[84:87]
	v_mfma_f32_16x16x32_bf16 v[80:83], v[216:219], v[240:243], v[80:83]
	v_mfma_f32_16x16x32_bf16 v[68:71], v[208:211], v[248:251], v[68:71]
	v_mfma_f32_16x16x32_bf16 v[64:67], v[216:219], v[248:251], v[64:67]
	s_setprio 0
	s_barrier
	s_add_i32 s4, s45, s33
	v_lshl_add_u64 v[142:143], v[142:143], 0, s[26:27]
	s_mov_b32 m0, s4
	ds_read_b128 v[220:223], v170 offset:49152
	ds_read_b128 v[224:227], v170 offset:50176
	ds_read_b128 v[228:231], v170 offset:51200
	ds_read_b128 v[232:235], v170 offset:52224
	ds_read_b128 v[236:239], v170 offset:53248
	ds_read_b128 v[240:243], v170 offset:54272
	ds_read_b128 v[244:247], v170 offset:55296
	ds_read_b128 v[248:251], v170 offset:56320
	global_load_lds_dwordx4 v[142:143], off
	s_add_i32 m0, s4, 0x2000
	s_add_u32 s4, s34, 0x40080
	v_lshl_add_u64 v[142:143], v[158:159], 0, s[26:27]
	s_addc_u32 s5, s35, 0
	s_add_i32 s34, s51, s33
	global_load_lds_dwordx4 v[142:143], off
	v_lshl_add_u64 v[142:143], s[4:5], 0, v[128:129]
	s_mov_b32 m0, s34
	s_nop 0
	global_load_lds_dwordx4 v[142:143], off
	v_lshl_add_u64 v[142:143], s[4:5], 0, v[130:131]
	s_add_i32 m0, s34, 0x2000
	s_nop 0
	global_load_lds_dwordx4 v[142:143], off
	v_lshl_add_u64 v[142:143], v[180:181], 0, s[26:27]
	s_mov_b32 m0, s73
	s_nop 0
	global_load_lds_dwordx4 v[142:143], off
	v_lshl_add_u64 v[142:143], v[202:203], 0, s[26:27]
	s_mov_b32 m0, s74
	s_nop 0
	global_load_lds_dwordx4 v[142:143], off
	s_waitcnt vmcnt(8)
	s_waitcnt lgkmcnt(0)
	s_barrier
	s_setprio 1
	s_waitcnt lgkmcnt(0)
	v_mfma_f32_16x16x32_bf16 v[60:63], v[138:141], v[220:223], v[60:63]
	v_mfma_f32_16x16x32_bf16 v[56:59], v[172:175], v[220:223], v[56:59]
	v_mfma_f32_16x16x32_bf16 v[44:47], v[138:141], v[228:231], v[44:47]
	v_mfma_f32_16x16x32_bf16 v[40:43], v[172:175], v[228:231], v[40:43]
	v_mfma_f32_16x16x32_bf16 v[28:31], v[138:141], v[236:239], v[28:31]
	v_mfma_f32_16x16x32_bf16 v[24:27], v[172:175], v[236:239], v[24:27]
	v_mfma_f32_16x16x32_bf16 v[12:15], v[138:141], v[244:247], v[12:15]
	v_mfma_f32_16x16x32_bf16 v[8:11], v[172:175], v[244:247], v[8:11]
	v_mfma_f32_16x16x32_bf16 v[60:63], v[154:157], v[224:227], v[60:63]
	v_mfma_f32_16x16x32_bf16 v[56:59], v[176:179], v[224:227], v[56:59]
	v_mfma_f32_16x16x32_bf16 v[44:47], v[154:157], v[232:235], v[44:47]
	v_mfma_f32_16x16x32_bf16 v[40:43], v[176:179], v[232:235], v[40:43]
	v_mfma_f32_16x16x32_bf16 v[28:31], v[154:157], v[240:243], v[28:31]
	v_mfma_f32_16x16x32_bf16 v[24:27], v[176:179], v[240:243], v[24:27]
	v_mfma_f32_16x16x32_bf16 v[12:15], v[154:157], v[248:251], v[12:15]
	v_mfma_f32_16x16x32_bf16 v[8:11], v[176:179], v[248:251], v[8:11]
	s_setprio 0
	s_setprio 1
	v_mfma_f32_16x16x32_bf16 v[52:55], v[204:207], v[220:223], v[52:55]
	v_mfma_f32_16x16x32_bf16 v[48:51], v[212:215], v[220:223], v[48:51]
	v_mfma_f32_16x16x32_bf16 v[36:39], v[204:207], v[228:231], v[36:39]
	v_mfma_f32_16x16x32_bf16 v[32:35], v[212:215], v[228:231], v[32:35]
	v_mfma_f32_16x16x32_bf16 v[20:23], v[204:207], v[236:239], v[20:23]
	v_mfma_f32_16x16x32_bf16 v[16:19], v[212:215], v[236:239], v[16:19]
	v_mfma_f32_16x16x32_bf16 v[4:7], v[204:207], v[244:247], v[4:7]
	v_mfma_f32_16x16x32_bf16 v[0:3], v[212:215], v[244:247], v[0:3]
	v_mfma_f32_16x16x32_bf16 v[52:55], v[208:211], v[224:227], v[52:55]
	v_mfma_f32_16x16x32_bf16 v[48:51], v[216:219], v[224:227], v[48:51]
	v_mfma_f32_16x16x32_bf16 v[36:39], v[208:211], v[232:235], v[36:39]
	v_mfma_f32_16x16x32_bf16 v[32:35], v[216:219], v[232:235], v[32:35]
	v_mfma_f32_16x16x32_bf16 v[20:23], v[208:211], v[240:243], v[20:23]
	v_mfma_f32_16x16x32_bf16 v[16:19], v[216:219], v[240:243], v[16:19]
	v_mfma_f32_16x16x32_bf16 v[4:7], v[208:211], v[248:251], v[4:7]
	v_mfma_f32_16x16x32_bf16 v[0:3], v[216:219], v[248:251], v[0:3]
	s_setprio 0
	s_barrier
	s_add_i32 s29, s29, 2
	s_add_u32 s3, s3, 0x100
	s_addc_u32 s28, s28, 0
	s_cmp_gt_u32 s29, 13
	s_mov_b64 s[60:61], s[62:63]
	s_cbranch_scc0 .LBB0_1207
	s_branch .Lkexit_1207

.Lkexit_1207:
	s_and_b64 vcc, exec, s[48:49]
	s_cbranch_vccz .LBB0_1210
	s_barrier

.LBB0_1304:
	s_ashr_i32 s51, s50, 31
	s_lshl_b64 s[2:3], s[50:51], 19
	s_add_u32 s52, s28, s2
	s_addc_u32 s53, s29, s3
	s_and_b64 s[2:3], s[38:39], exec
	s_cselect_b32 s36, s53, s35
	s_cselect_b32 s51, s52, s34
	s_ashr_i32 s49, s48, 31
	s_lshl_b64 s[2:3], s[48:49], 19
	s_add_u32 s54, s30, s2
	s_addc_u32 s55, s62, s3
	s_and_b64 s[2:3], s[38:39], exec
	s_cselect_b32 s49, s55, s61
	s_cselect_b32 s70, s54, s60
	s_add_u32 s2, s34, 0x40080
	s_addc_u32 s3, s35, 0
	s_add_u32 s71, s60, 0x100
	s_addc_u32 s72, s61, 0
	s_mov_b32 s73, -2
.Lpeel_1305:
	s_add_u32 s4, s2, 0xfffc0080
	s_addc_u32 s5, s3, -1
	s_add_i32 s74, 0, 0x10000
	s_cmp_eq_u32 s73, 12
	s_cselect_b32 s61, s36, s5
	s_cselect_b32 s60, s51, s4
	s_cselect_b32 s35, s49, s72
	s_cselect_b32 s34, s70, s71
	s_add_i32 s75, 0, 0x14000
	v_add_u32_e32 v164, s74, v143
	v_add_u32_e32 v180, s75, v143
	ds_read_b128 v[138:141], v164
	ds_read_b128 v[156:159], v164 offset:1024
	ds_read_b128 v[160:163], v164 offset:2048
	ds_read_b128 v[164:167], v164 offset:3072
	ds_read_b128 v[168:171], v180
	ds_read_b128 v[172:175], v180 offset:1024
	ds_read_b128 v[176:179], v180 offset:2048
	ds_read_b128 v[204:207], v180 offset:3072
	v_lshl_add_u64 v[180:181], s[2:3], 0, v[134:135]
	s_add_i32 m0, s59, 0xc000
	ds_read_b128 v[208:211], v155
	ds_read_b128 v[212:215], v155 offset:1024
	ds_read_b128 v[216:219], v155 offset:2048
	ds_read_b128 v[220:223], v155 offset:3072
	ds_read_b128 v[224:227], v155 offset:4096
	ds_read_b128 v[228:231], v155 offset:5120
	ds_read_b128 v[232:235], v155 offset:6144
	ds_read_b128 v[236:239], v155 offset:7168
	global_load_lds_dwordx4 v[180:181], off
	v_lshl_add_u64 v[180:181], s[2:3], 0, v[136:137]
	s_add_i32 m0, s59, 0xe000
	s_nop 0
	global_load_lds_dwordx4 v[180:181], off
	s_waitcnt vmcnt(8)
	s_waitcnt lgkmcnt(0)
	s_barrier
	s_setprio 1
	s_waitcnt lgkmcnt(0)
	v_mfma_f32_16x16x32_bf16 v[124:127], v[138:141], v[208:211], 0
	v_mfma_f32_16x16x32_bf16 v[120:123], v[160:163], v[208:211], 0
	v_mfma_f32_16x16x32_bf16 v[108:111], v[138:141], v[216:219], 0
	v_mfma_f32_16x16x32_bf16 v[104:107], v[160:163], v[216:219], 0
	v_mfma_f32_16x16x32_bf16 v[92:95], v[138:141], v[224:227], 0
	v_mfma_f32_16x16x32_bf16 v[88:91], v[160:163], v[224:227], 0
	v_mfma_f32_16x16x32_bf16 v[76:79], v[138:141], v[232:235], 0
	v_mfma_f32_16x16x32_bf16 v[72:75], v[160:163], v[232:235], 0
	v_mfma_f32_16x16x32_bf16 v[124:127], v[156:159], v[212:215], v[124:127]
	v_mfma_f32_16x16x32_bf16 v[120:123], v[164:167], v[212:215], v[120:123]
	v_mfma_f32_16x16x32_bf16 v[108:111], v[156:159], v[220:223], v[108:111]
	v_mfma_f32_16x16x32_bf16 v[104:107], v[164:167], v[220:223], v[104:107]
	v_mfma_f32_16x16x32_bf16 v[92:95], v[156:159], v[228:231], v[92:95]
	v_mfma_f32_16x16x32_bf16 v[88:91], v[164:167], v[228:231], v[88:91]
	v_mfma_f32_16x16x32_bf16 v[76:79], v[156:159], v[236:239], v[76:79]
	v_mfma_f32_16x16x32_bf16 v[72:75], v[164:167], v[236:239], v[72:75]
	s_setprio 0
	s_setprio 1
	v_mfma_f32_16x16x32_bf16 v[116:119], v[168:171], v[208:211], 0
	v_mfma_f32_16x16x32_bf16 v[112:115], v[176:179], v[208:211], 0
	v_mfma_f32_16x16x32_bf16 v[100:103], v[168:171], v[216:219], 0
	v_mfma_f32_16x16x32_bf16 v[96:99], v[176:179], v[216:219], 0
	v_mfma_f32_16x16x32_bf16 v[84:87], v[168:171], v[224:227], 0
	v_mfma_f32_16x16x32_bf16 v[80:83], v[176:179], v[224:227], 0
	v_mfma_f32_16x16x32_bf16 v[68:71], v[168:171], v[232:235], 0
	v_mfma_f32_16x16x32_bf16 v[64:67], v[176:179], v[232:235], 0
	v_mfma_f32_16x16x32_bf16 v[116:119], v[172:175], v[212:215], v[116:119]
	v_mfma_f32_16x16x32_bf16 v[112:115], v[204:207], v[212:215], v[112:115]
	v_mfma_f32_16x16x32_bf16 v[100:103], v[172:175], v[220:223], v[100:103]
	v_mfma_f32_16x16x32_bf16 v[96:99], v[204:207], v[220:223], v[96:99]
	v_mfma_f32_16x16x32_bf16 v[84:87], v[172:175], v[228:231], v[84:87]
	v_mfma_f32_16x16x32_bf16 v[80:83], v[204:207], v[228:231], v[80:83]
	v_mfma_f32_16x16x32_bf16 v[68:71], v[172:175], v[236:239], v[68:71]
	v_mfma_f32_16x16x32_bf16 v[64:67], v[204:207], v[236:239], v[64:67]
	s_setprio 0
	s_barrier
	s_add_i32 s4, s74, s1
	v_lshl_add_u64 v[180:181], s[34:35], 0, v[144:145]
	s_mov_b32 m0, s4
	ds_read_b128 v[208:211], v155 offset:16384
	ds_read_b128 v[212:215], v155 offset:17408
	ds_read_b128 v[216:219], v155 offset:18432
	ds_read_b128 v[220:223], v155 offset:19456
	ds_read_b128 v[224:227], v155 offset:20480
	ds_read_b128 v[228:231], v155 offset:21504
	ds_read_b128 v[232:235], v155 offset:22528
	ds_read_b128 v[236:239], v155 offset:23552
	global_load_lds_dwordx4 v[180:181], off
	s_add_i32 m0, s4, 0x2000
	s_add_u32 s4, s34, 0x40000
	v_lshl_add_u64 v[202:203], s[34:35], 0, v[128:129]
	s_addc_u32 s5, s35, 0
	s_add_i32 s74, s75, s1
	global_load_lds_dwordx4 v[202:203], off
	v_lshl_add_u64 v[240:241], s[4:5], 0, v[144:145]
	s_mov_b32 m0, s74
	v_lshl_add_u64 v[242:243], s[60:61], 0, v[130:131]
	global_load_lds_dwordx4 v[240:241], off
	v_lshl_add_u64 v[240:241], s[4:5], 0, v[128:129]
	s_add_i32 m0, s74, 0x2000
	s_nop 0
	global_load_lds_dwordx4 v[240:241], off
	v_lshl_add_u64 v[240:241], s[60:61], 0, v[132:133]
	s_mov_b32 m0, s59
	s_nop 0
	global_load_lds_dwordx4 v[240:241], off
	s_mov_b32 m0, s64
	s_nop 0
	global_load_lds_dwordx4 v[242:243], off
	s_waitcnt vmcnt(8)
	s_waitcnt lgkmcnt(0)
	s_barrier
	s_setprio 1
	s_waitcnt lgkmcnt(0)
	v_mfma_f32_16x16x32_bf16 v[60:63], v[138:141], v[208:211], 0
	v_mfma_f32_16x16x32_bf16 v[56:59], v[160:163], v[208:211], 0
	v_mfma_f32_16x16x32_bf16 v[44:47], v[138:141], v[216:219], 0
	v_mfma_f32_16x16x32_bf16 v[40:43], v[160:163], v[216:219], 0
	v_mfma_f32_16x16x32_bf16 v[28:31], v[138:141], v[224:227], 0
	v_mfma_f32_16x16x32_bf16 v[24:27], v[160:163], v[224:227], 0
	v_mfma_f32_16x16x32_bf16 v[12:15], v[138:141], v[232:235], 0
	v_mfma_f32_16x16x32_bf16 v[8:11], v[160:163], v[232:235], 0
	v_mfma_f32_16x16x32_bf16 v[60:63], v[156:159], v[212:215], v[60:63]
	v_mfma_f32_16x16x32_bf16 v[56:59], v[164:167], v[212:215], v[56:59]
	v_mfma_f32_16x16x32_bf16 v[44:47], v[156:159], v[220:223], v[44:47]
	v_mfma_f32_16x16x32_bf16 v[40:43], v[164:167], v[220:223], v[40:43]
	v_mfma_f32_16x16x32_bf16 v[28:31], v[156:159], v[228:231], v[28:31]
	v_mfma_f32_16x16x32_bf16 v[24:27], v[164:167], v[228:231], v[24:27]
	v_mfma_f32_16x16x32_bf16 v[12:15], v[156:159], v[236:239], v[12:15]
	v_mfma_f32_16x16x32_bf16 v[8:11], v[164:167], v[236:239], v[8:11]
	s_setprio 0
	s_setprio 1
	v_mfma_f32_16x16x32_bf16 v[52:55], v[168:171], v[208:211], 0
	v_mfma_f32_16x16x32_bf16 v[48:51], v[176:179], v[208:211], 0
	v_mfma_f32_16x16x32_bf16 v[36:39], v[168:171], v[216:219], 0
	v_mfma_f32_16x16x32_bf16 v[32:35], v[176:179], v[216:219], 0
	v_mfma_f32_16x16x32_bf16 v[20:23], v[168:171], v[224:227], 0
	v_mfma_f32_16x16x32_bf16 v[16:19], v[176:179], v[224:227], 0
	v_mfma_f32_16x16x32_bf16 v[4:7], v[168:171], v[232:235], 0
	v_mfma_f32_16x16x32_bf16 v[0:3], v[176:179], v[232:235], 0
	v_mfma_f32_16x16x32_bf16 v[52:55], v[172:175], v[212:215], v[52:55]
	v_mfma_f32_16x16x32_bf16 v[48:51], v[204:207], v[212:215], v[48:51]
	v_mfma_f32_16x16x32_bf16 v[36:39], v[172:175], v[220:223], v[36:39]
	v_mfma_f32_16x16x32_bf16 v[32:35], v[204:207], v[220:223], v[32:35]
	v_mfma_f32_16x16x32_bf16 v[20:23], v[172:175], v[228:231], v[20:23]
	v_mfma_f32_16x16x32_bf16 v[16:19], v[204:207], v[228:231], v[16:19]
	v_mfma_f32_16x16x32_bf16 v[4:7], v[172:175], v[236:239], v[4:7]
	v_mfma_f32_16x16x32_bf16 v[0:3], v[204:207], v[236:239], v[0:3]
	s_setprio 0
	s_barrier
	s_add_i32 s74, 0, 0x18000
	s_add_i32 s75, 0, 0x1c000
	v_add_u32_e32 v164, s74, v143
	v_add_u32_e32 v204, s75, v143
	ds_read_b128 v[138:141], v164
	ds_read_b128 v[156:159], v164 offset:1024
	ds_read_b128 v[160:163], v164 offset:2048
	ds_read_b128 v[164:167], v164 offset:3072
	ds_read_b128 v[168:171], v204
	ds_read_b128 v[172:175], v204 offset:1024
	ds_read_b128 v[176:179], v204 offset:2048
	ds_read_b128 v[204:207], v204 offset:3072
	s_add_u32 s4, s60, 0x40000
	s_addc_u32 s5, s61, 0
	s_mov_b32 m0, s65
	v_lshl_add_u64 v[244:245], s[4:5], 0, v[132:133]
	ds_read_b128 v[208:211], v155 offset:32768
	ds_read_b128 v[212:215], v155 offset:33792
	ds_read_b128 v[216:219], v155 offset:34816
	ds_read_b128 v[220:223], v155 offset:35840
	ds_read_b128 v[224:227], v155 offset:36864
	ds_read_b128 v[228:231], v155 offset:37888
	ds_read_b128 v[232:235], v155 offset:38912
	ds_read_b128 v[236:239], v155 offset:39936
	global_load_lds_dwordx4 v[244:245], off
	v_lshl_add_u64 v[244:245], s[4:5], 0, v[130:131]
	s_mov_b32 m0, s66
	s_nop 0
	global_load_lds_dwordx4 v[244:245], off
	s_waitcnt vmcnt(8)
	s_waitcnt lgkmcnt(0)
	s_barrier
	s_setprio 1
	s_waitcnt lgkmcnt(0)
	v_mfma_f32_16x16x32_bf16 v[124:127], v[138:141], v[208:211], v[124:127]
	v_mfma_f32_16x16x32_bf16 v[120:123], v[160:163], v[208:211], v[120:123]
	v_mfma_f32_16x16x32_bf16 v[108:111], v[138:141], v[216:219], v[108:111]
	v_mfma_f32_16x16x32_bf16 v[104:107], v[160:163], v[216:219], v[104:107]
	v_mfma_f32_16x16x32_bf16 v[92:95], v[138:141], v[224:227], v[92:95]
	v_mfma_f32_16x16x32_bf16 v[88:91], v[160:163], v[224:227], v[88:91]
	v_mfma_f32_16x16x32_bf16 v[76:79], v[138:141], v[232:235], v[76:79]
	v_mfma_f32_16x16x32_bf16 v[72:75], v[160:163], v[232:235], v[72:75]
	v_mfma_f32_16x16x32_bf16 v[124:127], v[156:159], v[212:215], v[124:127]
	v_mfma_f32_16x16x32_bf16 v[120:123], v[164:167], v[212:215], v[120:123]
	v_mfma_f32_16x16x32_bf16 v[108:111], v[156:159], v[220:223], v[108:111]
	v_mfma_f32_16x16x32_bf16 v[104:107], v[164:167], v[220:223], v[104:107]
	v_mfma_f32_16x16x32_bf16 v[92:95], v[156:159], v[228:231], v[92:95]
	v_mfma_f32_16x16x32_bf16 v[88:91], v[164:167], v[228:231], v[88:91]
	v_mfma_f32_16x16x32_bf16 v[76:79], v[156:159], v[236:239], v[76:79]
	v_mfma_f32_16x16x32_bf16 v[72:75], v[164:167], v[236:239], v[72:75]
	s_setprio 0
	s_setprio 1
	v_mfma_f32_16x16x32_bf16 v[116:119], v[168:171], v[208:211], v[116:119]
	v_mfma_f32_16x16x32_bf16 v[112:115], v[176:179], v[208:211], v[112:115]
	v_mfma_f32_16x16x32_bf16 v[100:103], v[168:171], v[216:219], v[100:103]
	v_mfma_f32_16x16x32_bf16 v[96:99], v[176:179], v[216:219], v[96:99]
	v_mfma_f32_16x16x32_bf16 v[84:87], v[168:171], v[224:227], v[84:87]
	v_mfma_f32_16x16x32_bf16 v[80:83], v[176:179], v[224:227], v[80:83]
	v_mfma_f32_16x16x32_bf16 v[68:71], v[168:171], v[232:235], v[68:71]
	v_mfma_f32_16x16x32_bf16 v[64:67], v[176:179], v[232:235], v[64:67]
	v_mfma_f32_16x16x32_bf16 v[116:119], v[172:175], v[212:215], v[116:119]
	v_mfma_f32_16x16x32_bf16 v[112:115], v[204:207], v[212:215], v[112:115]
	v_mfma_f32_16x16x32_bf16 v[100:103], v[172:175], v[220:223], v[100:103]
	v_mfma_f32_16x16x32_bf16 v[96:99], v[204:207], v[220:223], v[96:99]
	v_mfma_f32_16x16x32_bf16 v[84:87], v[172:175], v[228:231], v[84:87]
	v_mfma_f32_16x16x32_bf16 v[80:83], v[204:207], v[228:231], v[80:83]
	v_mfma_f32_16x16x32_bf16 v[68:71], v[172:175], v[236:239], v[68:71]
	v_mfma_f32_16x16x32_bf16 v[64:67], v[204:207], v[236:239], v[64:67]
	s_setprio 0
	s_barrier
	s_add_i32 s4, s74, s1
	v_lshl_add_u64 v[180:181], v[180:181], 0, s[26:27]
	s_mov_b32 m0, s4
	ds_read_b128 v[208:211], v155 offset:49152
	ds_read_b128 v[212:215], v155 offset:50176
	ds_read_b128 v[216:219], v155 offset:51200
	ds_read_b128 v[220:223], v155 offset:52224
	ds_read_b128 v[224:227], v155 offset:53248
	ds_read_b128 v[228:231], v155 offset:54272
	ds_read_b128 v[232:235], v155 offset:55296
	ds_read_b128 v[236:239], v155 offset:56320
	global_load_lds_dwordx4 v[180:181], off
	s_add_i32 m0, s4, 0x2000
	s_add_u32 s4, s34, 0x40080
	v_lshl_add_u64 v[180:181], v[202:203], 0, s[26:27]
	s_addc_u32 s5, s35, 0
	s_add_i32 s34, s75, s1
	global_load_lds_dwordx4 v[180:181], off
	v_lshl_add_u64 v[180:181], s[4:5], 0, v[144:145]
	s_mov_b32 m0, s34
	s_nop 0
	global_load_lds_dwordx4 v[180:181], off
	v_lshl_add_u64 v[180:181], s[4:5], 0, v[128:129]
	s_add_i32 m0, s34, 0x2000
	s_nop 0
	global_load_lds_dwordx4 v[180:181], off
	v_lshl_add_u64 v[180:181], v[240:241], 0, s[26:27]
	s_mov_b32 m0, s67
	s_nop 0
	global_load_lds_dwordx4 v[180:181], off
	v_lshl_add_u64 v[180:181], v[242:243], 0, s[26:27]
	s_mov_b32 m0, s68
	s_nop 0
	global_load_lds_dwordx4 v[180:181], off
	s_waitcnt vmcnt(8)
	s_waitcnt lgkmcnt(0)
	s_barrier
	s_setprio 1
	s_waitcnt lgkmcnt(0)
	v_mfma_f32_16x16x32_bf16 v[60:63], v[138:141], v[208:211], v[60:63]
	v_mfma_f32_16x16x32_bf16 v[56:59], v[160:163], v[208:211], v[56:59]
	v_mfma_f32_16x16x32_bf16 v[44:47], v[138:141], v[216:219], v[44:47]
	v_mfma_f32_16x16x32_bf16 v[40:43], v[160:163], v[216:219], v[40:43]
	v_mfma_f32_16x16x32_bf16 v[28:31], v[138:141], v[224:227], v[28:31]
	v_mfma_f32_16x16x32_bf16 v[24:27], v[160:163], v[224:227], v[24:27]
	v_mfma_f32_16x16x32_bf16 v[12:15], v[138:141], v[232:235], v[12:15]
	v_mfma_f32_16x16x32_bf16 v[8:11], v[160:163], v[232:235], v[8:11]
	v_mfma_f32_16x16x32_bf16 v[60:63], v[156:159], v[212:215], v[60:63]
	v_mfma_f32_16x16x32_bf16 v[56:59], v[164:167], v[212:215], v[56:59]
	v_mfma_f32_16x16x32_bf16 v[44:47], v[156:159], v[220:223], v[44:47]
	v_mfma_f32_16x16x32_bf16 v[40:43], v[164:167], v[220:223], v[40:43]
	v_mfma_f32_16x16x32_bf16 v[28:31], v[156:159], v[228:231], v[28:31]
	v_mfma_f32_16x16x32_bf16 v[24:27], v[164:167], v[228:231], v[24:27]
	v_mfma_f32_16x16x32_bf16 v[12:15], v[156:159], v[236:239], v[12:15]
	v_mfma_f32_16x16x32_bf16 v[8:11], v[164:167], v[236:239], v[8:11]
	s_setprio 0
	s_setprio 1
	v_mfma_f32_16x16x32_bf16 v[52:55], v[168:171], v[208:211], v[52:55]
	v_mfma_f32_16x16x32_bf16 v[48:51], v[176:179], v[208:211], v[48:51]
	v_mfma_f32_16x16x32_bf16 v[36:39], v[168:171], v[216:219], v[36:39]
	v_mfma_f32_16x16x32_bf16 v[32:35], v[176:179], v[216:219], v[32:35]
	v_mfma_f32_16x16x32_bf16 v[20:23], v[168:171], v[224:227], v[20:23]
	v_mfma_f32_16x16x32_bf16 v[16:19], v[176:179], v[224:227], v[16:19]
	v_mfma_f32_16x16x32_bf16 v[4:7], v[168:171], v[232:235], v[4:7]
	v_mfma_f32_16x16x32_bf16 v[0:3], v[176:179], v[232:235], v[0:3]
	v_mfma_f32_16x16x32_bf16 v[52:55], v[172:175], v[212:215], v[52:55]
	v_mfma_f32_16x16x32_bf16 v[48:51], v[204:207], v[212:215], v[48:51]
	v_mfma_f32_16x16x32_bf16 v[36:39], v[172:175], v[220:223], v[36:39]
	v_mfma_f32_16x16x32_bf16 v[32:35], v[204:207], v[220:223], v[32:35]
	v_mfma_f32_16x16x32_bf16 v[20:23], v[172:175], v[228:231], v[20:23]
	v_mfma_f32_16x16x32_bf16 v[16:19], v[204:207], v[228:231], v[16:19]
	v_mfma_f32_16x16x32_bf16 v[4:7], v[172:175], v[236:239], v[4:7]
	v_mfma_f32_16x16x32_bf16 v[0:3], v[204:207], v[236:239], v[0:3]
	s_setprio 0
	s_barrier
	s_add_i32 s73, s73, 2
	s_add_u32 s2, s2, 0x100
	s_addc_u32 s3, s3, 0
	s_add_u32 s71, s71, 0x100
	s_addc_u32 s72, s72, 0
	s_cmp_gt_u32 s73, 13
	s_cbranch_scc0 .LBB0_1305
	s_branch .Lkexit_1305

.LBB0_1398:
	s_add_u32 s3, s58, 0x100
	s_addc_u32 s28, s59, 0
	s_mov_b32 s29, -2
	s_waitcnt lgkmcnt(0)
.Lpeel_1399:
	s_add_u32 s58, s54, 0x100
	s_addc_u32 s59, s55, 0
	s_add_i32 s4, 0, 0x10000
	s_cmp_eq_u32 s29, 40
	s_cselect_b32 s61, s45, s59
	s_cselect_b32 s60, s44, s58
	v_add_u32_e32 v142, s4, v160
	s_cselect_b32 s35, s53, s28
	s_cselect_b32 s34, s52, s3
	s_add_i32 s47, 0, 0x14000
	ds_read_b128 v[138:141], v142
	ds_read_b128 v[154:157], v142 offset:1024
	ds_read_b128 v[172:175], v142 offset:2048
	ds_read_b128 v[176:179], v142 offset:3072
	v_add_u32_e32 v142, s47, v160
	ds_read_b128 v[204:207], v142
	ds_read_b128 v[208:211], v142 offset:1024
	ds_read_b128 v[212:215], v142 offset:2048
	ds_read_b128 v[216:219], v142 offset:3072
	v_lshl_add_u64 v[142:143], s[54:55], 0, v[134:135]
	s_add_i32 m0, s65, 0xc000
	ds_read_b128 v[220:223], v170
	ds_read_b128 v[224:227], v170 offset:1024
	ds_read_b128 v[228:231], v170 offset:2048
	ds_read_b128 v[232:235], v170 offset:3072
	ds_read_b128 v[236:239], v170 offset:4096
	ds_read_b128 v[240:243], v170 offset:5120
	ds_read_b128 v[244:247], v170 offset:6144
	ds_read_b128 v[248:251], v170 offset:7168
	global_load_lds_dwordx4 v[142:143], off
	v_lshl_add_u64 v[142:143], s[54:55], 0, v[136:137]
	s_add_i32 m0, s65, 0xe000
	s_nop 0
	global_load_lds_dwordx4 v[142:143], off
	s_waitcnt vmcnt(8)
	s_waitcnt lgkmcnt(0)
	s_barrier
	s_setprio 1
	s_waitcnt lgkmcnt(0)
	v_mfma_f32_16x16x32_bf16 v[124:127], v[138:141], v[220:223], 0
	v_mfma_f32_16x16x32_bf16 v[120:123], v[172:175], v[220:223], 0
	v_mfma_f32_16x16x32_bf16 v[108:111], v[138:141], v[228:231], 0
	v_mfma_f32_16x16x32_bf16 v[104:107], v[172:175], v[228:231], 0
	v_mfma_f32_16x16x32_bf16 v[92:95], v[138:141], v[236:239], 0
	v_mfma_f32_16x16x32_bf16 v[88:91], v[172:175], v[236:239], 0
	v_mfma_f32_16x16x32_bf16 v[76:79], v[138:141], v[244:247], 0
	v_mfma_f32_16x16x32_bf16 v[72:75], v[172:175], v[244:247], 0
	v_mfma_f32_16x16x32_bf16 v[124:127], v[154:157], v[224:227], v[124:127]
	v_mfma_f32_16x16x32_bf16 v[120:123], v[176:179], v[224:227], v[120:123]
	v_mfma_f32_16x16x32_bf16 v[108:111], v[154:157], v[232:235], v[108:111]
	v_mfma_f32_16x16x32_bf16 v[104:107], v[176:179], v[232:235], v[104:107]
	v_mfma_f32_16x16x32_bf16 v[92:95], v[154:157], v[240:243], v[92:95]
	v_mfma_f32_16x16x32_bf16 v[88:91], v[176:179], v[240:243], v[88:91]
	v_mfma_f32_16x16x32_bf16 v[76:79], v[154:157], v[248:251], v[76:79]
	v_mfma_f32_16x16x32_bf16 v[72:75], v[176:179], v[248:251], v[72:75]
	s_setprio 0
	s_setprio 1
	v_mfma_f32_16x16x32_bf16 v[116:119], v[204:207], v[220:223], 0
	v_mfma_f32_16x16x32_bf16 v[112:115], v[212:215], v[220:223], 0
	v_mfma_f32_16x16x32_bf16 v[100:103], v[204:207], v[228:231], 0
	v_mfma_f32_16x16x32_bf16 v[96:99], v[212:215], v[228:231], 0
	v_mfma_f32_16x16x32_bf16 v[84:87], v[204:207], v[236:239], 0
	v_mfma_f32_16x16x32_bf16 v[80:83], v[212:215], v[236:239], 0
	v_mfma_f32_16x16x32_bf16 v[68:71], v[204:207], v[244:247], 0
	v_mfma_f32_16x16x32_bf16 v[64:67], v[212:215], v[244:247], 0
	v_mfma_f32_16x16x32_bf16 v[116:119], v[208:211], v[224:227], v[116:119]
	v_mfma_f32_16x16x32_bf16 v[112:115], v[216:219], v[224:227], v[112:115]
	v_mfma_f32_16x16x32_bf16 v[100:103], v[208:211], v[232:235], v[100:103]
	v_mfma_f32_16x16x32_bf16 v[96:99], v[216:219], v[232:235], v[96:99]
	v_mfma_f32_16x16x32_bf16 v[84:87], v[208:211], v[240:243], v[84:87]
	v_mfma_f32_16x16x32_bf16 v[80:83], v[216:219], v[240:243], v[80:83]
	v_mfma_f32_16x16x32_bf16 v[68:71], v[208:211], v[248:251], v[68:71]
	v_mfma_f32_16x16x32_bf16 v[64:67], v[216:219], v[248:251], v[64:67]
	s_setprio 0
	s_barrier
	s_add_i32 s4, s4, s33
	v_lshl_add_u64 v[142:143], s[34:35], 0, v[128:129]
	s_mov_b32 m0, s4
	ds_read_b128 v[220:223], v170 offset:16384
	ds_read_b128 v[224:227], v170 offset:17408
	ds_read_b128 v[228:231], v170 offset:18432
	ds_read_b128 v[232:235], v170 offset:19456
	ds_read_b128 v[236:239], v170 offset:20480
	ds_read_b128 v[240:243], v170 offset:21504
	ds_read_b128 v[244:247], v170 offset:22528
	ds_read_b128 v[248:251], v170 offset:23552
	global_load_lds_dwordx4 v[142:143], off
	s_add_i32 m0, s4, 0x2000
	s_add_u32 s4, s34, 0xb0000
	v_lshl_add_u64 v[158:159], s[34:35], 0, v[130:131]
	s_addc_u32 s5, s35, 0
	s_add_i32 s47, s47, s33
	global_load_lds_dwordx4 v[158:159], off
	v_lshl_add_u64 v[180:181], s[4:5], 0, v[128:129]
	s_mov_b32 m0, s47
	v_lshl_add_u64 v[202:203], s[60:61], 0, v[130:131]
	global_load_lds_dwordx4 v[180:181], off
	v_lshl_add_u64 v[180:181], s[4:5], 0, v[130:131]
	s_add_i32 m0, s47, 0x2000
	s_nop 0
	global_load_lds_dwordx4 v[180:181], off
	v_lshl_add_u64 v[180:181], s[60:61], 0, v[128:129]
	s_mov_b32 m0, s65
	s_nop 0
	global_load_lds_dwordx4 v[180:181], off
	s_mov_b32 m0, s66
	s_nop 0
	global_load_lds_dwordx4 v[202:203], off
	s_waitcnt vmcnt(8)
	s_waitcnt lgkmcnt(0)
	s_barrier
	s_setprio 1
	s_waitcnt lgkmcnt(0)
	v_mfma_f32_16x16x32_bf16 v[60:63], v[138:141], v[220:223], 0
	v_mfma_f32_16x16x32_bf16 v[56:59], v[172:175], v[220:223], 0
	v_mfma_f32_16x16x32_bf16 v[44:47], v[138:141], v[228:231], 0
	v_mfma_f32_16x16x32_bf16 v[40:43], v[172:175], v[228:231], 0
	v_mfma_f32_16x16x32_bf16 v[28:31], v[138:141], v[236:239], 0
	v_mfma_f32_16x16x32_bf16 v[24:27], v[172:175], v[236:239], 0
	v_mfma_f32_16x16x32_bf16 v[12:15], v[138:141], v[244:247], 0
	v_mfma_f32_16x16x32_bf16 v[8:11], v[172:175], v[244:247], 0
	v_mfma_f32_16x16x32_bf16 v[60:63], v[154:157], v[224:227], v[60:63]
	v_mfma_f32_16x16x32_bf16 v[56:59], v[176:179], v[224:227], v[56:59]
	v_mfma_f32_16x16x32_bf16 v[44:47], v[154:157], v[232:235], v[44:47]
	v_mfma_f32_16x16x32_bf16 v[40:43], v[176:179], v[232:235], v[40:43]
	v_mfma_f32_16x16x32_bf16 v[28:31], v[154:157], v[240:243], v[28:31]
	v_mfma_f32_16x16x32_bf16 v[24:27], v[176:179], v[240:243], v[24:27]
	v_mfma_f32_16x16x32_bf16 v[12:15], v[154:157], v[248:251], v[12:15]
	v_mfma_f32_16x16x32_bf16 v[8:11], v[176:179], v[248:251], v[8:11]
	s_setprio 0
	s_setprio 1
	v_mfma_f32_16x16x32_bf16 v[52:55], v[204:207], v[220:223], 0
	v_mfma_f32_16x16x32_bf16 v[48:51], v[212:215], v[220:223], 0
	v_mfma_f32_16x16x32_bf16 v[36:39], v[204:207], v[228:231], 0
	v_mfma_f32_16x16x32_bf16 v[32:35], v[212:215], v[228:231], 0
	v_mfma_f32_16x16x32_bf16 v[20:23], v[204:207], v[236:239], 0
	v_mfma_f32_16x16x32_bf16 v[16:19], v[212:215], v[236:239], 0
	v_mfma_f32_16x16x32_bf16 v[4:7], v[204:207], v[244:247], 0
	v_mfma_f32_16x16x32_bf16 v[0:3], v[212:215], v[244:247], 0
	v_mfma_f32_16x16x32_bf16 v[52:55], v[208:211], v[224:227], v[52:55]
	v_mfma_f32_16x16x32_bf16 v[48:51], v[216:219], v[224:227], v[48:51]
	v_mfma_f32_16x16x32_bf16 v[36:39], v[208:211], v[232:235], v[36:39]
	v_mfma_f32_16x16x32_bf16 v[32:35], v[216:219], v[232:235], v[32:35]
	v_mfma_f32_16x16x32_bf16 v[20:23], v[208:211], v[240:243], v[20:23]
	v_mfma_f32_16x16x32_bf16 v[16:19], v[216:219], v[240:243], v[16:19]
	v_mfma_f32_16x16x32_bf16 v[4:7], v[208:211], v[248:251], v[4:7]
	v_mfma_f32_16x16x32_bf16 v[0:3], v[216:219], v[248:251], v[0:3]
	s_setprio 0
	s_barrier
	s_add_i32 s47, 0, 0x18000
	v_add_u32_e32 v144, s47, v160
	s_add_i32 s54, 0, 0x1c000
	ds_read_b128 v[138:141], v144
	ds_read_b128 v[154:157], v144 offset:1024
	ds_read_b128 v[172:175], v144 offset:2048
	ds_read_b128 v[176:179], v144 offset:3072
	v_add_u32_e32 v144, s54, v160
	ds_read_b128 v[204:207], v144
	ds_read_b128 v[208:211], v144 offset:1024
	ds_read_b128 v[212:215], v144 offset:2048
	ds_read_b128 v[216:219], v144 offset:3072
	s_add_u32 s4, s60, 0xb0000
	s_addc_u32 s5, s61, 0
	s_mov_b32 m0, s67
	v_lshl_add_u64 v[252:253], s[4:5], 0, v[128:129]
	ds_read_b128 v[220:223], v170 offset:32768
	ds_read_b128 v[224:227], v170 offset:33792
	ds_read_b128 v[228:231], v170 offset:34816
	ds_read_b128 v[232:235], v170 offset:35840
	ds_read_b128 v[236:239], v170 offset:36864
	ds_read_b128 v[240:243], v170 offset:37888
	ds_read_b128 v[244:247], v170 offset:38912
	ds_read_b128 v[248:251], v170 offset:39936
	global_load_lds_dwordx4 v[252:253], off
	v_lshl_add_u64 v[252:253], s[4:5], 0, v[130:131]
	s_mov_b32 m0, s68
	s_nop 0
	global_load_lds_dwordx4 v[252:253], off
	s_waitcnt vmcnt(8)
	s_waitcnt lgkmcnt(0)
	s_barrier
	s_setprio 1
	s_waitcnt lgkmcnt(0)
	v_mfma_f32_16x16x32_bf16 v[124:127], v[138:141], v[220:223], v[124:127]
	v_mfma_f32_16x16x32_bf16 v[120:123], v[172:175], v[220:223], v[120:123]
	v_mfma_f32_16x16x32_bf16 v[108:111], v[138:141], v[228:231], v[108:111]
	v_mfma_f32_16x16x32_bf16 v[104:107], v[172:175], v[228:231], v[104:107]
	v_mfma_f32_16x16x32_bf16 v[92:95], v[138:141], v[236:239], v[92:95]
	v_mfma_f32_16x16x32_bf16 v[88:91], v[172:175], v[236:239], v[88:91]
	v_mfma_f32_16x16x32_bf16 v[76:79], v[138:141], v[244:247], v[76:79]
	v_mfma_f32_16x16x32_bf16 v[72:75], v[172:175], v[244:247], v[72:75]
	v_mfma_f32_16x16x32_bf16 v[124:127], v[154:157], v[224:227], v[124:127]
	v_mfma_f32_16x16x32_bf16 v[120:123], v[176:179], v[224:227], v[120:123]
	v_mfma_f32_16x16x32_bf16 v[108:111], v[154:157], v[232:235], v[108:111]
	v_mfma_f32_16x16x32_bf16 v[104:107], v[176:179], v[232:235], v[104:107]
	v_mfma_f32_16x16x32_bf16 v[92:95], v[154:157], v[240:243], v[92:95]
	v_mfma_f32_16x16x32_bf16 v[88:91], v[176:179], v[240:243], v[88:91]
	v_mfma_f32_16x16x32_bf16 v[76:79], v[154:157], v[248:251], v[76:79]
	v_mfma_f32_16x16x32_bf16 v[72:75], v[176:179], v[248:251], v[72:75]
	s_setprio 0
	s_setprio 1
	v_mfma_f32_16x16x32_bf16 v[116:119], v[204:207], v[220:223], v[116:119]
	v_mfma_f32_16x16x32_bf16 v[112:115], v[212:215], v[220:223], v[112:115]
	v_mfma_f32_16x16x32_bf16 v[100:103], v[204:207], v[228:231], v[100:103]
	v_mfma_f32_16x16x32_bf16 v[96:99], v[212:215], v[228:231], v[96:99]
	v_mfma_f32_16x16x32_bf16 v[84:87], v[204:207], v[236:239], v[84:87]
	v_mfma_f32_16x16x32_bf16 v[80:83], v[212:215], v[236:239], v[80:83]
	v_mfma_f32_16x16x32_bf16 v[68:71], v[204:207], v[244:247], v[68:71]
	v_mfma_f32_16x16x32_bf16 v[64:67], v[212:215], v[244:247], v[64:67]
	v_mfma_f32_16x16x32_bf16 v[116:119], v[208:211], v[224:227], v[116:119]
	v_mfma_f32_16x16x32_bf16 v[112:115], v[216:219], v[224:227], v[112:115]
	v_mfma_f32_16x16x32_bf16 v[100:103], v[208:211], v[232:235], v[100:103]
	v_mfma_f32_16x16x32_bf16 v[96:99], v[216:219], v[232:235], v[96:99]
	v_mfma_f32_16x16x32_bf16 v[84:87], v[208:211], v[240:243], v[84:87]
	v_mfma_f32_16x16x32_bf16 v[80:83], v[216:219], v[240:243], v[80:83]
	v_mfma_f32_16x16x32_bf16 v[68:71], v[208:211], v[248:251], v[68:71]
	v_mfma_f32_16x16x32_bf16 v[64:67], v[216:219], v[248:251], v[64:67]
	s_setprio 0
	s_barrier
	s_add_i32 s4, s47, s33
	v_lshl_add_u64 v[142:143], v[142:143], 0, s[26:27]
	s_mov_b32 m0, s4
	ds_read_b128 v[220:223], v170 offset:49152
	ds_read_b128 v[224:227], v170 offset:50176
	ds_read_b128 v[228:231], v170 offset:51200
	ds_read_b128 v[232:235], v170 offset:52224
	ds_read_b128 v[236:239], v170 offset:53248
	ds_read_b128 v[240:243], v170 offset:54272
	ds_read_b128 v[244:247], v170 offset:55296
	ds_read_b128 v[248:251], v170 offset:56320
	global_load_lds_dwordx4 v[142:143], off
	s_add_i32 m0, s4, 0x2000
	s_add_u32 s4, s34, 0xb0080
	v_lshl_add_u64 v[142:143], v[158:159], 0, s[26:27]
	s_addc_u32 s5, s35, 0
	s_add_i32 s34, s54, s33
	global_load_lds_dwordx4 v[142:143], off
	v_lshl_add_u64 v[142:143], s[4:5], 0, v[128:129]
	s_mov_b32 m0, s34
	s_nop 0
	global_load_lds_dwordx4 v[142:143], off
	v_lshl_add_u64 v[142:143], s[4:5], 0, v[130:131]
	s_add_i32 m0, s34, 0x2000
	s_nop 0
	global_load_lds_dwordx4 v[142:143], off
	v_lshl_add_u64 v[142:143], v[180:181], 0, s[26:27]
	s_mov_b32 m0, s69
	s_nop 0
	global_load_lds_dwordx4 v[142:143], off
	v_lshl_add_u64 v[142:143], v[202:203], 0, s[26:27]
	s_mov_b32 m0, s70
	s_nop 0
	global_load_lds_dwordx4 v[142:143], off
	s_waitcnt vmcnt(8)
	s_waitcnt lgkmcnt(0)
	s_barrier
	s_setprio 1
	s_waitcnt lgkmcnt(0)
	v_mfma_f32_16x16x32_bf16 v[60:63], v[138:141], v[220:223], v[60:63]
	v_mfma_f32_16x16x32_bf16 v[56:59], v[172:175], v[220:223], v[56:59]
	v_mfma_f32_16x16x32_bf16 v[44:47], v[138:141], v[228:231], v[44:47]
	v_mfma_f32_16x16x32_bf16 v[40:43], v[172:175], v[228:231], v[40:43]
	v_mfma_f32_16x16x32_bf16 v[28:31], v[138:141], v[236:239], v[28:31]
	v_mfma_f32_16x16x32_bf16 v[24:27], v[172:175], v[236:239], v[24:27]
	v_mfma_f32_16x16x32_bf16 v[12:15], v[138:141], v[244:247], v[12:15]
	v_mfma_f32_16x16x32_bf16 v[8:11], v[172:175], v[244:247], v[8:11]
	v_mfma_f32_16x16x32_bf16 v[60:63], v[154:157], v[224:227], v[60:63]
	v_mfma_f32_16x16x32_bf16 v[56:59], v[176:179], v[224:227], v[56:59]
	v_mfma_f32_16x16x32_bf16 v[44:47], v[154:157], v[232:235], v[44:47]
	v_mfma_f32_16x16x32_bf16 v[40:43], v[176:179], v[232:235], v[40:43]
	v_mfma_f32_16x16x32_bf16 v[28:31], v[154:157], v[240:243], v[28:31]
	v_mfma_f32_16x16x32_bf16 v[24:27], v[176:179], v[240:243], v[24:27]
	v_mfma_f32_16x16x32_bf16 v[12:15], v[154:157], v[248:251], v[12:15]
	v_mfma_f32_16x16x32_bf16 v[8:11], v[176:179], v[248:251], v[8:11]
	s_setprio 0
	s_setprio 1
	v_mfma_f32_16x16x32_bf16 v[52:55], v[204:207], v[220:223], v[52:55]
	v_mfma_f32_16x16x32_bf16 v[48:51], v[212:215], v[220:223], v[48:51]
	v_mfma_f32_16x16x32_bf16 v[36:39], v[204:207], v[228:231], v[36:39]
	v_mfma_f32_16x16x32_bf16 v[32:35], v[212:215], v[228:231], v[32:35]
	v_mfma_f32_16x16x32_bf16 v[20:23], v[204:207], v[236:239], v[20:23]
	v_mfma_f32_16x16x32_bf16 v[16:19], v[212:215], v[236:239], v[16:19]
	v_mfma_f32_16x16x32_bf16 v[4:7], v[204:207], v[244:247], v[4:7]
	v_mfma_f32_16x16x32_bf16 v[0:3], v[212:215], v[244:247], v[0:3]
	v_mfma_f32_16x16x32_bf16 v[52:55], v[208:211], v[224:227], v[52:55]
	v_mfma_f32_16x16x32_bf16 v[48:51], v[216:219], v[224:227], v[48:51]
	v_mfma_f32_16x16x32_bf16 v[36:39], v[208:211], v[232:235], v[36:39]
	v_mfma_f32_16x16x32_bf16 v[32:35], v[216:219], v[232:235], v[32:35]
	v_mfma_f32_16x16x32_bf16 v[20:23], v[208:211], v[240:243], v[20:23]
	v_mfma_f32_16x16x32_bf16 v[16:19], v[216:219], v[240:243], v[16:19]
	v_mfma_f32_16x16x32_bf16 v[4:7], v[208:211], v[248:251], v[4:7]
	v_mfma_f32_16x16x32_bf16 v[0:3], v[216:219], v[248:251], v[0:3]
	s_setprio 0
	s_barrier
	s_add_i32 s29, s29, 2
	s_add_u32 s3, s3, 0x100
	s_addc_u32 s28, s28, 0
	s_cmp_gt_u32 s29, 41
	s_mov_b64 s[54:55], s[58:59]
	s_cbranch_scc0 .LBB0_1399
	s_branch .Lkexit_1399
